# v_cvt_pk_bf16_f32 peephole extended to 243 sites (bounded liveness fallback, long-branch aware)
# baseline (speedup 1.0000x reference)
.LBB0_405:
	s_or_b64 exec, exec, s[48:49]
	v_lshl_add_u64 v[2:3], v[2:3], 0, v[12:13]
	global_load_dwordx4 v[30:33], v[2:3], off
	global_load_dwordx4 v[34:37], v[2:3], off offset:1024
	global_load_dwordx4 v[38:41], v[2:3], off offset:2048
	s_nop 0
	global_load_dwordx4 v[2:5], v[2:3], off offset:3072
	s_nop 0
	global_load_dwordx4 v[42:45], v[8:9], off
	v_min_i32_e32 v0, 0x4000, v6
	v_ashrrev_i32_e32 v0, 11, v0
	v_mul_hi_i32_i24_e32 v21, 0x9000, v0
	v_mul_i32_i24_e32 v20, 0x9000, v0
	v_lshl_add_u64 v[20:21], s[14:15], 0, v[20:21]
	v_lshl_add_u64 v[22:23], v[20:21], 0, s[38:39]
	v_lshl_add_u64 v[46:47], v[22:23], 0, v[12:13]
	global_load_dwordx4 v[46:49], v[46:47], off
	v_lshl_add_u64 v[54:55], v[20:21], 0, v[12:13]
	global_load_dwordx4 v[50:53], v[54:55], off
	s_mov_b32 s4, s42
	s_waitcnt vmcnt(6)
	v_mov_b32_e32 v56, v31
	s_waitcnt vmcnt(5)
	v_mov_b32_e32 v57, v35
	v_mov_b32_e32 v20, v30
	v_mov_b32_e32 v21, v34
	s_waitcnt vmcnt(4)
	v_mov_b32_e32 v64, v39
	s_waitcnt vmcnt(3)
	v_mov_b32_e32 v65, v3
	v_pk_mul_f32 v[56:57], v[56:57], v[56:57]
	v_mov_b32_e32 v58, v32
	v_mov_b32_e32 v59, v36
	v_mov_b32_e32 v62, v38
	v_mov_b32_e32 v63, v2
	v_pk_mul_f32 v[64:65], v[64:65], v[64:65]
	v_pk_fma_f32 v[20:21], v[20:21], v[20:21], v[56:57]
	v_mov_b32_e32 v60, v33
	v_mov_b32_e32 v61, v37
	v_mov_b32_e32 v66, v40
	v_mov_b32_e32 v67, v4
	v_pk_fma_f32 v[56:57], v[62:63], v[62:63], v[64:65]
	v_pk_fma_f32 v[20:21], v[58:59], v[58:59], v[20:21]
	v_mov_b32_e32 v68, v41
	v_mov_b32_e32 v69, v5
	v_pk_fma_f32 v[56:57], v[66:67], v[66:67], v[56:57]
	v_pk_fma_f32 v[20:21], v[60:61], v[60:61], v[20:21]
	v_pk_fma_f32 v[56:57], v[68:69], v[68:69], v[56:57]
	v_add_f32_e32 v0, v20, v21
	v_add_f32_e32 v0, v0, v56
	v_add_f32_e32 v0, v0, v57
	ds_bpermute_b32 v20, v24, v0
	s_waitcnt vmcnt(2)
	v_mov_b32_e32 v57, v44
	v_mov_b32_e32 v44, v43
	v_mov_b32_e32 v43, v32
	s_waitcnt vmcnt(1)
	v_mov_b32_e32 v32, v46
	s_waitcnt lgkmcnt(0)
	v_add_f32_e32 v0, v0, v20
	ds_bpermute_b32 v20, v25, v0
	s_waitcnt vmcnt(0)
	v_mov_b32_e32 v59, v52
	v_mov_b32_e32 v52, v51
	v_mov_b32_e32 v58, v50
	v_mov_b32_e32 v50, v34
	s_waitcnt lgkmcnt(0)
	v_add_f32_e32 v0, v0, v20
	ds_bpermute_b32 v56, v26, v0
	v_lshlrev_b64 v[20:21], 11, v[6:7]
	v_lshl_add_u64 v[20:21], v[10:11], 0, v[20:21]
	v_mov_b32_e32 v51, v36
	v_mov_b32_e32 v36, v35
	s_waitcnt lgkmcnt(0)
	v_add_f32_e32 v0, v0, v56
	ds_bpermute_b32 v7, v27, v0
	v_mov_b32_e32 v56, v42
	v_mov_b32_e32 v42, v30
	v_mov_b32_e32 v30, v31
	v_mov_b32_e32 v31, v33
	s_waitcnt lgkmcnt(0)
	v_add_f32_e32 v0, v0, v7
	ds_bpermute_b32 v7, v28, v0
	v_mov_b32_e32 v33, v48
	v_mov_b32_e32 v48, v47
	v_pk_add_f32 v[46:47], v[48:49], 1.0 op_sel_hi:[1,0]
	v_pk_add_f32 v[32:33], v[32:33], 1.0 op_sel_hi:[1,0]
	s_waitcnt lgkmcnt(0)
	v_add_f32_e32 v0, v0, v7
	ds_bpermute_b32 v7, v29, v0
	s_waitcnt lgkmcnt(0)
	v_add_f32_e32 v0, v0, v7
	v_fmamk_f32 v0, v0, 0x3a800000, v174
	v_mul_f32_e32 v7, 0x4b800000, v0
	v_cmp_gt_f32_e32 vcc, s27, v0
	s_nop 1
	v_cndmask_b32_e32 v0, v0, v7, vcc
	v_rsq_f32_e32 v0, v0
	s_nop 0
	v_mul_f32_e32 v7, 0x45800000, v0
	v_cndmask_b32_e32 v0, v0, v7, vcc
	v_pk_mul_f32 v[30:31], v[30:31], v[0:1] op_sel_hi:[1,0]
	v_pk_mul_f32 v[42:43], v[42:43], v[0:1] op_sel_hi:[1,0]
	v_pk_mul_f32 v[30:31], v[44:45], v[30:31]
	v_pk_mul_f32 v[42:43], v[56:57], v[42:43]
	v_pk_fma_f32 v[30:31], v[46:47], v[30:31], v[52:53]
	v_pk_fma_f32 v[32:33], v[32:33], v[42:43], v[58:59]
	v_cvt_pk_bf16_f32 v7, v33, v31
	v_cvt_pk_bf16_f32 v32, v32, v30
	v_mov_b32_e32 v31, v7
	v_mov_b32_e32 v30, v32
	global_store_dwordx2 v[20:21], v[30:31], off
	global_load_dwordx4 v[30:33], v[8:9], off offset:1024
	v_lshl_add_u64 v[42:43], v[22:23], 0, v[14:15]
	global_load_dwordx4 v[42:45], v[42:43], off
	s_nop 0
	global_load_dwordx4 v[46:49], v[54:55], off offset:1024
	v_pk_mul_f32 v[34:35], v[50:51], v[0:1] op_sel_hi:[1,0]
	v_pk_mul_f32 v[36:37], v[36:37], v[0:1] op_sel_hi:[1,0]
	s_waitcnt vmcnt(2)
	v_mov_b32_e32 v50, v30
	v_mov_b32_e32 v51, v32
	s_waitcnt vmcnt(1)
	v_mov_b32_e32 v52, v42
	v_mov_b32_e32 v53, v44
	v_mov_b32_e32 v32, v31
	v_mov_b32_e32 v44, v43
	s_waitcnt vmcnt(0)
	v_mov_b32_e32 v56, v46
	v_mov_b32_e32 v57, v48
	v_mov_b32_e32 v48, v47
	v_pk_mul_f32 v[30:31], v[34:35], v[50:51]
	v_pk_add_f32 v[34:35], v[52:53], 1.0 op_sel_hi:[1,0]
	v_pk_mul_f32 v[32:33], v[36:37], v[32:33]
	v_pk_add_f32 v[36:37], v[44:45], 1.0 op_sel_hi:[1,0]
	v_pk_fma_f32 v[30:31], v[30:31], v[34:35], v[56:57]
	v_pk_fma_f32 v[32:33], v[32:33], v[36:37], v[48:49]
	v_cvt_pk_bf16_f32 v7, v31, v33
	v_cvt_pk_bf16_f32 v30, v30, v32
	v_mov_b32_e32 v31, v7
	global_store_dwordx2 v[20:21], v[30:31], off offset:512
	global_load_dwordx4 v[30:33], v[8:9], off offset:2048
	v_lshl_add_u64 v[34:35], v[22:23], 0, v[16:17]
	global_load_dwordx4 v[34:37], v[34:35], off
	s_nop 0
	global_load_dwordx4 v[42:45], v[54:55], off offset:2048
	v_mov_b32_e32 v46, v38
	v_mov_b32_e32 v47, v40
	v_mov_b32_e32 v38, v39
	v_mov_b32_e32 v39, v41
	v_pk_mul_f32 v[40:41], v[46:47], v[0:1] op_sel_hi:[1,0]
	v_pk_mul_f32 v[38:39], v[38:39], v[0:1] op_sel_hi:[1,0]
	v_lshl_add_u64 v[22:23], v[22:23], 0, v[18:19]
	s_waitcnt vmcnt(2)
	v_mov_b32_e32 v46, v30
	v_mov_b32_e32 v47, v32
	s_waitcnt vmcnt(1)
	v_mov_b32_e32 v48, v34
	v_mov_b32_e32 v49, v36
	v_mov_b32_e32 v32, v31
	v_mov_b32_e32 v36, v35
	s_waitcnt vmcnt(0)
	v_mov_b32_e32 v50, v42
	v_mov_b32_e32 v51, v44
	v_mov_b32_e32 v44, v43
	v_pk_mul_f32 v[30:31], v[40:41], v[46:47]
	v_pk_add_f32 v[34:35], v[48:49], 1.0 op_sel_hi:[1,0]
	v_pk_mul_f32 v[32:33], v[38:39], v[32:33]
	v_pk_add_f32 v[36:37], v[36:37], 1.0 op_sel_hi:[1,0]
	v_pk_fma_f32 v[30:31], v[30:31], v[34:35], v[50:51]
	v_pk_fma_f32 v[32:33], v[32:33], v[36:37], v[44:45]
	v_cvt_pk_bf16_f32 v7, v31, v33
	v_cvt_pk_bf16_f32 v30, v30, v32
	v_mov_b32_e32 v31, v7
	global_store_dwordx2 v[20:21], v[30:31], off offset:1024
	global_load_dwordx4 v[30:33], v[8:9], off offset:3072
	s_nop 0
	global_load_dwordx4 v[34:37], v[22:23], off
	global_load_dwordx4 v[38:41], v[54:55], off offset:3072
	v_mov_b32_e32 v22, v2
	v_mov_b32_e32 v23, v4
	v_mov_b32_e32 v4, v3
	v_pk_mul_f32 v[2:3], v[22:23], v[0:1] op_sel_hi:[1,0]
	v_pk_mul_f32 v[4:5], v[4:5], v[0:1] op_sel_hi:[1,0]
	s_waitcnt vmcnt(1)
	v_mov_b32_e32 v42, v34
	v_mov_b32_e32 v22, v30
	v_mov_b32_e32 v23, v32
	v_mov_b32_e32 v43, v36
	v_mov_b32_e32 v32, v31
	v_mov_b32_e32 v36, v35
	s_waitcnt vmcnt(0)
	v_mov_b32_e32 v44, v38
	v_mov_b32_e32 v45, v40
	v_mov_b32_e32 v40, v39
	v_pk_mul_f32 v[2:3], v[2:3], v[22:23]
	v_pk_add_f32 v[22:23], v[42:43], 1.0 op_sel_hi:[1,0]
	v_pk_mul_f32 v[4:5], v[4:5], v[32:33]
	v_pk_add_f32 v[30:31], v[36:37], 1.0 op_sel_hi:[1,0]
	v_pk_fma_f32 v[2:3], v[2:3], v[22:23], v[44:45]
	v_pk_fma_f32 v[4:5], v[4:5], v[30:31], v[40:41]
	v_cvt_pk_bf16_f32 v0, v3, v5
	v_and_b32_sdwa v23, v4, v177 dst_sel:DWORD dst_unused:UNUSED_PAD src0_sel:WORD_1 src1_sel:DWORD
	v_and_b32_sdwa v7, v2, v177 dst_sel:DWORD dst_unused:UNUSED_PAD src0_sel:WORD_1 src1_sel:DWORD
	v_add3_u32 v4, v4, v23, s28
	v_add3_u32 v2, v2, v7, s28
	v_and_b32_e32 v4, 0xffff0000, v4
	v_mov_b32_e32 v3, v0
	v_or_b32_sdwa v2, v4, v2 dst_sel:DWORD dst_unused:UNUSED_PAD src0_sel:DWORD src1_sel:WORD_1
	global_store_dwordx2 v[20:21], v[2:3], off offset:1536
	s_nop 0
	v_lshl_add_u32 v6, s4, 3, v6
	v_cmp_lt_i32_e32 vcc, s29, v6
	s_or_b64 s[46:47], vcc, s[46:47]
	s_andn2_b64 exec, exec, s[46:47]
	s_cbranch_execz .LBB0_410

.LBB0_474:
	s_add_i32 s4, s19, 4
	s_min_u32 s4, s4, 15
	s_lshl_b32 s4, s4, 7
	v_lshl_add_u64 v[74:75], v[54:55], 0, s[4:5]
	v_add_co_u32_e32 v78, vcc, s34, v74
	v_lshl_add_u64 v[82:83], v[56:57], 0, s[4:5]
	s_nop 0
	v_addc_co_u32_e32 v79, vcc, 0, v75, vcc
	v_add_co_u32_e32 v86, vcc, s34, v82
	global_load_dwordx4 v[74:77], v[74:75], off
	s_nop 0
	global_load_dwordx4 v[78:81], v[78:79], off
	v_addc_co_u32_e32 v87, vcc, 0, v83, vcc
	global_load_dwordx4 v[82:85], v[82:83], off
	s_nop 0
	global_load_dwordx4 v[86:89], v[86:87], off
	v_add_u32_e32 v73, v61, v64
	ds_read_b128 v[90:93], v65
	ds_read_b128 v[94:97], v65 offset:2304
	ds_read_b128 v[98:101], v73 offset:36864
	ds_read_b128 v[102:105], v73 offset:39168
	ds_read_b128 v[106:109], v73 offset:41472
	ds_read_b128 v[110:113], v73 offset:43776
	s_add_i32 s19, s19, 2
	s_waitcnt lgkmcnt(3)
	v_mfma_f32_16x16x32_bf16 v[42:45], v[98:101], v[90:93], v[42:45]
	s_waitcnt lgkmcnt(2)
	v_mfma_f32_16x16x32_bf16 v[46:49], v[102:105], v[90:93], v[46:49]
	s_waitcnt lgkmcnt(1)
	v_mfma_f32_16x16x32_bf16 v[34:37], v[106:109], v[90:93], v[34:37]
	s_waitcnt lgkmcnt(0)
	v_mfma_f32_16x16x32_bf16 v[38:41], v[110:113], v[90:93], v[38:41]
	v_mfma_f32_16x16x32_bf16 v[10:13], v[98:101], v[94:97], v[10:13]
	ds_read_b128 v[90:93], v65 offset:64
	ds_read_b128 v[98:101], v65 offset:2368
	v_mfma_f32_16x16x32_bf16 v[14:17], v[102:105], v[94:97], v[14:17]
	v_mfma_f32_16x16x32_bf16 v[2:5], v[106:109], v[94:97], v[2:5]
	ds_read_b128 v[102:105], v73 offset:36928
	ds_read_b128 v[106:109], v73 offset:39232
	ds_read_b128 v[114:117], v73 offset:41536
	ds_read_b128 v[118:121], v73 offset:43840
	v_mfma_f32_16x16x32_bf16 v[6:9], v[110:113], v[94:97], v[6:9]
	s_waitcnt lgkmcnt(3)
	v_mfma_f32_16x16x32_bf16 v[42:45], v[102:105], v[90:93], v[42:45]
	s_waitcnt vmcnt(7)
	ds_write_b128 v72, v[18:21] offset:55296
	s_waitcnt vmcnt(6)
	ds_write_b128 v72, v[22:25] offset:64512
	s_waitcnt vmcnt(5)
	ds_write_b128 v66, v[26:29]
	s_waitcnt vmcnt(4)
	ds_write_b128 v66, v[30:33] offset:9216
	s_waitcnt lgkmcnt(6)
	v_mfma_f32_16x16x32_bf16 v[46:49], v[106:109], v[90:93], v[46:49]
	s_waitcnt lgkmcnt(5)
	v_mfma_f32_16x16x32_bf16 v[34:37], v[114:117], v[90:93], v[34:37]
	s_waitcnt lgkmcnt(4)
	v_mfma_f32_16x16x32_bf16 v[38:41], v[118:121], v[90:93], v[38:41]
	v_mfma_f32_16x16x32_bf16 v[10:13], v[102:105], v[98:101], v[10:13]
	v_mfma_f32_16x16x32_bf16 v[14:17], v[106:109], v[98:101], v[14:17]
	v_mfma_f32_16x16x32_bf16 v[2:5], v[114:117], v[98:101], v[2:5]
	v_mfma_f32_16x16x32_bf16 v[6:9], v[118:121], v[98:101], v[6:9]
	s_min_u32 s4, s19, 12
	s_lshl_b32 s4, s4, 7
	v_lshl_add_u64 v[18:19], v[54:55], 0, s[4:5]
	v_add_co_u32_e32 v22, vcc, s34, v18
	v_lshl_add_u64 v[26:27], v[56:57], 0, s[4:5]
	s_nop 0
	v_addc_co_u32_e32 v23, vcc, 0, v19, vcc
	v_add_co_u32_e32 v30, vcc, s34, v26
	s_waitcnt lgkmcnt(0)
	s_barrier
	global_load_dwordx4 v[18:21], v[18:19], off offset:384
	s_nop 0
	global_load_dwordx4 v[22:25], v[22:23], off offset:384
	v_addc_co_u32_e32 v31, vcc, 0, v27, vcc
	global_load_dwordx4 v[26:29], v[26:27], off offset:384
	s_nop 0
	global_load_dwordx4 v[30:33], v[30:31], off offset:384
	ds_read_b128 v[90:93], v65 offset:55296
	ds_read_b128 v[94:97], v65 offset:57600
	ds_read_b128 v[98:101], v67
	ds_read_b128 v[102:105], v67 offset:2304
	ds_read_b128 v[106:109], v67 offset:4608
	ds_read_b128 v[110:113], v67 offset:6912
	s_waitcnt lgkmcnt(3)
	v_mfma_f32_16x16x32_bf16 v[42:45], v[98:101], v[90:93], v[42:45]
	s_waitcnt lgkmcnt(2)
	v_mfma_f32_16x16x32_bf16 v[46:49], v[102:105], v[90:93], v[46:49]
	s_waitcnt lgkmcnt(1)
	v_mfma_f32_16x16x32_bf16 v[34:37], v[106:109], v[90:93], v[34:37]
	s_waitcnt lgkmcnt(0)
	v_mfma_f32_16x16x32_bf16 v[38:41], v[110:113], v[90:93], v[38:41]
	v_mfma_f32_16x16x32_bf16 v[10:13], v[98:101], v[94:97], v[10:13]
	ds_read_b128 v[90:93], v65 offset:55360
	ds_read_b128 v[98:101], v65 offset:57664
	v_mfma_f32_16x16x32_bf16 v[14:17], v[102:105], v[94:97], v[14:17]
	v_mfma_f32_16x16x32_bf16 v[2:5], v[106:109], v[94:97], v[2:5]
	ds_read_b128 v[102:105], v68 offset:64
	ds_read_b128 v[106:109], v69 offset:64
	ds_read_b128 v[114:117], v70 offset:64
	ds_read_b128 v[118:121], v71 offset:64
	v_mfma_f32_16x16x32_bf16 v[6:9], v[110:113], v[94:97], v[6:9]
	s_waitcnt lgkmcnt(3)
	v_mfma_f32_16x16x32_bf16 v[42:45], v[102:105], v[90:93], v[42:45]
	s_waitcnt vmcnt(7)
	ds_write_b128 v72, v[74:77]
	s_waitcnt vmcnt(6)
	ds_write_b128 v72, v[78:81] offset:9216
	s_waitcnt vmcnt(5)
	ds_write_b128 v72, v[82:85] offset:36864
	s_waitcnt vmcnt(4)
	ds_write_b128 v72, v[86:89] offset:46080
	s_waitcnt lgkmcnt(6)
	v_mfma_f32_16x16x32_bf16 v[46:49], v[106:109], v[90:93], v[46:49]
	s_waitcnt lgkmcnt(5)
	v_mfma_f32_16x16x32_bf16 v[34:37], v[114:117], v[90:93], v[34:37]
	s_waitcnt lgkmcnt(4)
	v_mfma_f32_16x16x32_bf16 v[38:41], v[118:121], v[90:93], v[38:41]
	v_mfma_f32_16x16x32_bf16 v[10:13], v[102:105], v[98:101], v[10:13]
	v_mfma_f32_16x16x32_bf16 v[14:17], v[106:109], v[98:101], v[14:17]
	v_mfma_f32_16x16x32_bf16 v[2:5], v[114:117], v[98:101], v[2:5]
	v_mfma_f32_16x16x32_bf16 v[6:9], v[118:121], v[98:101], v[6:9]
	s_waitcnt lgkmcnt(0)
	s_barrier
	s_cmp_gt_u32 s19, 13
	s_cbranch_scc0 .LBB0_474
	s_waitcnt vmcnt(3)
	v_mul_f32_e32 v19, 0xbfb8aa3b, v42
	v_exp_f32_e32 v19, v19
	s_waitcnt vmcnt(2)
	v_mul_f32_e32 v22, 0xbfb8aa3b, v43
	v_exp_f32_e32 v25, v22
	s_waitcnt vmcnt(1)
	v_mul_f32_e32 v26, 0xbfb8aa3b, v45
	v_add_f32_e32 v19, 1.0, v19
	v_rcp_f32_e32 v24, v19
	v_add_f32_e32 v19, 1.0, v25
	v_mul_f32_e32 v25, 0xbfb8aa3b, v44
	v_exp_f32_e32 v25, v25
	v_exp_f32_e32 v27, v26
	v_rcp_f32_e32 v26, v19
	v_mov_b32_e32 v28, v42
	v_add_f32_e32 v19, 1.0, v25
	v_rcp_f32_e32 v25, v19
	v_add_f32_e32 v19, 1.0, v27
	v_rcp_f32_e32 v27, v19
	v_mov_b32_e32 v29, v44
	v_pk_mul_f32 v[24:25], v[28:29], v[24:25]
	v_mov_b32_e32 v28, v46
	v_mov_b32_e32 v29, v48
	v_mov_b32_e32 v44, v43
	v_pk_mul_f32 v[24:25], v[28:29], v[24:25]
	v_pk_mul_f32 v[26:27], v[44:45], v[26:27]
	v_mov_b32_e32 v48, v47
	v_pk_mul_f32 v[26:27], v[48:49], v[26:27]
	v_cvt_pk_bf16_f32 v24, v24, v26
	v_cvt_pk_bf16_f32 v25, v25, v27
	v_or_b32_e32 v18, s17, v58
	v_ashrrev_i32_e32 v18, 1, v18
	v_mul_f32_e32 v26, 0xbfb8aa3b, v34
	v_or_b32_e32 v18, v18, v62
	v_exp_f32_e32 v26, v26
	v_mul_f32_e32 v27, 0xbfb8aa3b, v35
	s_waitcnt vmcnt(0)
	v_add_u32_e32 v30, s16, v60
	v_mov_b64_e32 v[20:21], s[14:15]
	v_ashrrev_i32_e32 v19, 31, v18
	v_exp_f32_e32 v27, v27
	v_mad_i64_i32 v[22:23], s[16:17], v30, s52, v[20:21]
	v_lshlrev_b64 v[18:19], 1, v[18:19]
	v_lshl_add_u64 v[22:23], v[22:23], 0, v[18:19]
	s_waitcnt vmcnt(0)
	global_store_dwordx2 v[22:23], v[24:25], off
	v_add_f32_e32 v24, 1.0, v26
	v_mul_f32_e32 v26, 0xbfb8aa3b, v36
	v_add_f32_e32 v25, 1.0, v27
	v_exp_f32_e32 v27, v26
	v_mul_f32_e32 v26, 0xbfb8aa3b, v37
	v_exp_f32_e32 v28, v26
	v_rcp_f32_e32 v26, v25
	v_add_f32_e32 v25, 1.0, v27
	v_rcp_f32_e32 v24, v24
	v_rcp_f32_e32 v25, v25
	v_add_f32_e32 v27, 1.0, v28
	v_rcp_f32_e32 v27, v27
	v_mov_b32_e32 v28, v34
	v_mov_b32_e32 v29, v36
	v_pk_mul_f32 v[24:25], v[28:29], v[24:25]
	v_mov_b32_e32 v28, v38
	v_mov_b32_e32 v29, v40
	v_mov_b32_e32 v36, v35
	v_pk_mul_f32 v[24:25], v[28:29], v[24:25]
	v_pk_mul_f32 v[26:27], v[36:37], v[26:27]
	v_mov_b32_e32 v40, v39
	v_pk_mul_f32 v[26:27], v[40:41], v[26:27]
	v_cvt_pk_bf16_f32 v25, v25, v27
	v_cvt_pk_bf16_f32 v24, v24, v26
	global_store_dwordx2 v[22:23], v[24:25], off offset:32
	v_mul_f32_e32 v23, 0xbfb8aa3b, v10
	v_mul_f32_e32 v24, 0xbfb8aa3b, v11
	v_exp_f32_e32 v23, v23
	v_exp_f32_e32 v24, v24
	v_or_b32_e32 v22, 16, v30
	v_mad_i64_i32 v[20:21], s[16:17], v22, s52, v[20:21]
	v_add_f32_e32 v22, 1.0, v23
	v_add_f32_e32 v23, 1.0, v24
	v_mul_f32_e32 v24, 0xbfb8aa3b, v12
	v_exp_f32_e32 v25, v24
	v_mul_f32_e32 v24, 0xbfb8aa3b, v13
	v_exp_f32_e32 v26, v24
	v_rcp_f32_e32 v24, v23
	v_add_f32_e32 v23, 1.0, v25
	v_rcp_f32_e32 v22, v22
	v_add_f32_e32 v25, 1.0, v26
	v_rcp_f32_e32 v23, v23
	v_rcp_f32_e32 v25, v25
	v_lshl_add_u64 v[18:19], v[20:21], 0, v[18:19]
	v_mov_b32_e32 v20, v10
	v_mov_b32_e32 v21, v12
	v_mov_b32_e32 v12, v11
	v_pk_mul_f32 v[20:21], v[20:21], v[22:23]
	v_mov_b32_e32 v23, v16
	v_pk_mul_f32 v[10:11], v[12:13], v[24:25]
	v_mov_b32_e32 v16, v15
	v_mov_b32_e32 v22, v14
	v_pk_mul_f32 v[10:11], v[16:17], v[10:11]
	v_pk_mul_f32 v[20:21], v[22:23], v[20:21]
	v_cvt_pk_bf16_f32 v12, v21, v11
	v_cvt_pk_bf16_f32 v13, v20, v10
	v_mov_b32_e32 v11, v12
	v_mul_f32_e32 v12, 0xbfb8aa3b, v2
	v_mov_b32_e32 v10, v13
	v_exp_f32_e32 v12, v12
	v_mul_f32_e32 v13, 0xbfb8aa3b, v3
	v_exp_f32_e32 v13, v13
	global_store_dwordx2 v[18:19], v[10:11], off
	v_add_f32_e32 v10, 1.0, v12
	v_mul_f32_e32 v12, 0xbfb8aa3b, v4
	v_add_f32_e32 v11, 1.0, v13
	v_exp_f32_e32 v13, v12
	v_mul_f32_e32 v12, 0xbfb8aa3b, v5
	v_exp_f32_e32 v14, v12
	v_rcp_f32_e32 v12, v11
	v_add_f32_e32 v11, 1.0, v13
	v_rcp_f32_e32 v10, v10
	v_add_f32_e32 v13, 1.0, v14
	v_rcp_f32_e32 v11, v11
	v_rcp_f32_e32 v13, v13
	v_mov_b32_e32 v14, v2
	v_mov_b32_e32 v15, v4
	v_mov_b32_e32 v4, v3
	v_pk_mul_f32 v[10:11], v[14:15], v[10:11]
	v_mov_b32_e32 v15, v8
	v_pk_mul_f32 v[2:3], v[4:5], v[12:13]
	v_mov_b32_e32 v8, v7
	v_mov_b32_e32 v14, v6
	v_pk_mul_f32 v[2:3], v[8:9], v[2:3]
	v_pk_mul_f32 v[10:11], v[14:15], v[10:11]
	v_and_b32_sdwa v6, v3, v177 dst_sel:DWORD dst_unused:UNUSED_PAD src0_sel:WORD_1 src1_sel:DWORD
	v_cvt_pk_bf16_f32 v5, v10, v2
	v_and_b32_sdwa v4, v11, v177 dst_sel:DWORD dst_unused:UNUSED_PAD src0_sel:WORD_1 src1_sel:DWORD
	v_add3_u32 v3, v3, v6, s28
	v_add3_u32 v4, v11, v4, s28
	v_and_b32_e32 v3, 0xffff0000, v3
	v_or_b32_sdwa v3, v3, v4 dst_sel:DWORD dst_unused:UNUSED_PAD src0_sel:DWORD src1_sel:WORD_1
	v_mov_b32_e32 v2, v5
	s_mov_b32 s4, 0
	global_store_dwordx2 v[18:19], v[2:3], off offset:32
	s_branch .LBB0_469

.LBB0_665:
	s_bitcmp1_b32 s4, 0
	s_cselect_b32 s15, 0x12000, 0
	v_or_b32_e32 v208, s15, v206
	v_add_u32_e32 v214, v208, v0
	v_add_u32_e32 v208, v208, v167
	ds_read_b128 v[184:187], v214
	ds_read_b128 v[218:221], v208 offset:32768
	ds_read_b128 v[198:201], v214 offset:2048
	ds_read_b128 v[210:213], v214 offset:4096
	ds_read_b128 v[214:217], v214 offset:6144
	ds_read_b128 v[222:225], v208 offset:34816
	ds_read_b128 v[226:229], v208 offset:36864
	ds_read_b128 v[230:233], v208 offset:38912
	ds_read_b128 v[234:237], v208 offset:40960
	ds_read_b128 v[238:241], v208 offset:43008
	ds_read_b128 v[242:245], v208 offset:45056
	ds_read_b128 v[246:249], v208 offset:47104
	s_add_i32 s14, s4, 1
	s_bitcmp1_b32 s14, 0
	s_cselect_b32 s16, 0x12000, 0
	v_add_u32_e32 v208, s16, v166
	v_add_u32_e32 v171, s16, v166
	v_xor_b32_e32 v169, 64, v206
	v_add3_u32 v169, s15, v167, v169
	s_waitcnt lgkmcnt(10)
	v_mfma_f32_16x16x32_bf16 v[158:161], v[218:221], v[184:187], v[158:161]
	s_waitcnt lgkmcnt(9)
	v_mfma_f32_16x16x32_bf16 v[130:133], v[218:221], v[198:201], v[130:133]
	s_waitcnt lgkmcnt(8)
	v_mfma_f32_16x16x32_bf16 v[66:69], v[218:221], v[210:213], v[66:69]
	s_waitcnt lgkmcnt(7)
	v_mfma_f32_16x16x32_bf16 v[34:37], v[218:221], v[214:217], v[34:37]
	ds_read_b128 v[218:221], v169 offset:32768
	s_waitcnt lgkmcnt(7)
	v_mfma_f32_16x16x32_bf16 v[154:157], v[222:225], v[184:187], v[154:157]
	v_mfma_f32_16x16x32_bf16 v[122:125], v[222:225], v[198:201], v[122:125]
	v_mfma_f32_16x16x32_bf16 v[58:61], v[222:225], v[210:213], v[58:61]
	v_mfma_f32_16x16x32_bf16 v[26:29], v[222:225], v[214:217], v[26:29]
	ds_read_b128 v[222:225], v169 offset:34816
	s_waitcnt lgkmcnt(7)
	v_mfma_f32_16x16x32_bf16 v[150:153], v[226:229], v[184:187], v[150:153]
	v_mfma_f32_16x16x32_bf16 v[114:117], v[226:229], v[198:201], v[114:117]
	v_mfma_f32_16x16x32_bf16 v[54:57], v[226:229], v[210:213], v[54:57]
	v_mfma_f32_16x16x32_bf16 v[22:25], v[226:229], v[214:217], v[22:25]
	ds_read_b128 v[226:229], v169 offset:36864
	s_waitcnt lgkmcnt(7)
	v_mfma_f32_16x16x32_bf16 v[146:149], v[230:233], v[184:187], v[146:149]
	v_mfma_f32_16x16x32_bf16 v[82:85], v[230:233], v[198:201], v[82:85]
	v_mfma_f32_16x16x32_bf16 v[50:53], v[230:233], v[210:213], v[50:53]
	v_mfma_f32_16x16x32_bf16 v[18:21], v[230:233], v[214:217], v[18:21]
	ds_read_b128 v[230:233], v169 offset:38912
	s_waitcnt lgkmcnt(7)
	v_mfma_f32_16x16x32_bf16 v[142:145], v[234:237], v[184:187], v[142:145]
	v_mfma_f32_16x16x32_bf16 v[78:81], v[234:237], v[198:201], v[78:81]
	v_mfma_f32_16x16x32_bf16 v[46:49], v[234:237], v[210:213], v[46:49]
	v_mfma_f32_16x16x32_bf16 v[14:17], v[234:237], v[214:217], v[14:17]
	ds_read_b128 v[234:237], v169 offset:40960
	s_waitcnt lgkmcnt(7)
	v_mfma_f32_16x16x32_bf16 v[138:141], v[238:241], v[184:187], v[138:141]
	v_mfma_f32_16x16x32_bf16 v[74:77], v[238:241], v[198:201], v[74:77]
	v_mfma_f32_16x16x32_bf16 v[42:45], v[238:241], v[210:213], v[42:45]
	v_mfma_f32_16x16x32_bf16 v[10:13], v[238:241], v[214:217], v[10:13]
	ds_read_b128 v[238:241], v169 offset:43008
	s_waitcnt lgkmcnt(7)
	v_mfma_f32_16x16x32_bf16 v[134:137], v[242:245], v[184:187], v[134:137]
	v_mfma_f32_16x16x32_bf16 v[70:73], v[242:245], v[198:201], v[70:73]
	v_mfma_f32_16x16x32_bf16 v[38:41], v[242:245], v[210:213], v[38:41]
	v_mfma_f32_16x16x32_bf16 v[6:9], v[242:245], v[214:217], v[6:9]
	ds_read_b128 v[242:245], v169 offset:45056
	s_waitcnt lgkmcnt(7)
	v_mfma_f32_16x16x32_bf16 v[126:129], v[246:249], v[184:187], v[126:129]
	v_mfma_f32_16x16x32_bf16 v[62:65], v[246:249], v[198:201], v[62:65]
	v_xor_b32_e32 v169, 64, v206
	v_add3_u32 v169, s15, v0, v169
	ds_read_b128 v[184:187], v169
	ds_read_b128 v[198:201], v169 offset:2048
	v_mfma_f32_16x16x32_bf16 v[30:33], v[246:249], v[210:213], v[30:33]
	ds_read_b128 v[210:213], v169 offset:4096
	v_mfma_f32_16x16x32_bf16 v[2:5], v[246:249], v[214:217], v[2:5]
	ds_read_b128 v[214:217], v169 offset:6144
	v_xor_b32_e32 v169, 64, v206
	v_add3_u32 v169, s15, v167, v169
	ds_read_b128 v[246:249], v169 offset:47104
	s_waitcnt lgkmcnt(4)
	v_mfma_f32_16x16x32_bf16 v[158:161], v[218:221], v[184:187], v[158:161]
	s_waitcnt lgkmcnt(3)
	v_mfma_f32_16x16x32_bf16 v[130:133], v[218:221], v[198:201], v[130:133]
	s_waitcnt lgkmcnt(2)
	v_mfma_f32_16x16x32_bf16 v[66:69], v[218:221], v[210:213], v[66:69]
	s_waitcnt lgkmcnt(1)
	v_mfma_f32_16x16x32_bf16 v[34:37], v[218:221], v[214:217], v[34:37]
	s_waitcnt vmcnt(7)
	ds_write_b128 v171, v[94:97]
	v_mfma_f32_16x16x32_bf16 v[154:157], v[222:225], v[184:187], v[154:157]
	v_mfma_f32_16x16x32_bf16 v[122:125], v[222:225], v[198:201], v[122:125]
	global_load_dwordx4 v[94:97], v168, vcc offset:256
	v_mfma_f32_16x16x32_bf16 v[58:61], v[222:225], v[210:213], v[58:61]
	v_mfma_f32_16x16x32_bf16 v[26:29], v[222:225], v[214:217], v[26:29]
	s_waitcnt vmcnt(7)
	ds_write_b128 v171, v[86:89] offset:8192
	v_mfma_f32_16x16x32_bf16 v[150:153], v[226:229], v[184:187], v[150:153]
	v_mfma_f32_16x16x32_bf16 v[114:117], v[226:229], v[198:201], v[114:117]
	v_add_u32_e32 v86, s34, v168
	global_load_dwordx4 v[86:89], v86, vcc offset:256
	v_mfma_f32_16x16x32_bf16 v[54:57], v[226:229], v[210:213], v[54:57]
	v_mfma_f32_16x16x32_bf16 v[22:25], v[226:229], v[214:217], v[22:25]
	s_waitcnt vmcnt(7)
	ds_write_b128 v171, v[90:93] offset:16384
	v_mfma_f32_16x16x32_bf16 v[146:149], v[230:233], v[184:187], v[146:149]
	v_mfma_f32_16x16x32_bf16 v[82:85], v[230:233], v[198:201], v[82:85]
	v_add_u32_e32 v90, s35, v168
	global_load_dwordx4 v[90:93], v90, vcc offset:256
	v_mfma_f32_16x16x32_bf16 v[50:53], v[230:233], v[210:213], v[50:53]
	v_mfma_f32_16x16x32_bf16 v[18:21], v[230:233], v[214:217], v[18:21]
	s_waitcnt vmcnt(7)
	ds_write_b128 v171, v[106:109] offset:24576
	v_mfma_f32_16x16x32_bf16 v[142:145], v[234:237], v[184:187], v[142:145]
	v_mfma_f32_16x16x32_bf16 v[78:81], v[234:237], v[198:201], v[78:81]
	v_add_u32_e32 v106, s36, v168
	global_load_dwordx4 v[106:109], v106, vcc offset:256
	v_mfma_f32_16x16x32_bf16 v[46:49], v[234:237], v[210:213], v[46:49]
	v_mfma_f32_16x16x32_bf16 v[14:17], v[234:237], v[214:217], v[14:17]
	s_waitcnt vmcnt(7)
	ds_write_b128 v171, v[102:105] offset:32768
	v_mfma_f32_16x16x32_bf16 v[138:141], v[238:241], v[184:187], v[138:141]
	v_mfma_f32_16x16x32_bf16 v[74:77], v[238:241], v[198:201], v[74:77]
	global_load_dwordx4 v[102:105], v170, s[100:101] offset:256
	v_mfma_f32_16x16x32_bf16 v[42:45], v[238:241], v[210:213], v[42:45]
	v_mfma_f32_16x16x32_bf16 v[10:13], v[238:241], v[214:217], v[10:13]
	s_waitcnt vmcnt(7)
	ds_write_b128 v171, v[98:101] offset:40960
	v_mfma_f32_16x16x32_bf16 v[134:137], v[242:245], v[184:187], v[134:137]
	v_mfma_f32_16x16x32_bf16 v[70:73], v[242:245], v[198:201], v[70:73]
	v_add_u32_e32 v98, s34, v170
	global_load_dwordx4 v[98:101], v98, s[100:101] offset:256
	v_mfma_f32_16x16x32_bf16 v[38:41], v[242:245], v[210:213], v[38:41]
	v_mfma_f32_16x16x32_bf16 v[6:9], v[242:245], v[214:217], v[6:9]
	s_waitcnt vmcnt(7)
	ds_write_b128 v171, v[118:121] offset:49152
	s_waitcnt lgkmcnt(7)
	v_mfma_f32_16x16x32_bf16 v[126:129], v[246:249], v[184:187], v[126:129]
	v_mfma_f32_16x16x32_bf16 v[62:65], v[246:249], v[198:201], v[62:65]
	v_add_u32_e32 v118, s35, v170
	global_load_dwordx4 v[118:121], v118, s[100:101] offset:256
	v_mfma_f32_16x16x32_bf16 v[30:33], v[246:249], v[210:213], v[30:33]
	v_mfma_f32_16x16x32_bf16 v[2:5], v[246:249], v[214:217], v[2:5]
	s_waitcnt vmcnt(7)
	ds_write_b128 v171, v[110:113] offset:57344
	v_add_u32_e32 v110, s36, v170
	global_load_dwordx4 v[110:113], v110, s[100:101] offset:256
	v_add_u32_e32 v168, 0x80, v168
	v_add_u32_e32 v170, 0x80, v170
	s_waitcnt lgkmcnt(0)
	s_barrier
	s_cmp_eq_u32 s14, 16
	s_mov_b32 s4, s14
	s_cbranch_scc0 .LBB0_665
	s_waitcnt vmcnt(3)
	v_or_b32_e32 v88, s7, v207
	v_add_u32_e32 v94, s6, v205
	v_mov_b64_e32 v[86:87], s[12:13]
	v_ashrrev_i32_e32 v89, 31, v88
	v_mad_i64_i32 v[90:91], s[6:7], v94, s8, v[86:87]
	v_lshlrev_b64 v[88:89], 1, v[88:89]
	v_lshl_add_u64 v[90:91], v[90:91], 0, v[88:89]
	v_cvt_pk_bf16_f32 v93, v160, v161
	v_cvt_pk_bf16_f32 v92, v158, v159
	s_waitcnt vmcnt(0)
	global_store_dwordx2 v[90:91], v[92:93], off
	v_cvt_pk_bf16_f32 v93, v156, v157
	v_cvt_pk_bf16_f32 v92, v154, v155
	global_store_dwordx2 v[90:91], v[92:93], off offset:32
	v_cvt_pk_bf16_f32 v93, v152, v153
	v_cvt_pk_bf16_f32 v92, v150, v151
	global_store_dwordx2 v[90:91], v[92:93], off offset:64
	v_cvt_pk_bf16_f32 v93, v148, v149
	v_cvt_pk_bf16_f32 v92, v146, v147
	global_store_dwordx2 v[90:91], v[92:93], off offset:96
	v_cvt_pk_bf16_f32 v93, v144, v145
	v_cvt_pk_bf16_f32 v92, v142, v143
	global_store_dwordx2 v[90:91], v[92:93], off offset:128
	v_cvt_pk_bf16_f32 v93, v140, v141
	v_cvt_pk_bf16_f32 v92, v138, v139
	global_store_dwordx2 v[90:91], v[92:93], off offset:160
	v_cvt_pk_bf16_f32 v93, v136, v137
	v_cvt_pk_bf16_f32 v92, v134, v135
	global_store_dwordx2 v[90:91], v[92:93], off offset:192
	v_cvt_pk_bf16_f32 v93, v128, v129
	v_cvt_pk_bf16_f32 v92, v126, v127
	global_store_dwordx2 v[90:91], v[92:93], off offset:224
	v_or_b32_e32 v90, 16, v94
	v_mad_i64_i32 v[90:91], s[6:7], v90, s8, v[86:87]
	v_lshl_add_u64 v[90:91], v[90:91], 0, v[88:89]
	v_cvt_pk_bf16_f32 v93, v132, v133
	v_cvt_pk_bf16_f32 v92, v130, v131
	global_store_dwordx2 v[90:91], v[92:93], off
	v_cvt_pk_bf16_f32 v93, v124, v125
	v_cvt_pk_bf16_f32 v92, v122, v123
	global_store_dwordx2 v[90:91], v[92:93], off offset:32
	v_cvt_pk_bf16_f32 v93, v116, v117
	v_cvt_pk_bf16_f32 v92, v114, v115
	global_store_dwordx2 v[90:91], v[92:93], off offset:64
	v_cvt_pk_bf16_f32 v84, v84, v85
	v_cvt_pk_bf16_f32 v82, v82, v83
	v_mov_b32_e32 v83, v84
	global_store_dwordx2 v[90:91], v[82:83], off offset:96
	v_cvt_pk_bf16_f32 v80, v80, v81
	v_cvt_pk_bf16_f32 v78, v78, v79
	v_mov_b32_e32 v79, v80
	global_store_dwordx2 v[90:91], v[78:79], off offset:128
	v_cvt_pk_bf16_f32 v76, v76, v77
	v_cvt_pk_bf16_f32 v74, v74, v75
	v_mov_b32_e32 v75, v76
	global_store_dwordx2 v[90:91], v[74:75], off offset:160
	v_cvt_pk_bf16_f32 v72, v72, v73
	v_cvt_pk_bf16_f32 v70, v70, v71
	v_mov_b32_e32 v71, v72
	global_store_dwordx2 v[90:91], v[70:71], off offset:192
	v_cvt_pk_bf16_f32 v64, v64, v65
	v_cvt_pk_bf16_f32 v62, v62, v63
	v_mov_b32_e32 v63, v64
	v_cvt_pk_bf16_f32 v64, v68, v69
	v_cvt_pk_bf16_f32 v66, v66, v67
	global_store_dwordx2 v[90:91], v[62:63], off offset:224
	v_or_b32_e32 v62, 32, v94
	v_mad_i64_i32 v[62:63], s[6:7], v62, s8, v[86:87]
	v_lshl_add_u64 v[62:63], v[62:63], 0, v[88:89]
	v_mov_b32_e32 v65, v64
	v_mov_b32_e32 v64, v66
	global_store_dwordx2 v[62:63], v[64:65], off
	v_cvt_pk_bf16_f32 v60, v60, v61
	v_and_b32_sdwa v65, v58, v177 dst_sel:DWORD dst_unused:UNUSED_PAD src0_sel:WORD_1 src1_sel:DWORD
	v_add3_u32 v58, v58, v65, s28
	v_and_b32_sdwa v65, v59, v177 dst_sel:DWORD dst_unused:UNUSED_PAD src0_sel:WORD_1 src1_sel:DWORD
	v_add3_u32 v59, v59, v65, s28
	v_and_b32_e32 v64, 0xffff0000, v59
	v_mov_b32_e32 v59, v60
	v_or_b32_sdwa v58, v64, v58 dst_sel:DWORD dst_unused:UNUSED_PAD src0_sel:DWORD src1_sel:WORD_1
	global_store_dwordx2 v[62:63], v[58:59], off offset:32
	v_cvt_pk_bf16_f32 v56, v56, v57
	v_cvt_pk_bf16_f32 v54, v54, v55
	v_mov_b32_e32 v55, v56
	global_store_dwordx2 v[62:63], v[54:55], off offset:64
	v_cvt_pk_bf16_f32 v52, v52, v53
	v_cvt_pk_bf16_f32 v50, v50, v51
	v_mov_b32_e32 v51, v52
	global_store_dwordx2 v[62:63], v[50:51], off offset:96
	v_and_b32_sdwa v50, v48, v177 dst_sel:DWORD dst_unused:UNUSED_PAD src0_sel:WORD_1 src1_sel:DWORD
	v_and_b32_sdwa v51, v46, v177 dst_sel:DWORD dst_unused:UNUSED_PAD src0_sel:WORD_1 src1_sel:DWORD
	v_add3_u32 v46, v46, v51, s28
	v_add3_u32 v48, v48, v50, s28
	v_and_b32_sdwa v50, v49, v177 dst_sel:DWORD dst_unused:UNUSED_PAD src0_sel:WORD_1 src1_sel:DWORD
	v_and_b32_sdwa v51, v47, v177 dst_sel:DWORD dst_unused:UNUSED_PAD src0_sel:WORD_1 src1_sel:DWORD
	v_add3_u32 v49, v49, v50, s28
	v_add3_u32 v47, v47, v51, s28
	v_and_b32_e32 v49, 0xffff0000, v49
	v_and_b32_e32 v50, 0xffff0000, v47
	v_or_b32_sdwa v47, v49, v48 dst_sel:DWORD dst_unused:UNUSED_PAD src0_sel:DWORD src1_sel:WORD_1
	v_or_b32_sdwa v46, v50, v46 dst_sel:DWORD dst_unused:UNUSED_PAD src0_sel:DWORD src1_sel:WORD_1
	global_store_dwordx2 v[62:63], v[46:47], off offset:128
	v_and_b32_sdwa v46, v44, v177 dst_sel:DWORD dst_unused:UNUSED_PAD src0_sel:WORD_1 src1_sel:DWORD
	v_and_b32_sdwa v47, v42, v177 dst_sel:DWORD dst_unused:UNUSED_PAD src0_sel:WORD_1 src1_sel:DWORD
	v_add3_u32 v42, v42, v47, s28
	v_add3_u32 v44, v44, v46, s28
	v_and_b32_sdwa v46, v45, v177 dst_sel:DWORD dst_unused:UNUSED_PAD src0_sel:WORD_1 src1_sel:DWORD
	v_and_b32_sdwa v47, v43, v177 dst_sel:DWORD dst_unused:UNUSED_PAD src0_sel:WORD_1 src1_sel:DWORD
	v_add3_u32 v45, v45, v46, s28
	v_add3_u32 v43, v43, v47, s28
	v_and_b32_e32 v45, 0xffff0000, v45
	v_and_b32_e32 v46, 0xffff0000, v43
	v_or_b32_sdwa v43, v45, v44 dst_sel:DWORD dst_unused:UNUSED_PAD src0_sel:DWORD src1_sel:WORD_1
	v_or_b32_sdwa v42, v46, v42 dst_sel:DWORD dst_unused:UNUSED_PAD src0_sel:DWORD src1_sel:WORD_1
	global_store_dwordx2 v[62:63], v[42:43], off offset:160
	v_cvt_pk_bf16_f32 v40, v40, v41
	v_and_b32_sdwa v43, v38, v177 dst_sel:DWORD dst_unused:UNUSED_PAD src0_sel:WORD_1 src1_sel:DWORD
	v_add3_u32 v38, v38, v43, s28
	v_and_b32_sdwa v43, v39, v177 dst_sel:DWORD dst_unused:UNUSED_PAD src0_sel:WORD_1 src1_sel:DWORD
	v_add3_u32 v39, v39, v43, s28
	v_and_b32_e32 v42, 0xffff0000, v39
	v_mov_b32_e32 v39, v40
	v_or_b32_sdwa v38, v42, v38 dst_sel:DWORD dst_unused:UNUSED_PAD src0_sel:DWORD src1_sel:WORD_1
	global_store_dwordx2 v[62:63], v[38:39], off offset:192
	v_cvt_pk_bf16_f32 v32, v32, v33
	v_cvt_pk_bf16_f32 v30, v30, v31
	v_mov_b32_e32 v31, v32
	v_cvt_pk_bf16_f32 v32, v36, v37
	v_and_b32_sdwa v33, v34, v177 dst_sel:DWORD dst_unused:UNUSED_PAD src0_sel:WORD_1 src1_sel:DWORD
	v_add3_u32 v34, v34, v33, s28
	v_and_b32_sdwa v36, v35, v177 dst_sel:DWORD dst_unused:UNUSED_PAD src0_sel:WORD_1 src1_sel:DWORD
	global_store_dwordx2 v[62:63], v[30:31], off offset:224
	v_or_b32_e32 v30, 48, v94
	v_add3_u32 v35, v35, v36, s28
	v_mad_i64_i32 v[30:31], s[6:7], v30, s8, v[86:87]
	v_and_b32_e32 v35, 0xffff0000, v35
	v_lshl_add_u64 v[30:31], v[30:31], 0, v[88:89]
	v_mov_b32_e32 v33, v32
	v_or_b32_sdwa v32, v35, v34 dst_sel:DWORD dst_unused:UNUSED_PAD src0_sel:DWORD src1_sel:WORD_1
	global_store_dwordx2 v[30:31], v[32:33], off
	v_and_b32_sdwa v32, v28, v177 dst_sel:DWORD dst_unused:UNUSED_PAD src0_sel:WORD_1 src1_sel:DWORD
	v_cvt_pk_bf16_f32 v26, v26, v27
	v_add3_u32 v28, v28, v32, s28
	v_and_b32_sdwa v32, v29, v177 dst_sel:DWORD dst_unused:UNUSED_PAD src0_sel:WORD_1 src1_sel:DWORD
	v_add3_u32 v29, v29, v32, s28
	v_and_b32_e32 v29, 0xffff0000, v29
	v_or_b32_sdwa v27, v29, v28 dst_sel:DWORD dst_unused:UNUSED_PAD src0_sel:DWORD src1_sel:WORD_1
	global_store_dwordx2 v[30:31], v[26:27], off offset:32
	v_and_b32_sdwa v26, v24, v177 dst_sel:DWORD dst_unused:UNUSED_PAD src0_sel:WORD_1 src1_sel:DWORD
	v_and_b32_sdwa v27, v22, v177 dst_sel:DWORD dst_unused:UNUSED_PAD src0_sel:WORD_1 src1_sel:DWORD
	v_add3_u32 v22, v22, v27, s28
	v_add3_u32 v24, v24, v26, s28
	v_and_b32_sdwa v26, v25, v177 dst_sel:DWORD dst_unused:UNUSED_PAD src0_sel:WORD_1 src1_sel:DWORD
	v_and_b32_sdwa v27, v23, v177 dst_sel:DWORD dst_unused:UNUSED_PAD src0_sel:WORD_1 src1_sel:DWORD
	v_add3_u32 v25, v25, v26, s28
	v_add3_u32 v23, v23, v27, s28
	v_and_b32_e32 v25, 0xffff0000, v25
	v_and_b32_e32 v26, 0xffff0000, v23
	v_or_b32_sdwa v23, v25, v24 dst_sel:DWORD dst_unused:UNUSED_PAD src0_sel:DWORD src1_sel:WORD_1
	v_or_b32_sdwa v22, v26, v22 dst_sel:DWORD dst_unused:UNUSED_PAD src0_sel:DWORD src1_sel:WORD_1
	global_store_dwordx2 v[30:31], v[22:23], off offset:64
	v_and_b32_sdwa v22, v20, v177 dst_sel:DWORD dst_unused:UNUSED_PAD src0_sel:WORD_1 src1_sel:DWORD
	v_and_b32_sdwa v23, v18, v177 dst_sel:DWORD dst_unused:UNUSED_PAD src0_sel:WORD_1 src1_sel:DWORD
	v_add3_u32 v18, v18, v23, s28
	v_add3_u32 v20, v20, v22, s28
	v_and_b32_sdwa v22, v21, v177 dst_sel:DWORD dst_unused:UNUSED_PAD src0_sel:WORD_1 src1_sel:DWORD
	v_and_b32_sdwa v23, v19, v177 dst_sel:DWORD dst_unused:UNUSED_PAD src0_sel:WORD_1 src1_sel:DWORD
	v_add3_u32 v21, v21, v22, s28
	v_add3_u32 v19, v19, v23, s28
	v_and_b32_e32 v21, 0xffff0000, v21
	v_and_b32_e32 v22, 0xffff0000, v19
	v_or_b32_sdwa v19, v21, v20 dst_sel:DWORD dst_unused:UNUSED_PAD src0_sel:DWORD src1_sel:WORD_1
	v_or_b32_sdwa v18, v22, v18 dst_sel:DWORD dst_unused:UNUSED_PAD src0_sel:DWORD src1_sel:WORD_1
	global_store_dwordx2 v[30:31], v[18:19], off offset:96
	v_and_b32_sdwa v18, v16, v177 dst_sel:DWORD dst_unused:UNUSED_PAD src0_sel:WORD_1 src1_sel:DWORD
	v_cvt_pk_bf16_f32 v14, v14, v15
	v_add3_u32 v16, v16, v18, s28
	v_and_b32_sdwa v18, v17, v177 dst_sel:DWORD dst_unused:UNUSED_PAD src0_sel:WORD_1 src1_sel:DWORD
	v_add3_u32 v17, v17, v18, s28
	v_and_b32_e32 v17, 0xffff0000, v17
	v_or_b32_sdwa v15, v17, v16 dst_sel:DWORD dst_unused:UNUSED_PAD src0_sel:DWORD src1_sel:WORD_1
	global_store_dwordx2 v[30:31], v[14:15], off offset:128
	v_and_b32_sdwa v14, v12, v177 dst_sel:DWORD dst_unused:UNUSED_PAD src0_sel:WORD_1 src1_sel:DWORD
	v_and_b32_sdwa v15, v10, v177 dst_sel:DWORD dst_unused:UNUSED_PAD src0_sel:WORD_1 src1_sel:DWORD
	v_add3_u32 v10, v10, v15, s28
	v_add3_u32 v12, v12, v14, s28
	v_and_b32_sdwa v14, v13, v177 dst_sel:DWORD dst_unused:UNUSED_PAD src0_sel:WORD_1 src1_sel:DWORD
	v_and_b32_sdwa v15, v11, v177 dst_sel:DWORD dst_unused:UNUSED_PAD src0_sel:WORD_1 src1_sel:DWORD
	v_add3_u32 v13, v13, v14, s28
	v_add3_u32 v11, v11, v15, s28
	v_and_b32_e32 v13, 0xffff0000, v13
	v_and_b32_e32 v14, 0xffff0000, v11
	v_or_b32_sdwa v11, v13, v12 dst_sel:DWORD dst_unused:UNUSED_PAD src0_sel:DWORD src1_sel:WORD_1
	v_or_b32_sdwa v10, v14, v10 dst_sel:DWORD dst_unused:UNUSED_PAD src0_sel:DWORD src1_sel:WORD_1
	global_store_dwordx2 v[30:31], v[10:11], off offset:160
	v_and_b32_sdwa v10, v8, v177 dst_sel:DWORD dst_unused:UNUSED_PAD src0_sel:WORD_1 src1_sel:DWORD
	v_and_b32_sdwa v11, v6, v177 dst_sel:DWORD dst_unused:UNUSED_PAD src0_sel:WORD_1 src1_sel:DWORD
	v_add3_u32 v6, v6, v11, s28
	v_add3_u32 v8, v8, v10, s28
	v_and_b32_sdwa v10, v9, v177 dst_sel:DWORD dst_unused:UNUSED_PAD src0_sel:WORD_1 src1_sel:DWORD
	v_and_b32_sdwa v11, v7, v177 dst_sel:DWORD dst_unused:UNUSED_PAD src0_sel:WORD_1 src1_sel:DWORD
	v_add3_u32 v9, v9, v10, s28
	v_add3_u32 v7, v7, v11, s28
	v_and_b32_e32 v9, 0xffff0000, v9
	v_and_b32_e32 v10, 0xffff0000, v7
	v_or_b32_sdwa v7, v9, v8 dst_sel:DWORD dst_unused:UNUSED_PAD src0_sel:DWORD src1_sel:WORD_1
	v_or_b32_sdwa v6, v10, v6 dst_sel:DWORD dst_unused:UNUSED_PAD src0_sel:DWORD src1_sel:WORD_1
	global_store_dwordx2 v[30:31], v[6:7], off offset:192
	v_and_b32_sdwa v6, v4, v177 dst_sel:DWORD dst_unused:UNUSED_PAD src0_sel:WORD_1 src1_sel:DWORD
	v_and_b32_sdwa v7, v2, v177 dst_sel:DWORD dst_unused:UNUSED_PAD src0_sel:WORD_1 src1_sel:DWORD
	v_add3_u32 v2, v2, v7, s28
	v_add3_u32 v4, v4, v6, s28
	v_and_b32_sdwa v6, v5, v177 dst_sel:DWORD dst_unused:UNUSED_PAD src0_sel:WORD_1 src1_sel:DWORD
	v_and_b32_sdwa v7, v3, v177 dst_sel:DWORD dst_unused:UNUSED_PAD src0_sel:WORD_1 src1_sel:DWORD
	v_add3_u32 v5, v5, v6, s28
	v_add3_u32 v3, v3, v7, s28
	v_and_b32_e32 v5, 0xffff0000, v5
	v_and_b32_e32 v6, 0xffff0000, v3
	s_add_i32 s11, s11, s10
	v_or_b32_sdwa v3, v5, v4 dst_sel:DWORD dst_unused:UNUSED_PAD src0_sel:DWORD src1_sel:WORD_1
	v_or_b32_sdwa v2, v6, v2 dst_sel:DWORD dst_unused:UNUSED_PAD src0_sel:DWORD src1_sel:WORD_1
	s_cmpk_gt_i32 s11, 0x3ef
	global_store_dwordx2 v[30:31], v[2:3], off offset:224
	s_cbranch_scc0 .LBB0_664

.LBB0_741:
	s_waitcnt vmcnt(29)
	v_lshlrev_b32_e32 v116, 16, v104
	v_lshlrev_b32_e32 v112, 16, v76
	v_lshlrev_b32_e32 v113, 16, v103
	v_mov_b32_e32 v76, v116
	s_waitcnt vmcnt(28)
	v_lshlrev_b32_e32 v115, 16, v108
	v_mov_b32_e32 v114, v113
	v_pk_mul_f32 v[76:77], v[74:75], v[76:77]
	s_waitcnt vmcnt(27)
	v_lshlrev_b32_e32 v117, 16, v109
	v_mov_b32_e32 v108, v112
	v_mov_b32_e32 v109, v116
	v_pk_fma_f32 v[76:77], v[74:75], v[112:113], v[76:77] op_sel:[0,0,1] op_sel_hi:[1,1,0]
	v_pk_mul_f32 v[112:113], v[74:75], v[114:115] op_sel_hi:[0,1]
	v_mov_b32_e32 v104, v75
	v_pk_fma_f32 v[76:77], v[0:1], v[114:115], v[76:77] op_sel_hi:[0,1,1]
	s_waitcnt vmcnt(15)
	v_pk_fma_f32 v[108:109], v[104:105], v[108:109], v[112:113] op_sel_hi:[0,1,1]
	v_pk_fma_f32 v[108:109], v[0:1], v[116:117], v[108:109] op_sel_hi:[0,1,1]
	v_cvt_pk_bf16_f32 v77, v77, v109
	v_cvt_pk_bf16_f32 v76, v76, v108
	v_mov_b32_e32 v109, v77
	v_lshlrev_b32_e32 v77, 16, v110
	v_mov_b32_e32 v108, v76
	v_lshlrev_b32_e32 v76, 16, v91
	v_lshlrev_b32_e32 v111, 16, v94
	v_mov_b32_e32 v116, v77
	v_mov_b32_e32 v110, v76
	v_mov_b32_e32 v118, v117
	v_mov_b32_e32 v119, v111
	v_pk_mul_f32 v[116:117], v[74:75], v[116:117]
	v_lshlrev_b32_e32 v113, 16, v107
	v_mov_b32_e32 v112, v111
	v_pk_mov_b32 v[114:115], v[114:115], v[110:111] op_sel:[1,0]
	v_pk_mul_f32 v[118:119], v[74:75], v[118:119] op_sel_hi:[0,1]
	v_pk_fma_f32 v[110:111], v[74:75], v[110:111], v[116:117] op_sel:[0,0,1] op_sel_hi:[1,1,0]
	v_pk_fma_f32 v[114:115], v[104:105], v[114:115], v[118:119] op_sel_hi:[0,1,1]
	v_pk_fma_f32 v[110:111], v[0:1], v[112:113], v[110:111] op_sel_hi:[0,1,1]
	v_pk_fma_f32 v[114:115], v[0:1], v[76:77], v[114:115] op_sel_hi:[0,1,1]
	v_cvt_pk_bf16_f32 v94, v114, v110
	v_cvt_pk_bf16_f32 v91, v115, v111
	v_lshlrev_b32_e32 v114, 16, v95
	v_lshlrev_b32_e32 v95, 16, v97
	v_mov_b32_e32 v110, v94
	v_lshlrev_b32_e32 v115, 16, v101
	v_mov_b32_e32 v94, v114
	v_mov_b32_e32 v116, v113
	v_mov_b32_e32 v117, v95
	v_pk_mov_b32 v[76:77], v[76:77], v[94:95] op_sel:[1,0]
	v_pk_mul_f32 v[116:117], v[74:75], v[116:117] op_sel_hi:[0,1]
	v_mov_b32_e32 v112, v115
	v_pk_fma_f32 v[76:77], v[104:105], v[76:77], v[116:117] op_sel_hi:[0,1,1]
	v_pk_mul_f32 v[112:113], v[74:75], v[112:113]
	v_lshlrev_b32_e32 v101, 16, v100
	v_mov_b32_e32 v100, v95
	v_pk_fma_f32 v[76:77], v[0:1], v[114:115], v[76:77] op_sel_hi:[0,1,1]
	v_pk_fma_f32 v[94:95], v[74:75], v[94:95], v[112:113] op_sel:[0,0,1] op_sel_hi:[1,1,0]
	v_mov_b32_e32 v111, v91
	v_pk_fma_f32 v[94:95], v[0:1], v[100:101], v[94:95] op_sel_hi:[0,1,1]
	v_cvt_pk_bf16_f32 v77, v77, v95
	v_cvt_pk_bf16_f32 v76, v76, v94
	v_mov_b32_e32 v113, v77
	v_lshlrev_b32_e32 v77, 16, v106
	v_mov_b32_e32 v112, v76
	v_lshlrev_b32_e32 v76, 16, v86
	v_lshlrev_b32_e32 v95, 16, v88
	v_mov_b32_e32 v100, v77
	v_mov_b32_e32 v94, v76
	v_mov_b32_e32 v116, v101
	v_mov_b32_e32 v117, v95
	v_pk_mul_f32 v[100:101], v[74:75], v[100:101]
	v_lshlrev_b32_e32 v107, 16, v105
	v_mov_b32_e32 v106, v95
	v_pk_mov_b32 v[114:115], v[114:115], v[94:95] op_sel:[1,0]
	v_pk_mul_f32 v[116:117], v[74:75], v[116:117] op_sel_hi:[0,1]
	v_pk_fma_f32 v[94:95], v[74:75], v[94:95], v[100:101] op_sel:[0,0,1] op_sel_hi:[1,1,0]
	v_pk_fma_f32 v[114:115], v[104:105], v[114:115], v[116:117] op_sel_hi:[0,1,1]
	v_pk_fma_f32 v[94:95], v[0:1], v[106:107], v[94:95] op_sel_hi:[0,1,1]
	v_pk_fma_f32 v[114:115], v[0:1], v[76:77], v[114:115] op_sel_hi:[0,1,1]
	v_cvt_pk_bf16_f32 v88, v114, v94
	v_mov_b32_e32 v114, v88
	s_waitcnt vmcnt(14)
	v_lshlrev_b32_e32 v94, 16, v89
	s_waitcnt vmcnt(13)
	v_lshlrev_b32_e32 v89, 16, v90
	v_cvt_pk_bf16_f32 v115, v115, v95
	s_waitcnt vmcnt(12)
	v_lshlrev_b32_e32 v95, 16, v98
	v_mov_b32_e32 v88, v94
	s_waitcnt vmcnt(11)
	v_lshlrev_b32_e32 v91, 16, v96
	v_mov_b32_e32 v96, v107
	v_mov_b32_e32 v97, v89
	v_pk_mov_b32 v[76:77], v[76:77], v[88:89] op_sel:[1,0]
	v_pk_mul_f32 v[96:97], v[74:75], v[96:97] op_sel_hi:[0,1]
	v_mov_b32_e32 v106, v95
	v_pk_fma_f32 v[76:77], v[104:105], v[76:77], v[96:97] op_sel_hi:[0,1,1]
	v_pk_mul_f32 v[96:97], v[74:75], v[106:107]
	v_mov_b32_e32 v90, v89
	v_pk_fma_f32 v[76:77], v[0:1], v[94:95], v[76:77] op_sel_hi:[0,1,1]
	v_pk_fma_f32 v[88:89], v[74:75], v[88:89], v[96:97] op_sel:[0,0,1] op_sel_hi:[1,1,0]
	v_and_b32_sdwa v86, v77, v177 dst_sel:DWORD dst_unused:UNUSED_PAD src0_sel:WORD_1 src1_sel:DWORD
	v_pk_fma_f32 v[88:89], v[0:1], v[90:91], v[88:89] op_sel_hi:[0,1,1]
	v_cvt_pk_bf16_f32 v76, v76, v88
	v_add3_u32 v77, v77, v86, s28
	v_and_b32_sdwa v86, v89, v177 dst_sel:DWORD dst_unused:UNUSED_PAD src0_sel:WORD_1 src1_sel:DWORD
	v_add3_u32 v86, v89, v86, s28
	v_and_b32_e32 v86, 0xffff0000, v86
	v_or_b32_sdwa v89, v86, v77 dst_sel:DWORD dst_unused:UNUSED_PAD src0_sel:DWORD src1_sel:WORD_1
	v_mov_b32_e32 v88, v76
	s_waitcnt vmcnt(8)
	v_lshlrev_b32_e32 v77, 16, v102
	v_lshlrev_b32_e32 v76, 16, v82
	v_lshlrev_b32_e32 v83, 16, v83
	v_mov_b32_e32 v82, v76
	s_waitcnt vmcnt(7)
	v_lshlrev_b32_e32 v97, 16, v99
	v_mov_b32_e32 v98, v91
	v_mov_b32_e32 v99, v83
	v_mov_b32_e32 v90, v77
	v_pk_mov_b32 v[94:95], v[94:95], v[82:83] op_sel:[1,0]
	v_pk_mul_f32 v[98:99], v[74:75], v[98:99] op_sel_hi:[0,1]
	v_pk_mul_f32 v[90:91], v[74:75], v[90:91]
	v_mov_b32_e32 v96, v83
	v_pk_fma_f32 v[94:95], v[104:105], v[94:95], v[98:99] op_sel_hi:[0,1,1]
	v_pk_fma_f32 v[82:83], v[74:75], v[82:83], v[90:91] op_sel:[0,0,1] op_sel_hi:[1,1,0]
	v_pk_fma_f32 v[94:95], v[0:1], v[76:77], v[94:95] op_sel_hi:[0,1,1]
	v_pk_fma_f32 v[82:83], v[0:1], v[96:97], v[82:83] op_sel_hi:[0,1,1]
	v_cvt_pk_bf16_f32 v90, v94, v82
	v_cvt_pk_bf16_f32 v86, v95, v83
	v_mov_b32_e32 v91, v86
	s_waitcnt vmcnt(5)
	v_lshlrev_b32_e32 v83, 16, v87
	s_waitcnt vmcnt(4)
	v_lshlrev_b32_e32 v95, 16, v92
	v_lshlrev_b32_e32 v82, 16, v84
	s_waitcnt vmcnt(3)
	v_lshlrev_b32_e32 v87, 16, v93
	v_mov_b32_e32 v92, v97
	v_mov_b32_e32 v93, v83
	v_pk_mov_b32 v[76:77], v[76:77], v[82:83] op_sel:[1,0]
	v_pk_mul_f32 v[92:93], v[74:75], v[92:93] op_sel_hi:[0,1]
	v_mov_b32_e32 v96, v95
	v_mov_b32_e32 v94, v82
	v_pk_fma_f32 v[76:77], v[104:105], v[76:77], v[92:93] op_sel_hi:[0,1,1]
	v_pk_mul_f32 v[92:93], v[74:75], v[96:97]
	v_mov_b32_e32 v86, v83
	v_pk_fma_f32 v[76:77], v[0:1], v[94:95], v[76:77] op_sel_hi:[0,1,1]
	v_pk_fma_f32 v[82:83], v[74:75], v[82:83], v[92:93] op_sel:[0,0,1] op_sel_hi:[1,1,0]
	v_and_b32_sdwa v84, v77, v177 dst_sel:DWORD dst_unused:UNUSED_PAD src0_sel:WORD_1 src1_sel:DWORD
	v_pk_fma_f32 v[82:83], v[0:1], v[86:87], v[82:83] op_sel_hi:[0,1,1]
	v_cvt_pk_bf16_f32 v76, v76, v82
	v_add3_u32 v77, v77, v84, s28
	v_and_b32_sdwa v84, v83, v177 dst_sel:DWORD dst_unused:UNUSED_PAD src0_sel:WORD_1 src1_sel:DWORD
	v_add3_u32 v83, v83, v84, s28
	v_and_b32_e32 v83, 0xffff0000, v83
	v_or_b32_sdwa v83, v83, v77 dst_sel:DWORD dst_unused:UNUSED_PAD src0_sel:DWORD src1_sel:WORD_1
	v_mov_b32_e32 v82, v76
	s_waitcnt vmcnt(2)
	v_lshlrev_b32_e32 v76, 16, v81
	v_mul_f32_e32 v77, v74, v87
	v_fmac_f32_e32 v77, v75, v95
	v_mul_f32_e32 v81, v74, v76
	v_fmac_f32_e32 v77, v0, v76
	s_waitcnt vmcnt(1)
	v_lshlrev_b32_e32 v80, 16, v80
	v_fmac_f32_e32 v81, v75, v87
	v_fmac_f32_e32 v81, v0, v80
	v_bfe_u32 v84, v77, 16, 1
	v_add3_u32 v77, v77, v84, s28
	v_bfe_u32 v84, v81, 16, 1
	v_lshrrev_b32_e32 v77, 16, v77
	v_add3_u32 v81, v81, v84, s28
	v_and_or_b32 v84, v81, s42, v77
	s_waitcnt vmcnt(0)
	v_lshlrev_b32_e32 v77, 16, v85
	v_mul_f32_e32 v81, v74, v80
	v_fmac_f32_e32 v81, v75, v76
	v_mul_f32_e32 v74, v74, v77
	v_fmac_f32_e32 v81, v0, v77
	v_fmac_f32_e32 v74, v75, v80
	v_fmac_f32_e32 v74, v0, v79
	v_bfe_u32 v0, v81, 16, 1
	v_add3_u32 v0, v81, v0, s28
	v_bfe_u32 v75, v74, 16, 1
	v_lshrrev_b32_e32 v0, 16, v0
	v_add3_u32 v74, v74, v75, s28
	v_and_or_b32 v85, v74, s42, v0
	v_lshl_add_u64 v[74:75], s[52:53], 0, v[30:31]
	s_mov_b32 s2, 0xe735000
	v_add_co_u32_e32 v74, vcc, s2, v74
	v_add_u32_e32 v78, 0x200, v78
	s_nop 0
	v_addc_co_u32_e32 v75, vcc, 0, v75, vcc
	s_mov_b64 s[2:3], 0x1200000
	v_cmp_lt_i32_e32 vcc, s33, v78
	v_lshl_add_u64 v[30:31], v[30:31], 0, s[2:3]
	v_lshl_add_u64 v[4:5], v[4:5], 0, s[0:1]
	v_lshl_add_u64 v[6:7], v[6:7], 0, s[0:1]
	v_lshl_add_u64 v[8:9], v[8:9], 0, s[0:1]
	v_lshl_add_u64 v[10:11], v[10:11], 0, s[0:1]
	v_lshl_add_u64 v[12:13], v[12:13], 0, s[0:1]
	v_lshl_add_u64 v[14:15], v[14:15], 0, s[0:1]
	v_lshl_add_u64 v[16:17], v[16:17], 0, s[0:1]
	v_lshl_add_u64 v[18:19], v[18:19], 0, s[0:1]
	v_lshl_add_u64 v[20:21], v[20:21], 0, s[0:1]
	v_lshl_add_u64 v[22:23], v[22:23], 0, s[0:1]
	v_lshl_add_u64 v[24:25], v[24:25], 0, s[0:1]
	v_lshl_add_u64 v[26:27], v[26:27], 0, s[0:1]
	v_lshl_add_u64 v[28:29], v[28:29], 0, s[0:1]
	v_lshl_add_u64 v[32:33], v[32:33], 0, s[0:1]
	v_lshl_add_u64 v[34:35], v[34:35], 0, s[0:1]
	v_lshl_add_u64 v[36:37], v[36:37], 0, s[0:1]
	v_lshl_add_u64 v[38:39], v[38:39], 0, s[0:1]
	v_lshl_add_u64 v[40:41], v[40:41], 0, s[0:1]
	v_lshl_add_u64 v[42:43], v[42:43], 0, s[0:1]
	v_lshl_add_u64 v[44:45], v[44:45], 0, s[0:1]
	v_lshl_add_u64 v[46:47], v[46:47], 0, s[0:1]
	v_lshl_add_u64 v[48:49], v[48:49], 0, s[0:1]
	v_lshl_add_u64 v[50:51], v[50:51], 0, s[0:1]
	v_lshl_add_u64 v[52:53], v[52:53], 0, s[0:1]
	v_lshl_add_u64 v[54:55], v[54:55], 0, s[0:1]
	v_lshl_add_u64 v[56:57], v[56:57], 0, s[0:1]
	v_lshl_add_u64 v[58:59], v[58:59], 0, s[0:1]
	v_lshl_add_u64 v[60:61], v[60:61], 0, s[0:1]
	v_lshl_add_u64 v[62:63], v[62:63], 0, s[0:1]
	v_lshl_add_u64 v[64:65], v[64:65], 0, s[0:1]
	v_lshl_add_u64 v[66:67], v[66:67], 0, s[0:1]
	v_lshl_add_u64 v[68:69], v[68:69], 0, s[0:1]
	v_lshl_add_u64 v[70:71], v[70:71], 0, s[0:1]
	v_lshl_add_u64 v[72:73], v[72:73], 0, s[0:1]
	s_or_b64 s[46:47], vcc, s[46:47]
	s_mov_b64 s[40:41], 0x800
	v_lshl_add_u64 v[2:3], v[2:3], 0, s[6:7]
	global_store_dwordx4 v[74:75], v[108:111], off offset:2048
	global_store_dwordx4 v[74:75], v[112:115], off offset:2064
	global_store_dwordx4 v[74:75], v[88:91], off offset:2080
	global_store_dwordx4 v[74:75], v[82:85], off offset:2096
	s_andn2_b64 exec, exec, s[46:47]
	s_cbranch_execz .LBB0_722

.LBB0_974:
	s_waitcnt lgkmcnt(0)
	s_add_u32 s90, s18, 0x6035800
	s_addc_u32 s91, s19, 0
	s_or_b32 s15, s14, 64
	v_ashrrev_i32_e32 v51, 2, v50
	v_mov_b32_e32 v0, s15
	v_mov_b32_e32 v2, s14
	v_cmp_gt_i32_e32 vcc, 64, v51
	s_and_b32 s10, s4, 3
	s_lshl_b32 s4, s10, 7
	v_cndmask_b32_e32 v0, v0, v2, vcc
	v_and_b32_e32 v2, 63, v51
	v_add_u32_e32 v0, v0, v2
	v_mov_b64_e32 v[2:3], s[90:91]
	v_mad_i64_i32 v[2:3], s[20:21], v0, s24, v[2:3]
	v_lshlrev_b32_e32 v0, 4, v50
	v_and_b32_e32 v10, 48, v0
	v_lshl_add_u64 v[2:3], v[2:3], 0, s[4:5]
	v_lshlrev_b32_e32 v0, 1, v10
	s_waitcnt vmcnt(2)
	v_lshl_add_u64 v[6:7], v[2:3], 0, v[0:1]
	s_load_dwordx4 s[44:47], s[16:17], 0x98
	s_waitcnt lgkmcnt(0)
	s_barrier
	global_load_dwordx4 v[2:5], v[6:7], off offset:1536
	s_nop 0
	global_load_dwordx4 v[6:9], v[6:7], off offset:1552
	v_readlane_b32 s2, v255, 55
	v_readlane_b32 s3, v255, 56
	s_lshl_b64 s[48:49], s[2:3], 2
	s_add_u32 s20, s44, s48
	v_lshlrev_b32_e32 v22, 2, v10
	s_addc_u32 s21, s45, s49
	global_load_dwordx4 v[10:13], v22, s[20:21]
	global_load_dwordx4 v[14:17], v22, s[20:21] offset:16
	global_load_dwordx4 v[18:21], v22, s[20:21] offset:32
	s_nop 0
	global_load_dwordx4 v[22:25], v22, s[20:21] offset:48
	v_cmp_lt_i32_e32 vcc, v188, v182
	s_movk_i32 s2, 0x90
	s_waitcnt vmcnt(5)
	v_lshlrev_b32_e32 v29, 16, v5
	v_cndmask_b32_e32 v26, v181, v188, vcc
	v_cmp_lt_i32_e32 vcc, v191, v182
	v_lshlrev_b32_e32 v58, 2, v26
	v_lshlrev_b32_e32 v26, 16, v2
	v_cndmask_b32_e32 v27, v181, v191, vcc
	v_lshlrev_b32_e32 v59, 2, v27
	v_lshlrev_b32_e32 v27, 16, v3
	v_and_b32_e32 v3, 0xffff0000, v3
	v_and_b32_e32 v2, 0xffff0000, v2
	v_pk_mul_f32 v[34:35], v[26:27], v[26:27]
	v_pk_mul_f32 v[36:37], v[2:3], v[2:3]
	v_lshlrev_b32_e32 v28, 16, v4
	v_add_f32_e32 v34, v34, v36
	v_add_f32_e32 v34, v34, v35
	v_and_b32_e32 v5, 0xffff0000, v5
	v_and_b32_e32 v4, 0xffff0000, v4
	v_pk_mul_f32 v[38:39], v[28:29], v[28:29]
	v_add_f32_e32 v34, v37, v34
	v_pk_mul_f32 v[40:41], v[4:5], v[4:5]
	v_add_f32_e32 v34, v38, v34
	s_waitcnt vmcnt(4)
	v_lshlrev_b32_e32 v30, 16, v6
	v_and_b32_e32 v6, 0xffff0000, v6
	v_add_f32_e32 v34, v40, v34
	v_mov_b32_e32 v42, v6
	v_mov_b32_e32 v43, v30
	v_add_f32_e32 v34, v39, v34
	v_lshlrev_b32_e32 v31, 16, v7
	v_and_b32_e32 v7, 0xffff0000, v7
	v_pk_mul_f32 v[42:43], v[42:43], v[42:43]
	v_add_f32_e32 v34, v41, v34
	v_mov_b32_e32 v44, v7
	v_mov_b32_e32 v45, v31
	v_add_f32_e32 v34, v43, v34
	v_lshlrev_b32_e32 v32, 16, v8
	v_and_b32_e32 v8, 0xffff0000, v8
	v_pk_mul_f32 v[44:45], v[44:45], v[44:45]
	v_add_f32_e32 v34, v42, v34
	v_mov_b32_e32 v46, v8
	v_mov_b32_e32 v47, v32
	v_add_f32_e32 v34, v45, v34
	v_lshlrev_b32_e32 v33, 16, v9
	v_and_b32_e32 v9, 0xffff0000, v9
	v_pk_mul_f32 v[46:47], v[46:47], v[46:47]
	v_add_f32_e32 v34, v44, v34
	v_mov_b32_e32 v48, v9
	v_mov_b32_e32 v49, v33
	v_add_f32_e32 v34, v47, v34
	v_pk_mul_f32 v[48:49], v[48:49], v[48:49]
	v_add_f32_e32 v34, v46, v34
	v_add_f32_e32 v34, v49, v34
	v_add_f32_e32 v38, v48, v34
	ds_bpermute_b32 v39, v58, v38
	v_mad_u64_u32 v[34:35], s[20:21], v51, s2, v[0:1]
	s_waitcnt vmcnt(3)
	v_mov_b32_e32 v36, v10
	s_waitcnt vmcnt(2)
	v_mov_b32_e32 v10, v14
	s_waitcnt lgkmcnt(0)
	v_add_f32_e32 v0, v38, v39
	ds_bpermute_b32 v35, v59, v0
	v_mov_b32_e32 v37, v12
	v_mov_b32_e32 v12, v11
	v_mov_b32_e32 v11, v16
	v_mov_b32_e32 v16, v15
	s_waitcnt lgkmcnt(0)
	v_add_f32_e32 v0, v0, v35
	v_fmamk_f32 v0, v0, 0x3c800000, v174
	v_mul_f32_e32 v14, 0x4b800000, v0
	v_cmp_gt_f32_e32 vcc, s27, v0
	s_waitcnt vmcnt(1)
	v_mov_b32_e32 v15, v20
	v_mov_b32_e32 v20, v19
	v_cndmask_b32_e32 v0, v0, v14, vcc
	v_rsq_f32_e32 v0, v0
	v_mov_b32_e32 v14, v18
	s_movk_i32 s2, 0x1d1
	v_mul_f32_e32 v18, 0x45800000, v0
	v_cndmask_b32_e32 v0, v0, v18, vcc
	v_pk_mul_f32 v[2:3], v[0:1], v[2:3] op_sel_hi:[0,1]
	v_pk_mul_f32 v[18:19], v[0:1], v[26:27] op_sel_hi:[0,1]
	v_pk_mul_f32 v[4:5], v[0:1], v[4:5] op_sel_hi:[0,1]
	v_pk_mul_f32 v[2:3], v[12:13], v[2:3]
	v_pk_mul_f32 v[18:19], v[36:37], v[18:19]
	v_pk_mul_f32 v[4:5], v[16:17], v[4:5]
	v_cvt_pk_bf16_f32 v12, v19, v3
	v_cvt_pk_bf16_f32 v13, v18, v2
	v_pk_mul_f32 v[26:27], v[0:1], v[28:29] op_sel_hi:[0,1]
	v_pk_mul_f32 v[10:11], v[10:11], v[26:27]
	v_mov_b32_e32 v3, v12
	v_mov_b32_e32 v2, v13
	v_cvt_pk_bf16_f32 v11, v11, v5
	v_cvt_pk_bf16_f32 v10, v10, v4
	v_mov_b32_e32 v5, v11
	v_mov_b32_e32 v4, v10
	v_pk_mul_f32 v[10:11], v[0:1], v[30:31] op_sel_hi:[0,1]
	v_pk_mul_f32 v[10:11], v[14:15], v[10:11]
	v_pk_mul_f32 v[6:7], v[0:1], v[6:7] op_sel_hi:[0,1]
	v_pk_mul_f32 v[6:7], v[20:21], v[6:7]
	v_cvt_pk_bf16_f32 v11, v11, v7
	v_cvt_pk_bf16_f32 v10, v10, v6
	v_mov_b32_e32 v7, v11
	v_mov_b32_e32 v6, v10
	v_pk_mul_f32 v[10:11], v[0:1], v[32:33] op_sel_hi:[0,1]
	s_waitcnt vmcnt(0)
	v_mov_b32_e32 v12, v22
	v_mov_b32_e32 v13, v24
	v_pk_mul_f32 v[10:11], v[12:13], v[10:11]
	v_pk_mul_f32 v[8:9], v[0:1], v[8:9] op_sel_hi:[0,1]
	v_mov_b32_e32 v24, v23
	v_pk_mul_f32 v[8:9], v[24:25], v[8:9]
	v_and_b32_sdwa v0, v11, v177 dst_sel:DWORD dst_unused:UNUSED_PAD src0_sel:WORD_1 src1_sel:DWORD
	v_cvt_pk_bf16_f32 v10, v10, v8
	v_add3_u32 v0, v11, v0, s28
	v_and_b32_sdwa v11, v9, v177 dst_sel:DWORD dst_unused:UNUSED_PAD src0_sel:WORD_1 src1_sel:DWORD
	v_add3_u32 v9, v9, v11, s28
	v_and_b32_e32 v9, 0xffff0000, v9
	v_cmp_gt_i32_e32 vcc, s2, v50
	v_or_b32_sdwa v9, v9, v0 dst_sel:DWORD dst_unused:UNUSED_PAD src0_sel:DWORD src1_sel:WORD_1
	v_mov_b32_e32 v8, v10
	ds_write_b128 v34, v[2:5]
	ds_write_b128 v34, v[6:9] offset:16
	s_and_saveexec_b64 s[44:45], vcc
	s_cbranch_execz .LBB0_982
	s_load_dwordx2 s[50:51], s[16:17], 0xa8
	v_max_i32_e32 v0, 0xffffffd1, v50
	v_sub_u32_e32 v0, v0, v50
	v_add_u32_e32 v0, 0x1ff, v0
	s_movk_i32 s2, 0x1ff
	v_cmp_lt_u32_e32 vcc, s2, v0
	s_mov_b64 s[54:55], -1
	v_mov_b32_e32 v2, v50
	s_and_saveexec_b64 s[52:53], vcc
	s_cbranch_execz .LBB0_979
	v_readlane_b32 s2, v255, 57
	s_or_b32 s2, s10, s2
	s_mul_i32 s4, s2, 0x1d1
	v_lshrrev_b32_e32 v0, 9, v0
	s_lshl_b64 s[20:21], s[4:5], 2
	v_add_u32_e32 v0, 1, v0
	s_waitcnt lgkmcnt(0)
	s_add_u32 s54, s50, s20
	v_and_b32_e32 v4, 0xfffffe, v0
	v_add_u32_e32 v51, 0x200, v50
	s_addc_u32 s55, s51, s21
	v_lshl_add_u32 v5, v50, 2, v195
	s_mov_b64 s[56:57], 0
	v_mov_b32_e32 v6, v4
	v_mov_b64_e32 v[2:3], v[50:51]
	v_readlane_b32 s3, v255, 58

.LBB0_990:
	s_barrier
	global_load_dwordx4 v[34:37], v[52:53], off
	global_load_dwordx4 v[38:41], v[52:53], off offset:16
	s_waitcnt vmcnt(2)
	v_lshlrev_b32_e32 v42, 16, v2
	v_and_b32_e32 v44, 0xffff0000, v2
	v_lshlrev_b32_e32 v43, 16, v3
	v_and_b32_e32 v45, 0xffff0000, v3
	v_mov_b32_e32 v88, v42
	v_mov_b32_e32 v89, v44
	v_mov_b32_e32 v90, v45
	v_mov_b32_e32 v91, v43
	v_pk_mul_f32 v[88:89], v[88:89], v[88:89]
	v_lshlrev_b32_e32 v46, 16, v4
	v_and_b32_e32 v48, 0xffff0000, v4
	v_pk_mul_f32 v[90:91], v[90:91], v[90:91]
	v_add_f32_e32 v0, v88, v89
	v_mov_b32_e32 v92, v48
	v_mov_b32_e32 v93, v46
	v_add_f32_e32 v0, v91, v0
	v_lshlrev_b32_e32 v47, 16, v5
	v_and_b32_e32 v49, 0xffff0000, v5
	v_pk_mul_f32 v[92:93], v[92:93], v[92:93]
	v_add_f32_e32 v0, v90, v0
	v_mov_b32_e32 v94, v49
	v_mov_b32_e32 v95, v47
	v_add_f32_e32 v0, v93, v0
	v_pk_mul_f32 v[94:95], v[94:95], v[94:95]
	v_add_f32_e32 v0, v92, v0
	v_add_f32_e32 v0, v95, v0
	v_add_f32_e32 v0, v94, v0
	ds_bpermute_b32 v87, v58, v0
	s_add_i32 s7, s20, 1
	s_cmp_ge_i32 s7, s10
	s_waitcnt lgkmcnt(0)
	v_add_f32_e32 v0, v0, v87
	ds_bpermute_b32 v87, v59, v0
	s_waitcnt lgkmcnt(0)
	v_add_f32_e32 v0, v0, v87
	ds_bpermute_b32 v87, v64, v0
	s_waitcnt lgkmcnt(0)
	v_add_f32_e32 v0, v0, v87
	v_fmamk_f32 v0, v0, 0x3c800000, v174
	v_mul_f32_e32 v87, 0x4b800000, v0
	v_cmp_gt_f32_e64 s[90:91], s27, v0
	s_waitcnt vmcnt(1)
	v_mov_b32_e32 v88, v34
	v_cndmask_b32_e64 v0, v0, v87, s[90:91]
	v_rsq_f32_e32 v0, v0
	v_mov_b32_e32 v89, v36
	v_mov_b32_e32 v36, v35
	s_waitcnt vmcnt(0)
	v_mov_b32_e32 v34, v38
	v_mul_f32_e32 v87, 0x45800000, v0
	v_cndmask_b32_e64 v0, v0, v87, s[90:91]
	v_pk_mul_f32 v[42:43], v[0:1], v[42:43] op_sel_hi:[0,1]
	v_pk_mul_f32 v[44:45], v[0:1], v[44:45] op_sel_hi:[0,1]
	v_pk_mul_f32 v[46:47], v[0:1], v[46:47] op_sel_hi:[0,1]
	v_pk_mul_f32 v[48:49], v[0:1], v[48:49] op_sel_hi:[0,1]
	v_mov_b32_e32 v35, v40
	v_mov_b32_e32 v40, v39
	v_pk_mul_f32 v[38:39], v[88:89], v[42:43]
	v_pk_mul_f32 v[36:37], v[36:37], v[44:45]
	v_pk_mul_f32 v[34:35], v[34:35], v[46:47]
	v_pk_mul_f32 v[40:41], v[40:41], v[48:49]
	v_cvt_pk_bf16_f32 v0, v39, v37
	v_cvt_pk_bf16_f32 v38, v38, v36
	v_cvt_pk_bf16_f32 v42, v35, v41
	v_cvt_pk_bf16_f32 v39, v34, v40
	v_mov_b32_e32 v35, v0
	v_mov_b32_e32 v34, v38
	v_mov_b32_e32 v37, v42
	v_mov_b32_e32 v36, v39
	ds_write_b128 v84, v[34:37] offset:18432
	ds_write_b16 v55, v6 offset:27648
	ds_write_b16_d16_hi v65, v6 offset:27792
	ds_write_b16 v55, v7 offset:27936
	ds_write_b16_d16_hi v65, v7 offset:28080
	ds_write_b16 v55, v8 offset:28224
	ds_write_b16_d16_hi v65, v8 offset:28368
	ds_write_b16 v55, v9 offset:28512
	ds_write_b16_d16_hi v65, v9 offset:28656
	s_waitcnt lgkmcnt(0)
	s_barrier
	s_cbranch_scc1 .LBB0_994
	s_cmp_ge_i32 s7, s31
	s_mov_b32 s21, s4
	s_cbranch_scc1 .LBB0_993
	s_add_i32 s2, s7, s23
	s_lshl_b32 s2, s2, 6
	s_add_i32 s21, s2, s25

.LBB0_1034:
	s_waitcnt vmcnt(1)
	v_mov_b32_e32 v3, v67
	s_nop 1
	v_permlane32_swap_b32_e32 v67, v3
	v_add_f32_e32 v3, v67, v3
	v_mov_b32_e32 v4, v3
	s_nop 1
	v_permlane16_swap_b32_e32 v3, v4
	v_add_f32_e32 v3, v3, v4
	v_div_scale_f32 v4, s[6:7], v3, v3, 1.0
	v_rcp_f32_e32 v5, v4
	s_movk_i32 s2, 0x100
	v_mov_b32_e32 v2, s15
	s_waitcnt vmcnt(0)
	v_mov_b32_e32 v6, s14
	v_cmp_gt_u32_e32 vcc, s2, v50
	s_lshl_b32 s4, s26, 1
	v_mov_b32_e32 v9, v12
	v_cndmask_b32_e32 v6, v2, v6, vcc
	v_fma_f32 v2, -v4, v5, 1.0
	v_fmac_f32_e32 v5, v2, v5
	v_div_scale_f32 v2, vcc, 1.0, v3, 1.0
	v_mul_f32_e32 v7, v2, v5
	v_fma_f32 v8, -v4, v7, v2
	v_fmac_f32_e32 v7, v8, v5
	v_fma_f32 v2, -v4, v7, v2
	v_add_u32_e32 v4, v6, v51
	v_div_fmas_f32 v2, v2, v5, v7
	v_ashrrev_i32_e32 v5, 31, v4
	v_lshlrev_b64 v[4:5], 11, v[4:5]
	v_div_fixup_f32 v2, v2, v3, 1.0
	v_lshl_add_u64 v[4:5], s[18:19], 0, v[4:5]
	v_mov_b32_e32 v8, v10
	v_lshl_add_u64 v[4:5], v[4:5], 0, s[4:5]
	v_pk_mul_f32 v[8:9], v[8:9], v[2:3] op_sel_hi:[1,0]
	v_mov_b32_e32 v12, v11
	v_lshl_add_u64 v[4:5], v[0:1], 1, v[4:5]
	v_pk_mul_f32 v[10:11], v[12:13], v[2:3] op_sel_hi:[1,0]
	v_cvt_pk_bf16_f32 v0, v9, v11
	v_and_b32_sdwa v3, v8, v177 dst_sel:DWORD dst_unused:UNUSED_PAD src0_sel:WORD_1 src1_sel:DWORD
	v_add3_u32 v3, v8, v3, s28
	v_and_b32_sdwa v9, v10, v177 dst_sel:DWORD dst_unused:UNUSED_PAD src0_sel:WORD_1 src1_sel:DWORD
	s_mov_b64 s[6:7], 0x3200200
	v_add3_u32 v9, v10, v9, s28
	s_mov_b32 s2, 0x3200000
	v_lshl_add_u64 v[6:7], v[4:5], 0, s[6:7]
	v_and_b32_e32 v10, 0xffff0000, v9
	v_add_co_u32_e32 v4, vcc, s2, v4
	v_mov_b32_e32 v9, v0
	v_or_b32_sdwa v8, v10, v3 dst_sel:DWORD dst_unused:UNUSED_PAD src0_sel:DWORD src1_sel:WORD_1
	v_addc_co_u32_e32 v5, vcc, 0, v5, vcc
	global_store_dwordx2 v[4:5], v[8:9], off offset:512
	v_mov_b32_e32 v4, v22
	v_mov_b32_e32 v5, v24
	v_pk_mul_f32 v[4:5], v[4:5], v[2:3] op_sel_hi:[1,0]
	v_mov_b32_e32 v24, v23
	v_pk_mul_f32 v[8:9], v[24:25], v[2:3] op_sel_hi:[1,0]
	v_cvt_pk_bf16_f32 v0, v5, v9
	v_and_b32_sdwa v3, v4, v177 dst_sel:DWORD dst_unused:UNUSED_PAD src0_sel:WORD_1 src1_sel:DWORD
	v_add3_u32 v3, v4, v3, s28
	v_and_b32_sdwa v5, v8, v177 dst_sel:DWORD dst_unused:UNUSED_PAD src0_sel:WORD_1 src1_sel:DWORD
	v_add3_u32 v5, v8, v5, s28
	v_and_b32_e32 v8, 0xffff0000, v5
	v_mov_b32_e32 v5, v0
	v_or_b32_sdwa v4, v8, v3 dst_sel:DWORD dst_unused:UNUSED_PAD src0_sel:DWORD src1_sel:WORD_1
	global_store_dwordx2 v[6:7], v[4:5], off offset:32
	v_mov_b32_e32 v4, v26
	v_mov_b32_e32 v5, v28
	v_pk_mul_f32 v[4:5], v[4:5], v[2:3] op_sel_hi:[1,0]
	v_mov_b32_e32 v28, v27
	v_pk_mul_f32 v[8:9], v[28:29], v[2:3] op_sel_hi:[1,0]
	v_cvt_pk_bf16_f32 v0, v5, v9
	v_and_b32_sdwa v3, v4, v177 dst_sel:DWORD dst_unused:UNUSED_PAD src0_sel:WORD_1 src1_sel:DWORD
	v_add3_u32 v3, v4, v3, s28
	v_and_b32_sdwa v5, v8, v177 dst_sel:DWORD dst_unused:UNUSED_PAD src0_sel:WORD_1 src1_sel:DWORD
	v_add3_u32 v5, v8, v5, s28
	v_and_b32_e32 v8, 0xffff0000, v5
	v_mov_b32_e32 v5, v0
	v_or_b32_sdwa v4, v8, v3 dst_sel:DWORD dst_unused:UNUSED_PAD src0_sel:DWORD src1_sel:WORD_1
	global_store_dwordx2 v[6:7], v[4:5], off offset:64
	v_mov_b32_e32 v4, v30
	v_mov_b32_e32 v5, v32
	v_pk_mul_f32 v[4:5], v[4:5], v[2:3] op_sel_hi:[1,0]
	v_mov_b32_e32 v32, v31
	v_pk_mul_f32 v[2:3], v[32:33], v[2:3] op_sel_hi:[1,0]
	v_cvt_pk_bf16_f32 v0, v5, v3
	v_and_b32_sdwa v8, v4, v177 dst_sel:DWORD dst_unused:UNUSED_PAD src0_sel:WORD_1 src1_sel:DWORD
	v_add3_u32 v4, v4, v8, s28
	v_and_b32_sdwa v8, v2, v177 dst_sel:DWORD dst_unused:UNUSED_PAD src0_sel:WORD_1 src1_sel:DWORD
	v_add3_u32 v2, v2, v8, s28
	v_and_b32_e32 v2, 0xffff0000, v2
	v_readlane_b32 s90, v255, 10
	v_mov_b32_e32 v3, v0
	v_or_b32_sdwa v2, v2, v4 dst_sel:DWORD dst_unused:UNUSED_PAD src0_sel:DWORD src1_sel:WORD_1
	v_readlane_b32 s91, v255, 11
	global_store_dwordx2 v[6:7], v[2:3], off offset:96
	s_mov_b64 s[18:19], 0

.LBB0_1070:
	v_div_scale_f32 v0, s[14:15], v42, v42, 1.0
	v_rcp_f32_e32 v34, v0
	s_load_dwordx2 s[14:15], s[16:17], 0x90
	v_readlane_b32 s2, v255, 52
	s_or_b32 s4, s6, s2
	v_fma_f32 v35, -v0, v34, 1.0
	v_fmac_f32_e32 v34, v35, v34
	v_div_scale_f32 v35, vcc, 1.0, v42, 1.0
	s_lshl_b64 s[16:17], s[4:5], 2
	v_mul_f32_e32 v36, v35, v34
	s_waitcnt lgkmcnt(0)
	s_add_u32 s14, s14, s16
	v_fma_f32 v37, -v0, v36, v35
	s_addc_u32 s15, s15, s17
	v_fmac_f32_e32 v36, v37, v34
	s_add_u32 s16, s46, 0x900000
	v_fma_f32 v0, -v0, v36, v35
	s_addc_u32 s17, s47, 0
	v_div_fmas_f32 v0, v0, v34, v36
	global_load_dword v36, v1, s[14:15]
	s_and_b64 s[14:15], s[18:19], exec
	v_div_fixup_f32 v34, v0, v42, 1.0
	v_lshlrev_b32_e32 v0, 2, v38
	s_cselect_b32 s2, 11, 8
	v_or3_b32 v38, v0, v41, v40
	v_lshlrev_b32_e32 v0, s2, v39
	v_or_b32_e32 v0, s7, v0
	v_ashrrev_i32_e32 v39, 31, v38
	v_lshl_add_u64 v[40:41], v[0:1], 0, v[38:39]
	v_lshlrev_b64 v[40:41], 1, v[40:41]
	v_lshl_add_u64 v[44:45], s[16:17], 0, v[40:41]
	v_lshl_add_u64 v[42:43], s[46:47], 0, v[40:41]
	global_load_dwordx2 v[44:45], v[44:45], off
	s_nop 0
	global_load_dwordx2 v[46:47], v[42:43], off
	v_mov_b32_e32 v52, v18
	v_mov_b32_e32 v53, v20
	v_mov_b32_e32 v20, v19
	s_add_u32 s2, s50, s10
	s_addc_u32 s3, s51, 0
	s_add_u32 s18, s2, 0xde35800
	s_addc_u32 s19, s3, 0
	v_lshl_add_u64 v[40:41], s[18:19], 0, v[40:41]
	s_waitcnt vmcnt(1)
	v_lshlrev_b32_e32 v49, 16, v45
	s_waitcnt vmcnt(0)
	v_lshlrev_b32_e32 v51, 16, v47
	v_lshlrev_b32_e32 v50, 16, v46
	v_and_b32_e32 v47, 0xffff0000, v47
	v_and_b32_e32 v46, 0xffff0000, v46
	v_pk_mul_f32 v[18:19], v[36:37], v[46:47] op_sel_hi:[0,1]
	v_lshlrev_b32_e32 v48, 16, v44
	v_and_b32_e32 v45, 0xffff0000, v45
	v_and_b32_e32 v44, 0xffff0000, v44
	v_pk_mul_f32 v[50:51], v[36:37], v[50:51] op_sel_hi:[0,1]
	v_pk_fma_f32 v[18:19], v[34:35], v[20:21], v[18:19] op_sel_hi:[0,1,1]
	v_pk_fma_f32 v[50:51], v[34:35], v[52:53], v[50:51] op_sel_hi:[0,1,1]
	v_pk_mul_f32 v[18:19], v[18:19], v[44:45]
	v_pk_mul_f32 v[48:49], v[50:51], v[48:49]
	v_and_b32_sdwa v35, v19, v177 dst_sel:DWORD dst_unused:UNUSED_PAD src0_sel:WORD_1 src1_sel:DWORD
	v_and_b32_sdwa v37, v18, v177 dst_sel:DWORD dst_unused:UNUSED_PAD src0_sel:WORD_1 src1_sel:DWORD
	v_and_b32_sdwa v20, v49, v177 dst_sel:DWORD dst_unused:UNUSED_PAD src0_sel:WORD_1 src1_sel:DWORD
	v_and_b32_sdwa v21, v48, v177 dst_sel:DWORD dst_unused:UNUSED_PAD src0_sel:WORD_1 src1_sel:DWORD
	v_add3_u32 v19, v19, v35, s28
	v_add3_u32 v18, v18, v37, s28
	v_add3_u32 v21, v48, v21, s28
	v_add3_u32 v20, v49, v20, s28
	v_and_b32_e32 v19, 0xffff0000, v19
	v_and_b32_e32 v18, 0xffff0000, v18
	v_or_b32_sdwa v19, v19, v20 dst_sel:DWORD dst_unused:UNUSED_PAD src0_sel:DWORD src1_sel:WORD_1
	v_or_b32_sdwa v18, v18, v21 dst_sel:DWORD dst_unused:UNUSED_PAD src0_sel:DWORD src1_sel:WORD_1
	global_store_dwordx2 v[40:41], v[18:19], off
	v_or_b32_e32 v18, 8, v38
	v_ashrrev_i32_e32 v19, 31, v18
	v_lshl_add_u64 v[18:19], v[0:1], 0, v[18:19]
	v_lshl_add_u64 v[18:19], v[18:19], 1, s[16:17]
	global_load_dwordx2 v[18:19], v[18:19], off
	s_nop 0
	global_load_dwordx2 v[20:21], v[42:43], off offset:16
	v_mov_b32_e32 v49, v24
	v_mov_b32_e32 v24, v23
	v_mov_b32_e32 v48, v22
	s_waitcnt vmcnt(1)
	v_lshlrev_b32_e32 v45, 16, v19
	s_waitcnt vmcnt(0)
	v_lshlrev_b32_e32 v47, 16, v21
	v_lshlrev_b32_e32 v46, 16, v20
	v_and_b32_e32 v21, 0xffff0000, v21
	v_and_b32_e32 v20, 0xffff0000, v20
	v_pk_mul_f32 v[20:21], v[36:37], v[20:21] op_sel_hi:[0,1]
	v_lshlrev_b32_e32 v44, 16, v18
	v_and_b32_e32 v19, 0xffff0000, v19
	v_and_b32_e32 v18, 0xffff0000, v18
	v_pk_mul_f32 v[46:47], v[36:37], v[46:47] op_sel_hi:[0,1]
	v_pk_fma_f32 v[20:21], v[34:35], v[24:25], v[20:21] op_sel_hi:[0,1,1]
	v_pk_fma_f32 v[46:47], v[34:35], v[48:49], v[46:47] op_sel_hi:[0,1,1]
	v_pk_mul_f32 v[18:19], v[20:21], v[18:19]
	v_pk_mul_f32 v[44:45], v[46:47], v[44:45]
	v_cvt_pk_bf16_f32 v20, v45, v19
	v_cvt_pk_bf16_f32 v21, v44, v18
	v_mov_b32_e32 v19, v20
	v_mov_b32_e32 v18, v21
	global_store_dwordx2 v[40:41], v[18:19], off offset:16
	v_or_b32_e32 v18, 16, v38
	v_ashrrev_i32_e32 v19, 31, v18
	v_lshl_add_u64 v[18:19], v[0:1], 0, v[18:19]
	v_lshl_add_u64 v[18:19], v[18:19], 1, s[16:17]
	global_load_dwordx2 v[18:19], v[18:19], off
	s_nop 0
	global_load_dwordx2 v[20:21], v[42:43], off offset:32
	v_mov_b32_e32 v44, v26
	v_mov_b32_e32 v45, v28
	v_mov_b32_e32 v28, v27
	v_mov_b32_e32 v26, v30
	v_mov_b32_e32 v27, v32
	v_mov_b32_e32 v32, v31
	s_waitcnt vmcnt(1)
	v_lshlrev_b32_e32 v23, 16, v19
	s_waitcnt vmcnt(0)
	v_lshlrev_b32_e32 v25, 16, v21
	v_lshlrev_b32_e32 v24, 16, v20
	v_and_b32_e32 v21, 0xffff0000, v21
	v_and_b32_e32 v20, 0xffff0000, v20
	v_pk_mul_f32 v[24:25], v[36:37], v[24:25] op_sel_hi:[0,1]
	v_lshlrev_b32_e32 v22, 16, v18
	v_pk_fma_f32 v[24:25], v[34:35], v[44:45], v[24:25] op_sel_hi:[0,1,1]
	v_pk_mul_f32 v[20:21], v[36:37], v[20:21] op_sel_hi:[0,1]
	v_and_b32_e32 v19, 0xffff0000, v19
	v_and_b32_e32 v18, 0xffff0000, v18
	v_pk_mul_f32 v[22:23], v[24:25], v[22:23]
	v_pk_fma_f32 v[20:21], v[34:35], v[28:29], v[20:21] op_sel_hi:[0,1,1]
	v_pk_mul_f32 v[18:19], v[20:21], v[18:19]
	v_cvt_pk_bf16_f32 v20, v23, v19
	v_cvt_pk_bf16_f32 v21, v22, v18
	v_mov_b32_e32 v19, v20
	v_mov_b32_e32 v18, v21
	global_store_dwordx2 v[40:41], v[18:19], off offset:32
	v_or_b32_e32 v18, 24, v38
	v_ashrrev_i32_e32 v19, 31, v18
	v_lshl_add_u64 v[18:19], v[0:1], 0, v[18:19]
	v_lshl_add_u64 v[18:19], v[18:19], 1, s[16:17]
	global_load_dwordx2 v[18:19], v[18:19], off
	s_nop 0
	global_load_dwordx2 v[20:21], v[42:43], off offset:48
	s_waitcnt vmcnt(1)
	v_lshlrev_b32_e32 v23, 16, v19
	s_waitcnt vmcnt(0)
	v_lshlrev_b32_e32 v25, 16, v21
	v_lshlrev_b32_e32 v24, 16, v20
	v_and_b32_e32 v21, 0xffff0000, v21
	v_and_b32_e32 v20, 0xffff0000, v20
	v_pk_mul_f32 v[24:25], v[36:37], v[24:25] op_sel_hi:[0,1]
	v_lshlrev_b32_e32 v22, 16, v18
	v_pk_fma_f32 v[24:25], v[34:35], v[26:27], v[24:25] op_sel_hi:[0,1,1]
	v_pk_mul_f32 v[20:21], v[36:37], v[20:21] op_sel_hi:[0,1]
	v_and_b32_e32 v19, 0xffff0000, v19
	v_and_b32_e32 v18, 0xffff0000, v18
	v_pk_mul_f32 v[22:23], v[24:25], v[22:23]
	v_pk_fma_f32 v[20:21], v[34:35], v[32:33], v[20:21] op_sel_hi:[0,1,1]
	v_pk_mul_f32 v[18:19], v[20:21], v[18:19]
	v_cvt_pk_bf16_f32 v20, v23, v19
	v_cvt_pk_bf16_f32 v21, v22, v18
	v_mov_b32_e32 v19, v20
	v_mov_b32_e32 v18, v21
	global_store_dwordx2 v[40:41], v[18:19], off offset:48
	s_and_saveexec_b64 s[6:7], s[44:45]
	s_xor_b64 s[6:7], exec, s[6:7]
	s_cbranch_execz .LBB0_961
	v_add_u32_e32 v18, 0x400, v38
	v_ashrrev_i32_e32 v19, 31, v18
	v_lshl_add_u64 v[18:19], v[0:1], 0, v[18:19]
	v_lshlrev_b64 v[18:19], 1, v[18:19]
	v_lshl_add_u64 v[20:21], s[16:17], 0, v[18:19]
	v_lshl_add_u64 v[22:23], s[46:47], 0, v[18:19]
	global_load_dwordx2 v[20:21], v[20:21], off
	s_nop 0
	global_load_dwordx2 v[22:23], v[22:23], off
	v_mov_b32_e32 v37, v36
	v_mov_b32_e32 v35, v34
	v_mov_b32_e32 v28, v2
	v_mov_b32_e32 v29, v4
	v_mov_b32_e32 v4, v3
	v_lshl_add_u64 v[18:19], s[18:19], 0, v[18:19]
	s_waitcnt vmcnt(1)
	v_lshlrev_b32_e32 v25, 16, v21
	s_waitcnt vmcnt(0)
	v_lshlrev_b32_e32 v27, 16, v23
	v_lshlrev_b32_e32 v26, 16, v22
	v_and_b32_e32 v23, 0xffff0000, v23
	v_and_b32_e32 v22, 0xffff0000, v22
	v_pk_mul_f32 v[2:3], v[36:37], v[22:23]
	v_lshlrev_b32_e32 v24, 16, v20
	v_and_b32_e32 v21, 0xffff0000, v21
	v_and_b32_e32 v20, 0xffff0000, v20
	v_pk_mul_f32 v[26:27], v[36:37], v[26:27]
	v_pk_fma_f32 v[2:3], v[34:35], v[4:5], v[2:3]
	v_pk_fma_f32 v[26:27], v[34:35], v[28:29], v[26:27]
	v_pk_mul_f32 v[2:3], v[2:3], v[20:21]
	v_pk_mul_f32 v[24:25], v[26:27], v[24:25]
	v_cvt_pk_bf16_f32 v4, v25, v3
	v_cvt_pk_bf16_f32 v5, v24, v2
	v_mov_b32_e32 v3, v4
	v_mov_b32_e32 v2, v5
	global_store_dwordx2 v[18:19], v[2:3], off
	v_add_u32_e32 v2, 0x408, v38
	v_ashrrev_i32_e32 v3, 31, v2
	v_lshl_add_u64 v[2:3], v[0:1], 0, v[2:3]
	v_lshlrev_b64 v[2:3], 1, v[2:3]
	v_lshl_add_u64 v[4:5], s[16:17], 0, v[2:3]
	v_lshl_add_u64 v[18:19], s[46:47], 0, v[2:3]
	global_load_dwordx2 v[4:5], v[4:5], off
	s_nop 0
	global_load_dwordx2 v[18:19], v[18:19], off
	v_mov_b32_e32 v24, v6
	v_mov_b32_e32 v25, v8
	v_mov_b32_e32 v8, v7
	v_lshl_add_u64 v[2:3], s[18:19], 0, v[2:3]
	s_waitcnt vmcnt(1)
	v_lshlrev_b32_e32 v21, 16, v5
	s_waitcnt vmcnt(0)
	v_lshlrev_b32_e32 v23, 16, v19
	v_lshlrev_b32_e32 v22, 16, v18
	v_and_b32_e32 v19, 0xffff0000, v19
	v_and_b32_e32 v18, 0xffff0000, v18
	v_pk_mul_f32 v[6:7], v[36:37], v[18:19]
	v_lshlrev_b32_e32 v20, 16, v4
	v_and_b32_e32 v5, 0xffff0000, v5
	v_and_b32_e32 v4, 0xffff0000, v4
	v_pk_mul_f32 v[22:23], v[36:37], v[22:23]
	v_pk_fma_f32 v[6:7], v[34:35], v[8:9], v[6:7]
	v_pk_fma_f32 v[22:23], v[34:35], v[24:25], v[22:23]
	v_pk_mul_f32 v[4:5], v[6:7], v[4:5]
	v_pk_mul_f32 v[20:21], v[22:23], v[20:21]
	v_cvt_pk_bf16_f32 v6, v21, v5
	v_cvt_pk_bf16_f32 v7, v20, v4
	v_mov_b32_e32 v5, v6
	v_mov_b32_e32 v4, v7
	global_store_dwordx2 v[2:3], v[4:5], off
	v_add_u32_e32 v2, 0x410, v38
	v_ashrrev_i32_e32 v3, 31, v2
	v_lshl_add_u64 v[2:3], v[0:1], 0, v[2:3]
	v_lshlrev_b64 v[2:3], 1, v[2:3]
	v_lshl_add_u64 v[4:5], s[16:17], 0, v[2:3]
	v_lshl_add_u64 v[6:7], s[46:47], 0, v[2:3]
	global_load_dwordx2 v[4:5], v[4:5], off
	s_nop 0
	global_load_dwordx2 v[6:7], v[6:7], off
	v_mov_b32_e32 v20, v10
	v_mov_b32_e32 v21, v12
	v_mov_b32_e32 v12, v11
	v_lshl_add_u64 v[2:3], s[18:19], 0, v[2:3]
	s_waitcnt vmcnt(1)
	v_lshlrev_b32_e32 v9, 16, v5
	s_waitcnt vmcnt(0)
	v_lshlrev_b32_e32 v19, 16, v7
	v_lshlrev_b32_e32 v18, 16, v6
	v_and_b32_e32 v7, 0xffff0000, v7
	v_and_b32_e32 v6, 0xffff0000, v6
	v_pk_mul_f32 v[18:19], v[36:37], v[18:19]
	v_lshlrev_b32_e32 v8, 16, v4
	v_pk_fma_f32 v[18:19], v[34:35], v[20:21], v[18:19]
	v_pk_mul_f32 v[6:7], v[36:37], v[6:7]
	v_and_b32_e32 v5, 0xffff0000, v5
	v_and_b32_e32 v4, 0xffff0000, v4
	v_pk_mul_f32 v[8:9], v[18:19], v[8:9]
	v_pk_fma_f32 v[6:7], v[34:35], v[12:13], v[6:7]
	v_mov_b32_e32 v12, v14
	v_pk_mul_f32 v[4:5], v[6:7], v[4:5]
	v_cvt_pk_bf16_f32 v6, v9, v5
	v_cvt_pk_bf16_f32 v7, v8, v4
	v_mov_b32_e32 v5, v6
	v_mov_b32_e32 v4, v7
	global_store_dwordx2 v[2:3], v[4:5], off
	v_add_u32_e32 v2, 0x418, v38
	v_ashrrev_i32_e32 v3, 31, v2
	v_lshl_add_u64 v[2:3], v[0:1], 0, v[2:3]
	v_lshlrev_b64 v[2:3], 1, v[2:3]
	v_lshl_add_u64 v[4:5], s[16:17], 0, v[2:3]
	v_lshl_add_u64 v[6:7], s[46:47], 0, v[2:3]
	global_load_dwordx2 v[4:5], v[4:5], off
	s_nop 0
	global_load_dwordx2 v[6:7], v[6:7], off
	v_mov_b32_e32 v13, v16
	v_mov_b32_e32 v16, v15
	v_lshl_add_u64 v[2:3], s[18:19], 0, v[2:3]
	s_waitcnt vmcnt(1)
	v_lshlrev_b32_e32 v9, 16, v5
	s_waitcnt vmcnt(0)
	v_lshlrev_b32_e32 v11, 16, v7
	v_lshlrev_b32_e32 v10, 16, v6
	v_and_b32_e32 v7, 0xffff0000, v7
	v_and_b32_e32 v6, 0xffff0000, v6
	v_pk_mul_f32 v[10:11], v[36:37], v[10:11]
	v_lshlrev_b32_e32 v8, 16, v4
	v_pk_fma_f32 v[10:11], v[34:35], v[12:13], v[10:11]
	v_pk_mul_f32 v[6:7], v[36:37], v[6:7]
	v_and_b32_e32 v5, 0xffff0000, v5
	v_and_b32_e32 v4, 0xffff0000, v4
	v_pk_mul_f32 v[8:9], v[10:11], v[8:9]
	v_pk_fma_f32 v[6:7], v[34:35], v[16:17], v[6:7]
	v_and_b32_sdwa v0, v9, v177 dst_sel:DWORD dst_unused:UNUSED_PAD src0_sel:WORD_1 src1_sel:DWORD
	v_pk_mul_f32 v[4:5], v[6:7], v[4:5]
	v_cvt_pk_bf16_f32 v6, v8, v4
	v_and_b32_sdwa v7, v5, v177 dst_sel:DWORD dst_unused:UNUSED_PAD src0_sel:WORD_1 src1_sel:DWORD
	v_add3_u32 v5, v5, v7, s28
	v_add3_u32 v0, v9, v0, s28
	v_and_b32_e32 v5, 0xffff0000, v5
	v_or_b32_sdwa v5, v5, v0 dst_sel:DWORD dst_unused:UNUSED_PAD src0_sel:DWORD src1_sel:WORD_1
	v_mov_b32_e32 v4, v6
	global_store_dwordx2 v[2:3], v[4:5], off
	s_branch .LBB0_961

.LBB0_1195:
	s_or_b64 exec, exec, s[16:17]
	v_lshlrev_b64 v[76:77], 8, v[62:63]
	s_waitcnt vmcnt(3)
	v_and_b32_e32 v87, 0xffff0000, v89
	v_lshlrev_b32_e32 v86, 16, v89
	v_and_b32_e32 v97, 0xffff0000, v88
	v_lshlrev_b32_e32 v96, 16, v88
	v_and_b32_e32 v89, 0xffff0000, v75
	v_lshlrev_b32_e32 v88, 16, v75
	v_and_b32_e32 v105, 0xffff0000, v74
	v_lshlrev_b32_e32 v104, 16, v74
	v_lshlrev_b64 v[74:75], 1, v[76:77]
	v_lshl_add_u64 v[76:77], v[46:47], 0, v[74:75]
	v_lshl_add_u64 v[74:75], v[48:49], 0, v[74:75]
	global_load_dwordx2 v[76:77], v[76:77], off
	s_nop 0
	global_load_dwordx2 v[78:79], v[74:75], off
	v_lshlrev_b64 v[106:107], 10, v[62:63]
	v_and_b32_e32 v85, 0xffff0000, v91
	v_lshlrev_b32_e32 v84, 16, v91
	v_and_b32_e32 v95, 0xffff0000, v90
	v_lshlrev_b32_e32 v94, 16, v90
	v_and_b32_e32 v91, 0xffff0000, v71
	v_lshlrev_b32_e32 v90, 16, v71
	v_and_b32_e32 v101, 0xffff0000, v70
	v_lshlrev_b32_e32 v100, 16, v70
	s_waitcnt vmcnt(2)
	v_lshlrev_b32_e32 v70, 16, v108
	v_and_b32_e32 v63, 0xffff0000, v109
	v_and_b32_e32 v62, 0xffff0000, v108
	v_lshlrev_b32_e32 v71, 16, v109
	v_lshl_add_u64 v[106:107], v[106:107], 1, v[54:55]
	v_and_b32_e32 v99, 0xffff0000, v66
	v_lshlrev_b32_e32 v98, 16, v66
	v_lshlrev_b64 v[114:115], 2, v[50:51]
	v_pk_add_f32 v[96:97], v[96:97], v[98:99] neg_lo:[0,1] neg_hi:[0,1]
	v_pk_add_f32 v[94:95], v[94:95], v[98:99] neg_lo:[0,1] neg_hi:[0,1]
	v_pk_fma_f32 v[14:15], v[96:97], v[14:15], v[98:99]
	v_and_b32_e32 v103, 0xffff0000, v72
	v_pk_fma_f32 v[10:11], v[94:95], v[10:11], v[14:15]
	v_lshlrev_b32_e32 v102, 16, v72
	v_pk_add_f32 v[14:15], v[102:103], v[104:105] neg_lo:[0,1] neg_hi:[0,1]
	v_and_b32_e32 v83, 0xffff0000, v67
	v_pk_fma_f32 v[6:7], v[14:15], v[6:7], v[104:105]
	v_pk_add_f32 v[14:15], v[100:101], v[104:105] neg_lo:[0,1] neg_hi:[0,1]
	v_lshlrev_b32_e32 v82, 16, v67
	v_pk_fma_f32 v[2:3], v[14:15], v[2:3], v[6:7]
	v_and_b32_e32 v93, 0xffff0000, v73
	v_lshlrev_b32_e32 v92, 16, v73
	v_lshlrev_b32_e32 v73, 16, v69
	v_lshlrev_b32_e32 v72, 16, v68
	v_and_b32_e32 v67, 0xffff0000, v81
	v_and_b32_e32 v66, 0xffff0000, v80
	v_and_b32_e32 v69, 0xffff0000, v69
	v_and_b32_e32 v68, 0xffff0000, v68
	s_waitcnt vmcnt(1)
	v_lshlrev_b32_e32 v75, 16, v77
	v_lshlrev_b32_e32 v74, 16, v76
	s_waitcnt vmcnt(0)
	v_lshlrev_b32_e32 v109, 16, v79
	v_lshlrev_b32_e32 v108, 16, v78
	v_pk_add_f32 v[74:75], v[74:75], v[108:109]
	global_load_dwordx2 v[108:109], v[106:107], off offset:512
	s_nop 0
	global_load_dwordx2 v[106:107], v[106:107], off offset:1536
	s_load_dwordx8 s[44:51], s[52:53], 0x108
	v_and_b32_e32 v77, 0xffff0000, v77
	v_and_b32_e32 v76, 0xffff0000, v76
	v_and_b32_e32 v79, 0xffff0000, v79
	v_and_b32_e32 v78, 0xffff0000, v78
	s_waitcnt lgkmcnt(0)
	v_lshl_add_u64 v[116:117], s[44:45], 0, v[114:115]
	global_load_dwordx4 v[94:97], v[116:117], off
	v_lshl_add_u64 v[118:119], s[46:47], 0, v[114:115]
	global_load_dwordx4 v[98:101], v[118:119], off
	v_pk_add_f32 v[76:77], v[76:77], v[78:79]
	s_waitcnt vmcnt(3)
	v_lshlrev_b32_e32 v110, 16, v108
	v_add_f32_e32 v0, v74, v76
	v_add_f32_e32 v0, v0, v75
	v_add_f32_e32 v0, v77, v0
	v_and_b32_e32 v111, 0xffff0000, v108
	s_waitcnt vmcnt(2)
	v_lshlrev_b32_e32 v112, 16, v106
	v_and_b32_e32 v113, 0xffff0000, v106
	v_pk_add_f32 v[6:7], v[110:111], v[112:113]
	s_waitcnt lgkmcnt(0)
	s_nop 1
	v_add_f32_dpp v0, v0, v0 quad_perm:[1,0,3,2] row_mask:0xf bank_mask:0xf bound_ctrl:1
	v_pk_add_f32 v[6:7], v[6:7], -2.0 op_sel_hi:[1,0]
	v_lshlrev_b32_e32 v108, 16, v109
	s_waitcnt vmcnt(1)
	v_pk_fma_f32 v[6:7], v[6:7], v[94:95], 2.0 op_sel_hi:[1,1,0]
	v_and_b32_e32 v109, 0xffff0000, v109
	s_waitcnt lgkmcnt(0)
	s_nop 1
	v_add_f32_dpp v0, v0, v0 quad_perm:[2,3,0,1] row_mask:0xf bank_mask:0xf bound_ctrl:1
	v_pk_mul_f32 v[6:7], v[10:11], v[6:7]
	v_lshlrev_b32_e32 v106, 16, v107
	v_pk_mul_f32 v[2:3], v[2:3], v[6:7]
	v_pk_add_f32 v[6:7], v[84:85], v[82:83] neg_lo:[0,1] neg_hi:[0,1]
	s_waitcnt lgkmcnt(0)
	s_nop 1
	v_add_f32_dpp v0, v0, v0 row_half_mirror row_mask:0xf bank_mask:0xf bound_ctrl:1
	s_waitcnt vmcnt(0)
	v_pk_mul_f32 v[2:3], v[98:99], v[2:3]
	v_and_b32_e32 v107, 0xffff0000, v107
	s_waitcnt lgkmcnt(0)
	s_nop 1
	v_add_f32_dpp v0, v0, v0 row_mirror row_mask:0xf bank_mask:0xf bound_ctrl:1
	v_mul_f32_e32 v78, 0x3c800000, v0
	v_add_f32_e32 v0, 0, v2
	v_add_f32_e32 v0, v0, v3
	v_pk_add_f32 v[2:3], v[86:87], v[82:83] neg_lo:[0,1] neg_hi:[0,1]
	s_nop 0
	v_pk_fma_f32 v[2:3], v[2:3], v[16:17], v[82:83]
	global_load_dwordx4 v[14:17], v[44:45], off
	v_pk_fma_f32 v[2:3], v[6:7], v[12:13], v[2:3]
	v_pk_add_f32 v[6:7], v[92:93], v[88:89] neg_lo:[0,1] neg_hi:[0,1]
	s_nop 0
	v_pk_fma_f32 v[6:7], v[6:7], v[8:9], v[88:89]
	v_pk_add_f32 v[8:9], v[90:91], v[88:89] neg_lo:[0,1] neg_hi:[0,1]
	s_nop 0
	v_pk_fma_f32 v[4:5], v[8:9], v[4:5], v[6:7]
	global_load_dwordx4 v[8:11], v[36:37], off offset:2048
	v_pk_add_f32 v[6:7], v[108:109], v[106:107]
	s_waitcnt vmcnt(0)
	v_mov_b32_e32 v12, v8
	v_pk_add_f32 v[6:7], v[6:7], -2.0 op_sel_hi:[1,0]
	v_mov_b32_e32 v13, v10
	v_pk_fma_f32 v[6:7], v[6:7], v[96:97], 2.0 op_sel_hi:[1,1,0]
	v_mov_b32_e32 v10, v9
	v_pk_mul_f32 v[2:3], v[2:3], v[6:7]
	v_pk_add_f32 v[8:9], v[68:69], v[62:63] neg_lo:[0,1] neg_hi:[0,1]
	v_pk_mul_f32 v[2:3], v[4:5], v[2:3]
	v_lshlrev_b32_e32 v5, 16, v81
	v_lshlrev_b32_e32 v4, 16, v80
	v_pk_add_f32 v[4:5], v[4:5], v[70:71] neg_lo:[0,1] neg_hi:[0,1]
	v_pk_mul_f32 v[2:3], v[100:101], v[2:3]
	v_pk_fma_f32 v[4:5], v[4:5], v[12:13], v[70:71]
	v_pk_add_f32 v[12:13], v[72:73], v[70:71] neg_lo:[0,1] neg_hi:[0,1]
	v_mov_b32_e32 v70, v14
	v_mov_b32_e32 v71, v16
	v_pk_fma_f32 v[12:13], v[12:13], v[70:71], v[4:5]
	v_pk_add_f32 v[4:5], v[66:67], v[62:63] neg_lo:[0,1] neg_hi:[0,1]
	v_mov_b32_e32 v16, v15
	v_pk_fma_f32 v[4:5], v[4:5], v[10:11], v[62:63]
	v_pk_add_f32 v[14:15], v[76:77], v[78:79] op_sel_hi:[1,0] neg_lo:[0,1] neg_hi:[0,1]
	v_pk_fma_f32 v[10:11], v[8:9], v[16:17], v[4:5]
	v_pk_add_f32 v[4:5], v[74:75], v[78:79] op_sel_hi:[1,0] neg_lo:[0,1] neg_hi:[0,1]
	v_mov_b32_e32 v9, v14
	v_mov_b32_e32 v8, v4
	v_pk_mul_f32 v[8:9], v[8:9], v[8:9]
	v_mov_b32_e32 v16, v15
	v_mov_b32_e32 v17, v5
	v_pk_mul_f32 v[16:17], v[16:17], v[16:17]
	v_add_f32_e32 v8, v8, v9
	v_add_f32_e32 v8, v17, v8
	v_add_f32_e32 v8, v16, v8
	v_add_f32_e32 v0, v0, v2
	v_add_f32_e32 v0, v0, v3
	v_lshl_add_u64 v[6:7], s[50:51], 0, v[114:115]
	s_waitcnt lgkmcnt(0)
	s_nop 1
	v_add_f32_dpp v8, v8, v8 quad_perm:[1,0,3,2] row_mask:0xf bank_mask:0xf bound_ctrl:1
	s_waitcnt lgkmcnt(0)
	s_nop 1
	v_add_f32_dpp v0, v0, v0 quad_perm:[1,0,3,2] row_mask:0xf bank_mask:0xf bound_ctrl:1
	s_waitcnt lgkmcnt(0)
	s_nop 1
	v_add_f32_dpp v8, v8, v8 quad_perm:[2,3,0,1] row_mask:0xf bank_mask:0xf bound_ctrl:1
	s_waitcnt lgkmcnt(0)
	s_nop 1
	v_add_f32_dpp v0, v0, v0 quad_perm:[2,3,0,1] row_mask:0xf bank_mask:0xf bound_ctrl:1
	s_waitcnt lgkmcnt(0)
	s_nop 1
	v_add_f32_dpp v8, v8, v8 row_half_mirror row_mask:0xf bank_mask:0xf bound_ctrl:1
	s_waitcnt lgkmcnt(0)
	s_nop 1
	v_add_f32_dpp v0, v0, v0 row_half_mirror row_mask:0xf bank_mask:0xf bound_ctrl:1
	s_waitcnt lgkmcnt(0)
	s_nop 1
	v_add_f32_dpp v8, v8, v8 row_mirror row_mask:0xf bank_mask:0xf bound_ctrl:1
	v_fmamk_f32 v8, v8, 0x3c800000, v180
	v_cmp_gt_f32_e32 vcc, s27, v8
	v_mul_f32_e32 v9, 0x4b800000, v8
	s_waitcnt lgkmcnt(0)
	s_nop 1
	v_add_f32_dpp v0, v0, v0 row_mirror row_mask:0xf bank_mask:0xf bound_ctrl:1
	v_cndmask_b32_e32 v8, v8, v9, vcc
	v_rsq_f32_e32 v8, v8
	v_lshl_add_u64 v[2:3], s[48:49], 0, v[114:115]
	v_mul_f32_e32 v9, 0x45800000, v8
	v_cndmask_b32_e32 v16, v8, v9, vcc
	v_pk_mul_f32 v[62:63], v[4:5], v[16:17] op_sel_hi:[1,0]
	global_load_dwordx4 v[2:5], v[2:3], off
	v_pk_mul_f32 v[14:15], v[14:15], v[16:17] op_sel_hi:[1,0]
	global_load_dwordx4 v[6:9], v[6:7], off
	s_waitcnt vmcnt(1)
	v_mov_b32_e32 v67, v4
	v_mov_b32_e32 v4, v3
	s_waitcnt vmcnt(0)
	v_mov_b32_e32 v69, v8
	v_mov_b32_e32 v8, v7
	v_mov_b32_e32 v66, v2
	v_mov_b32_e32 v68, v6
	v_pk_fma_f32 v[2:3], v[14:15], v[4:5], v[8:9]
	v_pk_fma_f32 v[62:63], v[62:63], v[66:67], v[68:69]
	v_pk_fma_f32 v[2:3], v[10:11], v[0:1], v[2:3] op_sel_hi:[1,0,1]
	v_pk_fma_f32 v[12:13], v[12:13], v[0:1], v[62:63] op_sel_hi:[1,0,1]
	v_pk_mul_f32 v[2:3], v[58:59], v[2:3]
	v_pk_mul_f32 v[12:13], v[60:61], v[12:13]
	v_cvt_pk_bf16_f32 v0, v13, v3
	v_and_b32_sdwa v6, v2, v177 dst_sel:DWORD dst_unused:UNUSED_PAD src0_sel:WORD_1 src1_sel:DWORD
	v_and_b32_sdwa v4, v12, v177 dst_sel:DWORD dst_unused:UNUSED_PAD src0_sel:WORD_1 src1_sel:DWORD
	v_add3_u32 v2, v2, v6, s28
	v_add3_u32 v4, v12, v4, s28
	v_and_b32_e32 v2, 0xffff0000, v2
	v_mov_b32_e32 v3, v0
	v_or_b32_sdwa v2, v2, v4 dst_sel:DWORD dst_unused:UNUSED_PAD src0_sel:DWORD src1_sel:WORD_1
	global_store_dwordx2 v[64:65], v[2:3], off offset:1536

.LBB0_1224:
	s_or_b64 exec, exec, s[16:17]
	v_lshlrev_b64 v[90:91], 8, v[18:19]
	v_lshlrev_b64 v[90:91], 1, v[90:91]
	s_waitcnt vmcnt(3)
	v_and_b32_e32 v99, 0xffff0000, v93
	v_lshlrev_b32_e32 v98, 16, v93
	v_and_b32_e32 v115, 0xffff0000, v92
	v_lshlrev_b32_e32 v114, 16, v92
	v_lshl_add_u64 v[92:93], v[46:47], 0, v[90:91]
	v_and_b32_e32 v103, 0xffff0000, v95
	v_lshlrev_b32_e32 v102, 16, v95
	v_and_b32_e32 v113, 0xffff0000, v94
	v_lshlrev_b32_e32 v112, 16, v94
	v_lshl_add_u64 v[90:91], v[48:49], 0, v[90:91]
	global_load_dwordx2 v[92:93], v[92:93], off
	s_nop 0
	global_load_dwordx2 v[94:95], v[90:91], off
	v_lshlrev_b64 v[122:123], 10, v[18:19]
	v_and_b32_e32 v109, 0xffff0000, v85
	v_lshlrev_b32_e32 v108, 16, v85
	v_and_b32_e32 v119, 0xffff0000, v84
	v_lshlrev_b32_e32 v118, 16, v84
	s_waitcnt vmcnt(2)
	v_lshlrev_b32_e32 v89, 16, v125
	v_lshlrev_b32_e32 v88, 16, v124
	v_and_b32_e32 v85, 0xffff0000, v125
	v_and_b32_e32 v84, 0xffff0000, v124
	v_lshl_add_u64 v[122:123], v[122:123], 1, v[54:55]
	v_and_b32_e32 v111, 0xffff0000, v104
	v_lshlrev_b32_e32 v110, 16, v104
	v_lshlrev_b64 v[130:131], 2, v[50:51]
	v_pk_add_f32 v[112:113], v[112:113], v[114:115] neg_lo:[0,1] neg_hi:[0,1]
	v_pk_add_f32 v[110:111], v[110:111], v[114:115] neg_lo:[0,1] neg_hi:[0,1]
	v_pk_fma_f32 v[14:15], v[112:113], v[14:15], v[114:115]
	v_and_b32_e32 v121, 0xffff0000, v86
	v_pk_fma_f32 v[10:11], v[110:111], v[10:11], v[14:15]
	v_lshlrev_b32_e32 v120, 16, v86
	v_and_b32_e32 v117, 0xffff0000, v82
	v_lshlrev_b32_e32 v116, 16, v82
	v_pk_add_f32 v[14:15], v[118:119], v[120:121] neg_lo:[0,1] neg_hi:[0,1]
	v_and_b32_e32 v101, 0xffff0000, v105
	v_pk_fma_f32 v[6:7], v[14:15], v[6:7], v[120:121]
	v_pk_add_f32 v[14:15], v[116:117], v[120:121] neg_lo:[0,1] neg_hi:[0,1]
	v_lshlrev_b32_e32 v100, 16, v105
	v_and_b32_e32 v105, 0xffff0000, v87
	v_lshlrev_b32_e32 v104, 16, v87
	v_lshlrev_b32_e32 v86, 16, v126
	v_and_b32_e32 v81, 0xffff0000, v127
	v_and_b32_e32 v80, 0xffff0000, v126
	v_lshlrev_b32_e32 v87, 16, v127
	v_pk_fma_f32 v[2:3], v[14:15], v[2:3], v[6:7]
	v_and_b32_e32 v107, 0xffff0000, v83
	v_lshlrev_b32_e32 v106, 16, v83
	v_and_b32_e32 v83, 0xffff0000, v97
	v_and_b32_e32 v82, 0xffff0000, v96
	s_waitcnt vmcnt(1)
	v_lshlrev_b32_e32 v91, 16, v93
	v_lshlrev_b32_e32 v90, 16, v92
	s_waitcnt vmcnt(0)
	v_lshlrev_b32_e32 v125, 16, v95
	v_lshlrev_b32_e32 v124, 16, v94
	v_pk_add_f32 v[90:91], v[90:91], v[124:125]
	global_load_dwordx2 v[124:125], v[122:123], off offset:512
	s_nop 0
	global_load_dwordx2 v[122:123], v[122:123], off offset:1536
	s_load_dwordx8 s[44:51], s[52:53], 0x108
	v_and_b32_e32 v93, 0xffff0000, v93
	v_and_b32_e32 v92, 0xffff0000, v92
	v_and_b32_e32 v95, 0xffff0000, v95
	v_and_b32_e32 v94, 0xffff0000, v94
	s_waitcnt lgkmcnt(0)
	v_lshl_add_u64 v[132:133], s[44:45], 0, v[130:131]
	global_load_dwordx4 v[110:113], v[132:133], off
	v_lshl_add_u64 v[134:135], s[46:47], 0, v[130:131]
	global_load_dwordx4 v[114:117], v[134:135], off
	v_pk_add_f32 v[92:93], v[92:93], v[94:95]
	s_waitcnt vmcnt(3)
	v_lshlrev_b32_e32 v126, 16, v124
	v_add_f32_e32 v0, v90, v92
	v_add_f32_e32 v0, v0, v91
	v_add_f32_e32 v0, v93, v0
	v_and_b32_e32 v127, 0xffff0000, v124
	s_waitcnt vmcnt(2)
	v_lshlrev_b32_e32 v128, 16, v122
	v_and_b32_e32 v129, 0xffff0000, v122
	v_pk_add_f32 v[6:7], v[126:127], v[128:129]
	s_waitcnt lgkmcnt(0)
	s_nop 1
	v_add_f32_dpp v0, v0, v0 quad_perm:[1,0,3,2] row_mask:0xf bank_mask:0xf bound_ctrl:1
	v_pk_add_f32 v[6:7], v[6:7], -2.0 op_sel_hi:[1,0]
	v_lshlrev_b32_e32 v124, 16, v125
	s_waitcnt vmcnt(1)
	v_pk_fma_f32 v[6:7], v[6:7], v[110:111], 2.0 op_sel_hi:[1,1,0]
	v_and_b32_e32 v125, 0xffff0000, v125
	s_waitcnt lgkmcnt(0)
	s_nop 1
	v_add_f32_dpp v0, v0, v0 quad_perm:[2,3,0,1] row_mask:0xf bank_mask:0xf bound_ctrl:1
	v_pk_mul_f32 v[6:7], v[10:11], v[6:7]
	v_lshlrev_b32_e32 v122, 16, v123
	v_pk_mul_f32 v[2:3], v[2:3], v[6:7]
	v_pk_add_f32 v[6:7], v[100:101], v[98:99] neg_lo:[0,1] neg_hi:[0,1]
	s_waitcnt lgkmcnt(0)
	s_nop 1
	v_add_f32_dpp v0, v0, v0 row_half_mirror row_mask:0xf bank_mask:0xf bound_ctrl:1
	s_waitcnt vmcnt(0)
	v_pk_mul_f32 v[2:3], v[114:115], v[2:3]
	v_and_b32_e32 v123, 0xffff0000, v123
	s_waitcnt lgkmcnt(0)
	s_nop 1
	v_add_f32_dpp v0, v0, v0 row_mirror row_mask:0xf bank_mask:0xf bound_ctrl:1
	v_mul_f32_e32 v94, 0x3c800000, v0
	v_add_f32_e32 v0, 0, v2
	v_add_f32_e32 v0, v0, v3
	v_pk_add_f32 v[2:3], v[102:103], v[98:99] neg_lo:[0,1] neg_hi:[0,1]
	s_nop 0
	v_pk_fma_f32 v[2:3], v[2:3], v[16:17], v[98:99]
	global_load_dwordx4 v[14:17], v[44:45], off
	v_pk_fma_f32 v[2:3], v[6:7], v[12:13], v[2:3]
	v_pk_add_f32 v[6:7], v[108:109], v[104:105] neg_lo:[0,1] neg_hi:[0,1]
	s_nop 0
	v_pk_fma_f32 v[6:7], v[6:7], v[8:9], v[104:105]
	v_pk_add_f32 v[8:9], v[106:107], v[104:105] neg_lo:[0,1] neg_hi:[0,1]
	s_nop 0
	v_pk_fma_f32 v[4:5], v[8:9], v[4:5], v[6:7]
	global_load_dwordx4 v[8:11], v[36:37], off offset:2048
	v_pk_add_f32 v[6:7], v[124:125], v[122:123]
	s_waitcnt vmcnt(0)
	v_mov_b32_e32 v12, v8
	v_pk_add_f32 v[6:7], v[6:7], -2.0 op_sel_hi:[1,0]
	v_mov_b32_e32 v13, v10
	v_pk_fma_f32 v[6:7], v[6:7], v[112:113], 2.0 op_sel_hi:[1,1,0]
	v_mov_b32_e32 v10, v9
	v_pk_mul_f32 v[2:3], v[2:3], v[6:7]
	v_pk_add_f32 v[8:9], v[84:85], v[80:81] neg_lo:[0,1] neg_hi:[0,1]
	v_pk_mul_f32 v[2:3], v[4:5], v[2:3]
	v_lshlrev_b32_e32 v5, 16, v97
	v_lshlrev_b32_e32 v4, 16, v96
	v_pk_add_f32 v[4:5], v[4:5], v[86:87] neg_lo:[0,1] neg_hi:[0,1]
	v_pk_mul_f32 v[2:3], v[116:117], v[2:3]
	v_pk_fma_f32 v[4:5], v[4:5], v[12:13], v[86:87]
	v_pk_add_f32 v[12:13], v[88:89], v[86:87] neg_lo:[0,1] neg_hi:[0,1]
	v_mov_b32_e32 v86, v14
	v_mov_b32_e32 v87, v16
	v_pk_fma_f32 v[12:13], v[12:13], v[86:87], v[4:5]
	v_pk_add_f32 v[4:5], v[82:83], v[80:81] neg_lo:[0,1] neg_hi:[0,1]
	v_mov_b32_e32 v16, v15
	v_pk_fma_f32 v[4:5], v[4:5], v[10:11], v[80:81]
	v_pk_add_f32 v[14:15], v[92:93], v[94:95] op_sel_hi:[1,0] neg_lo:[0,1] neg_hi:[0,1]
	v_pk_fma_f32 v[10:11], v[8:9], v[16:17], v[4:5]
	v_pk_add_f32 v[4:5], v[90:91], v[94:95] op_sel_hi:[1,0] neg_lo:[0,1] neg_hi:[0,1]
	v_mov_b32_e32 v9, v14
	v_mov_b32_e32 v8, v4
	v_pk_mul_f32 v[8:9], v[8:9], v[8:9]
	v_mov_b32_e32 v16, v15
	v_mov_b32_e32 v17, v5
	v_pk_mul_f32 v[16:17], v[16:17], v[16:17]
	v_add_f32_e32 v8, v8, v9
	v_add_f32_e32 v8, v17, v8
	v_add_f32_e32 v8, v16, v8
	v_add_f32_e32 v0, v0, v2
	v_add_f32_e32 v0, v0, v3
	v_lshl_add_u64 v[6:7], s[50:51], 0, v[130:131]
	s_waitcnt lgkmcnt(0)
	s_nop 1
	v_add_f32_dpp v8, v8, v8 quad_perm:[1,0,3,2] row_mask:0xf bank_mask:0xf bound_ctrl:1
	s_waitcnt lgkmcnt(0)
	s_nop 1
	v_add_f32_dpp v0, v0, v0 quad_perm:[1,0,3,2] row_mask:0xf bank_mask:0xf bound_ctrl:1
	s_waitcnt lgkmcnt(0)
	s_nop 1
	v_add_f32_dpp v8, v8, v8 quad_perm:[2,3,0,1] row_mask:0xf bank_mask:0xf bound_ctrl:1
	s_waitcnt lgkmcnt(0)
	s_nop 1
	v_add_f32_dpp v0, v0, v0 quad_perm:[2,3,0,1] row_mask:0xf bank_mask:0xf bound_ctrl:1
	s_waitcnt lgkmcnt(0)
	s_nop 1
	v_add_f32_dpp v8, v8, v8 row_half_mirror row_mask:0xf bank_mask:0xf bound_ctrl:1
	s_waitcnt lgkmcnt(0)
	s_nop 1
	v_add_f32_dpp v0, v0, v0 row_half_mirror row_mask:0xf bank_mask:0xf bound_ctrl:1
	s_waitcnt lgkmcnt(0)
	s_nop 1
	v_add_f32_dpp v8, v8, v8 row_mirror row_mask:0xf bank_mask:0xf bound_ctrl:1
	v_fmamk_f32 v8, v8, 0x3c800000, v180
	v_cmp_gt_f32_e32 vcc, s27, v8
	v_mul_f32_e32 v9, 0x4b800000, v8
	s_waitcnt lgkmcnt(0)
	s_nop 1
	v_add_f32_dpp v0, v0, v0 row_mirror row_mask:0xf bank_mask:0xf bound_ctrl:1
	v_cndmask_b32_e32 v8, v8, v9, vcc
	v_rsq_f32_e32 v8, v8
	v_lshl_add_u64 v[2:3], s[48:49], 0, v[130:131]
	v_mul_f32_e32 v9, 0x45800000, v8
	v_cndmask_b32_e32 v16, v8, v9, vcc
	v_pk_mul_f32 v[80:81], v[4:5], v[16:17] op_sel_hi:[1,0]
	global_load_dwordx4 v[2:5], v[2:3], off
	v_pk_mul_f32 v[14:15], v[14:15], v[16:17] op_sel_hi:[1,0]
	global_load_dwordx4 v[6:9], v[6:7], off
	s_waitcnt vmcnt(1)
	v_mov_b32_e32 v83, v4
	v_mov_b32_e32 v4, v3
	s_waitcnt vmcnt(0)
	v_mov_b32_e32 v85, v8
	v_mov_b32_e32 v8, v7
	v_mov_b32_e32 v82, v2
	v_mov_b32_e32 v84, v6
	v_pk_fma_f32 v[2:3], v[14:15], v[4:5], v[8:9]
	v_pk_fma_f32 v[80:81], v[80:81], v[82:83], v[84:85]
	v_pk_fma_f32 v[2:3], v[10:11], v[0:1], v[2:3] op_sel_hi:[1,0,1]
	v_pk_fma_f32 v[12:13], v[12:13], v[0:1], v[80:81] op_sel_hi:[1,0,1]
	v_pk_mul_f32 v[2:3], v[74:75], v[2:3]
	v_pk_mul_f32 v[12:13], v[76:77], v[12:13]
	v_cvt_pk_bf16_f32 v0, v13, v3
	v_and_b32_sdwa v6, v2, v177 dst_sel:DWORD dst_unused:UNUSED_PAD src0_sel:WORD_1 src1_sel:DWORD
	v_and_b32_sdwa v4, v12, v177 dst_sel:DWORD dst_unused:UNUSED_PAD src0_sel:WORD_1 src1_sel:DWORD
	v_add3_u32 v2, v2, v6, s28
	v_add3_u32 v4, v12, v4, s28
	v_and_b32_e32 v2, 0xffff0000, v2
	v_mov_b32_e32 v3, v0
	v_or_b32_sdwa v2, v2, v4 dst_sel:DWORD dst_unused:UNUSED_PAD src0_sel:DWORD src1_sel:WORD_1
	global_store_dwordx2 v[78:79], v[2:3], off offset:1536
	s_or_b64 exec, exec, s[14:15]
	v_cmp_gt_i32_e32 vcc, s11, v64
	s_and_saveexec_b64 s[14:15], vcc
	s_cbranch_execnz .LBB0_1227

.LBB0_1239:
	s_or_b64 exec, exec, s[16:17]
	v_lshlrev_b64 v[86:87], 8, v[64:65]
	v_lshlrev_b64 v[86:87], 1, v[86:87]
	s_waitcnt vmcnt(3)
	v_and_b32_e32 v95, 0xffff0000, v89
	v_lshlrev_b32_e32 v94, 16, v89
	v_and_b32_e32 v111, 0xffff0000, v88
	v_lshlrev_b32_e32 v110, 16, v88
	v_lshl_add_u64 v[88:89], v[46:47], 0, v[86:87]
	v_and_b32_e32 v99, 0xffff0000, v91
	v_lshlrev_b32_e32 v98, 16, v91
	v_and_b32_e32 v109, 0xffff0000, v90
	v_lshlrev_b32_e32 v108, 16, v90
	v_lshl_add_u64 v[86:87], v[48:49], 0, v[86:87]
	global_load_dwordx2 v[88:89], v[88:89], off
	s_nop 0
	global_load_dwordx2 v[90:91], v[86:87], off
	v_lshlrev_b64 v[118:119], 10, v[64:65]
	v_and_b32_e32 v105, 0xffff0000, v81
	v_lshlrev_b32_e32 v104, 16, v81
	v_and_b32_e32 v115, 0xffff0000, v80
	v_lshlrev_b32_e32 v114, 16, v80
	s_waitcnt vmcnt(2)
	v_lshlrev_b32_e32 v85, 16, v121
	v_lshlrev_b32_e32 v84, 16, v120
	v_and_b32_e32 v81, 0xffff0000, v121
	v_and_b32_e32 v80, 0xffff0000, v120
	v_lshl_add_u64 v[118:119], v[118:119], 1, v[54:55]
	v_and_b32_e32 v107, 0xffff0000, v100
	v_lshlrev_b32_e32 v106, 16, v100
	v_lshlrev_b64 v[126:127], 2, v[50:51]
	v_pk_add_f32 v[108:109], v[108:109], v[110:111] neg_lo:[0,1] neg_hi:[0,1]
	v_pk_add_f32 v[106:107], v[106:107], v[110:111] neg_lo:[0,1] neg_hi:[0,1]
	v_pk_fma_f32 v[14:15], v[108:109], v[14:15], v[110:111]
	v_and_b32_e32 v117, 0xffff0000, v82
	v_pk_fma_f32 v[10:11], v[106:107], v[10:11], v[14:15]
	v_lshlrev_b32_e32 v116, 16, v82
	v_and_b32_e32 v113, 0xffff0000, v78
	v_lshlrev_b32_e32 v112, 16, v78
	v_pk_add_f32 v[14:15], v[114:115], v[116:117] neg_lo:[0,1] neg_hi:[0,1]
	v_and_b32_e32 v97, 0xffff0000, v101
	v_pk_fma_f32 v[6:7], v[14:15], v[6:7], v[116:117]
	v_pk_add_f32 v[14:15], v[112:113], v[116:117] neg_lo:[0,1] neg_hi:[0,1]
	v_lshlrev_b32_e32 v96, 16, v101
	v_and_b32_e32 v101, 0xffff0000, v83
	v_lshlrev_b32_e32 v100, 16, v83
	v_lshlrev_b32_e32 v82, 16, v122
	v_and_b32_e32 v77, 0xffff0000, v123
	v_and_b32_e32 v76, 0xffff0000, v122
	v_lshlrev_b32_e32 v83, 16, v123
	v_pk_fma_f32 v[2:3], v[14:15], v[2:3], v[6:7]
	v_and_b32_e32 v103, 0xffff0000, v79
	v_lshlrev_b32_e32 v102, 16, v79
	v_and_b32_e32 v79, 0xffff0000, v93
	v_and_b32_e32 v78, 0xffff0000, v92
	s_waitcnt vmcnt(1)
	v_lshlrev_b32_e32 v87, 16, v89
	v_lshlrev_b32_e32 v86, 16, v88
	s_waitcnt vmcnt(0)
	v_lshlrev_b32_e32 v121, 16, v91
	v_lshlrev_b32_e32 v120, 16, v90
	v_pk_add_f32 v[86:87], v[86:87], v[120:121]
	global_load_dwordx2 v[120:121], v[118:119], off offset:512
	s_nop 0
	global_load_dwordx2 v[118:119], v[118:119], off offset:1536
	s_load_dwordx8 s[44:51], s[52:53], 0x108
	v_and_b32_e32 v89, 0xffff0000, v89
	v_and_b32_e32 v88, 0xffff0000, v88
	v_and_b32_e32 v91, 0xffff0000, v91
	v_and_b32_e32 v90, 0xffff0000, v90
	s_waitcnt lgkmcnt(0)
	v_lshl_add_u64 v[128:129], s[44:45], 0, v[126:127]
	global_load_dwordx4 v[106:109], v[128:129], off
	v_lshl_add_u64 v[130:131], s[46:47], 0, v[126:127]
	global_load_dwordx4 v[110:113], v[130:131], off
	v_pk_add_f32 v[88:89], v[88:89], v[90:91]
	s_waitcnt vmcnt(3)
	v_lshlrev_b32_e32 v122, 16, v120
	v_add_f32_e32 v0, v86, v88
	v_add_f32_e32 v0, v0, v87
	v_add_f32_e32 v0, v89, v0
	v_and_b32_e32 v123, 0xffff0000, v120
	s_waitcnt vmcnt(2)
	v_lshlrev_b32_e32 v124, 16, v118
	v_and_b32_e32 v125, 0xffff0000, v118
	v_pk_add_f32 v[6:7], v[122:123], v[124:125]
	s_waitcnt lgkmcnt(0)
	s_nop 1
	v_add_f32_dpp v0, v0, v0 quad_perm:[1,0,3,2] row_mask:0xf bank_mask:0xf bound_ctrl:1
	v_pk_add_f32 v[6:7], v[6:7], -2.0 op_sel_hi:[1,0]
	v_lshlrev_b32_e32 v120, 16, v121
	s_waitcnt vmcnt(1)
	v_pk_fma_f32 v[6:7], v[6:7], v[106:107], 2.0 op_sel_hi:[1,1,0]
	v_and_b32_e32 v121, 0xffff0000, v121
	s_waitcnt lgkmcnt(0)
	s_nop 1
	v_add_f32_dpp v0, v0, v0 quad_perm:[2,3,0,1] row_mask:0xf bank_mask:0xf bound_ctrl:1
	v_pk_mul_f32 v[6:7], v[10:11], v[6:7]
	v_lshlrev_b32_e32 v118, 16, v119
	v_pk_mul_f32 v[2:3], v[2:3], v[6:7]
	v_pk_add_f32 v[6:7], v[96:97], v[94:95] neg_lo:[0,1] neg_hi:[0,1]
	s_waitcnt lgkmcnt(0)
	s_nop 1
	v_add_f32_dpp v0, v0, v0 row_half_mirror row_mask:0xf bank_mask:0xf bound_ctrl:1
	s_waitcnt vmcnt(0)
	v_pk_mul_f32 v[2:3], v[110:111], v[2:3]
	v_and_b32_e32 v119, 0xffff0000, v119
	s_waitcnt lgkmcnt(0)
	s_nop 1
	v_add_f32_dpp v0, v0, v0 row_mirror row_mask:0xf bank_mask:0xf bound_ctrl:1
	v_mul_f32_e32 v90, 0x3c800000, v0
	v_add_f32_e32 v0, 0, v2
	v_add_f32_e32 v0, v0, v3
	v_pk_add_f32 v[2:3], v[98:99], v[94:95] neg_lo:[0,1] neg_hi:[0,1]
	s_nop 0
	v_pk_fma_f32 v[2:3], v[2:3], v[16:17], v[94:95]
	global_load_dwordx4 v[14:17], v[44:45], off
	v_pk_fma_f32 v[2:3], v[6:7], v[12:13], v[2:3]
	v_pk_add_f32 v[6:7], v[104:105], v[100:101] neg_lo:[0,1] neg_hi:[0,1]
	s_nop 0
	v_pk_fma_f32 v[6:7], v[6:7], v[8:9], v[100:101]
	v_pk_add_f32 v[8:9], v[102:103], v[100:101] neg_lo:[0,1] neg_hi:[0,1]
	s_nop 0
	v_pk_fma_f32 v[4:5], v[8:9], v[4:5], v[6:7]
	global_load_dwordx4 v[8:11], v[36:37], off offset:2048
	v_pk_add_f32 v[6:7], v[120:121], v[118:119]
	s_waitcnt vmcnt(0)
	v_mov_b32_e32 v12, v8
	v_pk_add_f32 v[6:7], v[6:7], -2.0 op_sel_hi:[1,0]
	v_mov_b32_e32 v13, v10
	v_pk_fma_f32 v[6:7], v[6:7], v[108:109], 2.0 op_sel_hi:[1,1,0]
	v_mov_b32_e32 v10, v9
	v_pk_mul_f32 v[2:3], v[2:3], v[6:7]
	v_pk_add_f32 v[8:9], v[80:81], v[76:77] neg_lo:[0,1] neg_hi:[0,1]
	v_pk_mul_f32 v[2:3], v[4:5], v[2:3]
	v_lshlrev_b32_e32 v5, 16, v93
	v_lshlrev_b32_e32 v4, 16, v92
	v_pk_add_f32 v[4:5], v[4:5], v[82:83] neg_lo:[0,1] neg_hi:[0,1]
	v_pk_mul_f32 v[2:3], v[112:113], v[2:3]
	v_pk_fma_f32 v[4:5], v[4:5], v[12:13], v[82:83]
	v_pk_add_f32 v[12:13], v[84:85], v[82:83] neg_lo:[0,1] neg_hi:[0,1]
	v_mov_b32_e32 v82, v14
	v_mov_b32_e32 v83, v16
	v_pk_fma_f32 v[12:13], v[12:13], v[82:83], v[4:5]
	v_pk_add_f32 v[4:5], v[78:79], v[76:77] neg_lo:[0,1] neg_hi:[0,1]
	v_mov_b32_e32 v16, v15
	v_pk_fma_f32 v[4:5], v[4:5], v[10:11], v[76:77]
	v_pk_add_f32 v[14:15], v[88:89], v[90:91] op_sel_hi:[1,0] neg_lo:[0,1] neg_hi:[0,1]
	v_pk_fma_f32 v[10:11], v[8:9], v[16:17], v[4:5]
	v_pk_add_f32 v[4:5], v[86:87], v[90:91] op_sel_hi:[1,0] neg_lo:[0,1] neg_hi:[0,1]
	v_mov_b32_e32 v9, v14
	v_mov_b32_e32 v8, v4
	v_pk_mul_f32 v[8:9], v[8:9], v[8:9]
	v_mov_b32_e32 v16, v15
	v_mov_b32_e32 v17, v5
	v_pk_mul_f32 v[16:17], v[16:17], v[16:17]
	v_add_f32_e32 v8, v8, v9
	v_add_f32_e32 v8, v17, v8
	v_add_f32_e32 v8, v16, v8
	v_add_f32_e32 v0, v0, v2
	v_add_f32_e32 v0, v0, v3
	v_lshl_add_u64 v[6:7], s[50:51], 0, v[126:127]
	s_waitcnt lgkmcnt(0)
	s_nop 1
	v_add_f32_dpp v8, v8, v8 quad_perm:[1,0,3,2] row_mask:0xf bank_mask:0xf bound_ctrl:1
	s_waitcnt lgkmcnt(0)
	s_nop 1
	v_add_f32_dpp v0, v0, v0 quad_perm:[1,0,3,2] row_mask:0xf bank_mask:0xf bound_ctrl:1
	s_waitcnt lgkmcnt(0)
	s_nop 1
	v_add_f32_dpp v8, v8, v8 quad_perm:[2,3,0,1] row_mask:0xf bank_mask:0xf bound_ctrl:1
	s_waitcnt lgkmcnt(0)
	s_nop 1
	v_add_f32_dpp v0, v0, v0 quad_perm:[2,3,0,1] row_mask:0xf bank_mask:0xf bound_ctrl:1
	s_waitcnt lgkmcnt(0)
	s_nop 1
	v_add_f32_dpp v8, v8, v8 row_half_mirror row_mask:0xf bank_mask:0xf bound_ctrl:1
	s_waitcnt lgkmcnt(0)
	s_nop 1
	v_add_f32_dpp v0, v0, v0 row_half_mirror row_mask:0xf bank_mask:0xf bound_ctrl:1
	s_waitcnt lgkmcnt(0)
	s_nop 1
	v_add_f32_dpp v8, v8, v8 row_mirror row_mask:0xf bank_mask:0xf bound_ctrl:1
	v_fmamk_f32 v8, v8, 0x3c800000, v180
	v_cmp_gt_f32_e32 vcc, s27, v8
	v_mul_f32_e32 v9, 0x4b800000, v8
	s_waitcnt lgkmcnt(0)
	s_nop 1
	v_add_f32_dpp v0, v0, v0 row_mirror row_mask:0xf bank_mask:0xf bound_ctrl:1
	v_cndmask_b32_e32 v8, v8, v9, vcc
	v_rsq_f32_e32 v8, v8
	v_lshl_add_u64 v[2:3], s[48:49], 0, v[126:127]
	v_mul_f32_e32 v9, 0x45800000, v8
	v_cndmask_b32_e32 v16, v8, v9, vcc
	v_pk_mul_f32 v[76:77], v[4:5], v[16:17] op_sel_hi:[1,0]
	global_load_dwordx4 v[2:5], v[2:3], off
	v_pk_mul_f32 v[14:15], v[14:15], v[16:17] op_sel_hi:[1,0]
	global_load_dwordx4 v[6:9], v[6:7], off
	s_waitcnt vmcnt(1)
	v_mov_b32_e32 v79, v4
	v_mov_b32_e32 v4, v3
	s_waitcnt vmcnt(0)
	v_mov_b32_e32 v81, v8
	v_mov_b32_e32 v8, v7
	v_mov_b32_e32 v78, v2
	v_mov_b32_e32 v80, v6
	v_pk_fma_f32 v[2:3], v[14:15], v[4:5], v[8:9]
	v_pk_fma_f32 v[76:77], v[76:77], v[78:79], v[80:81]
	v_pk_fma_f32 v[2:3], v[10:11], v[0:1], v[2:3] op_sel_hi:[1,0,1]
	v_pk_fma_f32 v[12:13], v[12:13], v[0:1], v[76:77] op_sel_hi:[1,0,1]
	v_pk_mul_f32 v[2:3], v[68:69], v[2:3]
	v_pk_mul_f32 v[12:13], v[70:71], v[12:13]
	v_cvt_pk_bf16_f32 v0, v13, v3
	v_and_b32_sdwa v6, v2, v177 dst_sel:DWORD dst_unused:UNUSED_PAD src0_sel:WORD_1 src1_sel:DWORD
	v_and_b32_sdwa v4, v12, v177 dst_sel:DWORD dst_unused:UNUSED_PAD src0_sel:WORD_1 src1_sel:DWORD
	v_add3_u32 v2, v2, v6, s28
	v_add3_u32 v4, v12, v4, s28
	v_and_b32_e32 v2, 0xffff0000, v2
	v_mov_b32_e32 v3, v0
	v_or_b32_sdwa v2, v2, v4 dst_sel:DWORD dst_unused:UNUSED_PAD src0_sel:DWORD src1_sel:WORD_1
	global_store_dwordx2 v[74:75], v[2:3], off offset:1536
	s_or_b64 exec, exec, s[14:15]
	v_cmp_gt_i32_e32 vcc, s11, v62
	s_and_saveexec_b64 s[14:15], vcc
	s_cbranch_execz .LBB0_1196

.LBB0_1379:
	s_or_b64 exec, exec, s[46:47]
	v_lshl_add_u64 v[2:3], v[2:3], 0, v[0:1]
	global_load_dwordx4 v[36:39], v[2:3], off
	global_load_dwordx4 v[40:43], v[2:3], off offset:1024
	global_load_dwordx4 v[44:47], v[2:3], off offset:2048
	s_nop 0
	global_load_dwordx4 v[2:5], v[2:3], off offset:3072
	s_nop 0
	global_load_dwordx4 v[48:51], v[8:9], off
	global_load_dwordx4 v[78:81], v[10:11], off
	global_load_dwordx4 v[90:93], v[12:13], off
	global_load_dwordx4 v[102:105], v[14:15], off
	v_min_i32_e32 v19, 0x4000, v6
	v_ashrrev_i32_e32 v19, 11, v19
	v_mul_hi_i32_i24_e32 v25, 0x9000, v19
	v_mul_i32_i24_e32 v24, 0x9000, v19
	v_lshl_add_u64 v[24:25], s[16:17], 0, v[24:25]
	v_lshl_add_u64 v[26:27], v[24:25], 0, s[38:39]
	v_lshl_add_u64 v[28:29], v[26:27], 0, v[0:1]
	global_load_dwordx4 v[52:55], v[28:29], off
	global_load_dwordx4 v[82:85], v[28:29], off offset:1024
	global_load_dwordx4 v[94:97], v[28:29], off offset:2048
	global_load_dwordx4 v[106:109], v[28:29], off offset:3072
	v_lshl_add_u64 v[28:29], v[24:25], 0, v[0:1]
	global_load_dwordx4 v[56:59], v[28:29], off
	global_load_dwordx4 v[86:89], v[28:29], off offset:1024
	global_load_dwordx4 v[98:101], v[28:29], off offset:2048
	global_load_dwordx4 v[110:113], v[28:29], off offset:3072
	s_mov_b32 s2, s42
	s_waitcnt vmcnt(15)
	v_mov_b32_e32 v60, v37
	s_waitcnt vmcnt(14)
	v_mov_b32_e32 v61, v41
	v_mov_b32_e32 v24, v36
	v_mov_b32_e32 v25, v40
	s_waitcnt vmcnt(13)
	v_mov_b32_e32 v68, v45
	s_waitcnt vmcnt(12)
	v_mov_b32_e32 v69, v3
	v_pk_mul_f32 v[60:61], v[60:61], v[60:61]
	v_mov_b32_e32 v62, v38
	v_mov_b32_e32 v63, v42
	v_mov_b32_e32 v66, v44
	v_mov_b32_e32 v67, v2
	v_pk_mul_f32 v[68:69], v[68:69], v[68:69]
	v_pk_fma_f32 v[24:25], v[24:25], v[24:25], v[60:61]
	v_mov_b32_e32 v64, v39
	v_mov_b32_e32 v65, v43
	v_mov_b32_e32 v70, v46
	v_mov_b32_e32 v71, v4
	v_pk_fma_f32 v[60:61], v[66:67], v[66:67], v[68:69]
	v_pk_fma_f32 v[24:25], v[62:63], v[62:63], v[24:25]
	v_mov_b32_e32 v72, v47
	v_mov_b32_e32 v73, v5
	v_pk_fma_f32 v[60:61], v[70:71], v[70:71], v[60:61]
	v_pk_fma_f32 v[24:25], v[64:65], v[64:65], v[24:25]
	v_pk_fma_f32 v[60:61], v[72:73], v[72:73], v[60:61]
	v_add_f32_e32 v19, v24, v25
	v_add_f32_e32 v19, v19, v60
	v_add_f32_e32 v19, v19, v61
	ds_bpermute_b32 v21, v30, v19
	v_lshlrev_b64 v[24:25], 11, v[6:7]
	s_waitcnt vmcnt(11)
	v_mov_b32_e32 v60, v48
	v_mov_b32_e32 v48, v36
	v_mov_b32_e32 v36, v37
	s_waitcnt lgkmcnt(0)
	v_add_f32_e32 v19, v19, v21
	ds_bpermute_b32 v21, v31, v19
	v_mov_b32_e32 v37, v39
	s_waitcnt vmcnt(3)
	v_mov_b32_e32 v62, v56
	v_mov_b32_e32 v61, v50
	v_mov_b32_e32 v50, v49
	s_waitcnt lgkmcnt(0)
	v_add_f32_e32 v21, v19, v21
	ds_bpermute_b32 v23, v32, v21
	v_mov_b32_e32 v49, v38
	v_mov_b32_e32 v39, v54
	v_mov_b32_e32 v54, v53
	v_mov_b32_e32 v38, v52
	s_waitcnt lgkmcnt(0)
	v_add_f32_e32 v7, v21, v23
	ds_bpermute_b32 v21, v33, v7
	v_mov_b32_e32 v63, v58
	v_mov_b32_e32 v58, v57
	v_pk_add_f32 v[52:53], v[54:55], 1.0 op_sel_hi:[1,0]
	v_pk_add_f32 v[38:39], v[38:39], 1.0 op_sel_hi:[1,0]
	s_waitcnt lgkmcnt(0)
	v_add_f32_e32 v7, v7, v21
	ds_bpermute_b32 v21, v34, v7
	v_lshl_add_u64 v[24:25], v[16:17], 0, v[24:25]
	v_mov_b32_e32 v19, v1
	s_waitcnt lgkmcnt(0)
	v_add_f32_e32 v7, v7, v21
	ds_bpermute_b32 v21, v35, v7
	s_waitcnt lgkmcnt(0)
	v_add_f32_e32 v7, v7, v21
	v_fmamk_f32 v7, v7, 0x3a800000, v174
	v_mul_f32_e32 v21, 0x4b800000, v7
	v_cmp_gt_f32_e32 vcc, s27, v7
	s_nop 1
	v_cndmask_b32_e32 v7, v7, v21, vcc
	v_rsq_f32_e32 v7, v7
	s_nop 0
	v_mul_f32_e32 v21, 0x45800000, v7
	v_cndmask_b32_e32 v56, v7, v21, vcc
	v_pk_mul_f32 v[36:37], v[36:37], v[56:57] op_sel_hi:[1,0]
	v_pk_mul_f32 v[48:49], v[48:49], v[56:57] op_sel_hi:[1,0]
	v_pk_mul_f32 v[36:37], v[50:51], v[36:37]
	v_pk_mul_f32 v[48:49], v[60:61], v[48:49]
	v_pk_fma_f32 v[36:37], v[52:53], v[36:37], v[58:59]
	v_pk_fma_f32 v[38:39], v[38:39], v[48:49], v[62:63]
	v_cvt_pk_bf16_f32 v21, v38, v36
	v_cvt_pk_bf16_f32 v37, v39, v37
	v_mov_b32_e32 v36, v21
	global_store_dwordx2 v[24:25], v[36:37], off
	v_lshl_add_u64 v[48:49], v[26:27], 0, v[18:19]
	s_waitcnt vmcnt(1)
	v_mov_b32_e32 v52, v86
	v_mov_b32_e32 v53, v87
	v_mov_b32_e32 v54, v88
	v_mov_b32_e32 v55, v89
	v_mov_b32_e32 v48, v82
	v_mov_b32_e32 v49, v83
	v_mov_b32_e32 v50, v84
	v_mov_b32_e32 v51, v85
	v_mov_b32_e32 v36, v78
	v_mov_b32_e32 v37, v79
	v_mov_b32_e32 v38, v80
	v_mov_b32_e32 v39, v81
	v_mov_b32_e32 v58, v40
	v_mov_b32_e32 v59, v42
	v_mov_b32_e32 v42, v41
	v_pk_mul_f32 v[40:41], v[58:59], v[56:57] op_sel_hi:[1,0]
	v_pk_mul_f32 v[42:43], v[42:43], v[56:57] op_sel_hi:[1,0]
	v_mov_b32_e32 v21, v1
	v_mov_b32_e32 v58, v36
	v_mov_b32_e32 v59, v38
	v_mov_b32_e32 v60, v48
	v_mov_b32_e32 v61, v50
	v_mov_b32_e32 v38, v37
	v_mov_b32_e32 v50, v49
	v_mov_b32_e32 v62, v52
	v_mov_b32_e32 v63, v54
	v_mov_b32_e32 v54, v53
	v_pk_mul_f32 v[36:37], v[40:41], v[58:59]
	v_pk_add_f32 v[40:41], v[60:61], 1.0 op_sel_hi:[1,0]
	v_pk_mul_f32 v[38:39], v[42:43], v[38:39]
	v_pk_add_f32 v[42:43], v[50:51], 1.0 op_sel_hi:[1,0]
	v_pk_fma_f32 v[36:37], v[36:37], v[40:41], v[62:63]
	v_pk_fma_f32 v[38:39], v[38:39], v[42:43], v[54:55]
	v_cvt_pk_bf16_f32 v19, v36, v38
	v_cvt_pk_bf16_f32 v37, v37, v39
	v_mov_b32_e32 v36, v19
	global_store_dwordx2 v[24:25], v[36:37], off offset:512
	v_lshl_add_u64 v[40:41], v[26:27], 0, v[20:21]
	v_mov_b32_e32 v48, v98
	v_mov_b32_e32 v49, v99
	v_mov_b32_e32 v50, v100
	v_mov_b32_e32 v51, v101
	v_mov_b32_e32 v40, v94
	v_mov_b32_e32 v41, v95
	v_mov_b32_e32 v42, v96
	v_mov_b32_e32 v43, v97
	v_mov_b32_e32 v36, v90
	v_mov_b32_e32 v37, v91
	v_mov_b32_e32 v38, v92
	v_mov_b32_e32 v39, v93
	v_mov_b32_e32 v52, v44
	v_mov_b32_e32 v53, v46
	v_mov_b32_e32 v44, v45
	v_mov_b32_e32 v45, v47
	v_pk_mul_f32 v[46:47], v[52:53], v[56:57] op_sel_hi:[1,0]
	v_pk_mul_f32 v[44:45], v[44:45], v[56:57] op_sel_hi:[1,0]
	v_mov_b32_e32 v23, v1
	v_lshl_add_u64 v[26:27], v[26:27], 0, v[22:23]
	v_mov_b32_e32 v52, v36
	v_mov_b32_e32 v53, v38
	v_mov_b32_e32 v54, v40
	v_mov_b32_e32 v55, v42
	v_mov_b32_e32 v38, v37
	v_mov_b32_e32 v42, v41
	v_mov_b32_e32 v58, v48
	v_mov_b32_e32 v59, v50
	v_mov_b32_e32 v50, v49
	v_pk_mul_f32 v[36:37], v[46:47], v[52:53]
	v_pk_add_f32 v[40:41], v[54:55], 1.0 op_sel_hi:[1,0]
	v_pk_mul_f32 v[38:39], v[44:45], v[38:39]
	v_pk_add_f32 v[42:43], v[42:43], 1.0 op_sel_hi:[1,0]
	v_pk_fma_f32 v[36:37], v[36:37], v[40:41], v[58:59]
	v_pk_fma_f32 v[38:39], v[38:39], v[42:43], v[50:51]
	v_cvt_pk_bf16_f32 v19, v36, v38
	v_cvt_pk_bf16_f32 v37, v37, v39
	v_mov_b32_e32 v36, v19
	global_store_dwordx2 v[24:25], v[36:37], off offset:1024
	v_mov_b32_e32 v26, v110
	v_mov_b32_e32 v27, v111
	v_mov_b32_e32 v28, v112
	v_mov_b32_e32 v29, v113
	v_mov_b32_e32 v40, v106
	v_mov_b32_e32 v41, v107
	v_mov_b32_e32 v42, v108
	v_mov_b32_e32 v43, v109
	v_mov_b32_e32 v36, v102
	v_mov_b32_e32 v37, v103
	v_mov_b32_e32 v38, v104
	v_mov_b32_e32 v39, v105
	v_mov_b32_e32 v44, v2
	v_mov_b32_e32 v45, v4
	v_mov_b32_e32 v4, v3
	v_pk_mul_f32 v[2:3], v[44:45], v[56:57] op_sel_hi:[1,0]
	v_pk_mul_f32 v[4:5], v[4:5], v[56:57] op_sel_hi:[1,0]
	v_mov_b32_e32 v47, v42
	v_mov_b32_e32 v45, v38
	v_mov_b32_e32 v38, v37
	v_mov_b32_e32 v42, v41
	v_mov_b32_e32 v44, v36
	v_mov_b32_e32 v46, v40
	v_mov_b32_e32 v49, v28
	v_mov_b32_e32 v28, v27
	v_pk_mul_f32 v[4:5], v[4:5], v[38:39]
	v_pk_add_f32 v[36:37], v[42:43], 1.0 op_sel_hi:[1,0]
	v_mov_b32_e32 v48, v26
	v_pk_mul_f32 v[2:3], v[2:3], v[44:45]
	v_pk_add_f32 v[26:27], v[46:47], 1.0 op_sel_hi:[1,0]
	v_pk_fma_f32 v[4:5], v[4:5], v[36:37], v[28:29]
	v_pk_fma_f32 v[2:3], v[2:3], v[26:27], v[48:49]
	v_cvt_pk_bf16_f32 v3, v3, v5
	v_and_b32_sdwa v23, v4, v177 dst_sel:DWORD dst_unused:UNUSED_PAD src0_sel:WORD_1 src1_sel:DWORD
	v_and_b32_sdwa v19, v2, v177 dst_sel:DWORD dst_unused:UNUSED_PAD src0_sel:WORD_1 src1_sel:DWORD
	v_add3_u32 v4, v4, v23, s28
	v_add3_u32 v2, v2, v19, s28
	v_and_b32_e32 v4, 0xffff0000, v4
	v_or_b32_sdwa v2, v4, v2 dst_sel:DWORD dst_unused:UNUSED_PAD src0_sel:DWORD src1_sel:WORD_1
	global_store_dwordx2 v[24:25], v[2:3], off offset:1536
	s_nop 0
	v_lshl_add_u32 v6, s2, 3, v6
	v_cmp_le_i32_e32 vcc, s11, v6
	s_or_b64 s[18:19], vcc, s[18:19]
	s_andn2_b64 exec, exec, s[18:19]
	s_cbranch_execz .LBB0_1384

.LBB0_1455:
	s_add_i32 s2, s16, 4
	s_min_u32 s2, s2, 15
	s_lshl_b32 s4, s2, 7
	v_lshl_add_u64 v[98:99], v[110:111], 0, s[4:5]
	v_add_co_u32_e32 v94, vcc, s34, v98
	v_lshl_add_u64 v[132:133], v[112:113], 0, s[4:5]
	s_nop 0
	v_addc_co_u32_e32 v95, vcc, 0, v99, vcc
	v_add_co_u32_e32 v100, vcc, s35, v98
	global_load_dwordx4 v[90:93], v[98:99], off
	s_nop 0
	v_addc_co_u32_e32 v101, vcc, 0, v99, vcc
	v_add_co_u32_e32 v102, vcc, s36, v98
	global_load_dwordx4 v[94:97], v[94:95], off
	s_nop 0
	v_addc_co_u32_e32 v103, vcc, 0, v99, vcc
	v_add_co_u32_e32 v136, vcc, s34, v132
	global_load_dwordx4 v[98:101], v[100:101], off
	s_nop 0
	v_addc_co_u32_e32 v137, vcc, 0, v133, vcc
	global_load_dwordx4 v[102:105], v[102:103], off
	v_add_u32_e32 v131, v117, v120
	global_load_dwordx4 v[132:135], v[132:133], off
	ds_read_b128 v[140:143], v121
	global_load_dwordx4 v[136:139], v[136:137], off
	ds_read_b128 v[144:147], v121 offset:2304
	ds_read_b128 v[148:151], v121 offset:4608
	ds_read_b128 v[152:155], v121 offset:6912
	ds_read_b128 v[156:159], v131 offset:36864
	ds_read_b128 v[160:163], v131 offset:39168
	ds_read_b128 v[164:167], v131 offset:41472
	ds_read_b128 v[168:171], v131 offset:43776
	s_add_i32 s16, s16, 2
	s_waitcnt lgkmcnt(3)
	v_mfma_f32_16x16x32_bf16 v[82:85], v[156:159], v[140:143], v[82:85]
	s_waitcnt lgkmcnt(2)
	v_mfma_f32_16x16x32_bf16 v[86:89], v[160:163], v[140:143], v[86:89]
	ds_read_b128 v[184:187], v121 offset:64
	s_waitcnt lgkmcnt(2)
	v_mfma_f32_16x16x32_bf16 v[74:77], v[164:167], v[140:143], v[74:77]
	s_waitcnt lgkmcnt(1)
	v_mfma_f32_16x16x32_bf16 v[78:81], v[168:171], v[140:143], v[78:81]
	ds_read_b128 v[140:143], v121 offset:2368
	v_mfma_f32_16x16x32_bf16 v[66:69], v[156:159], v[144:147], v[66:69]
	v_mfma_f32_16x16x32_bf16 v[70:73], v[160:163], v[144:147], v[70:73]
	ds_read_b128 v[198:201], v121 offset:4672
	v_mfma_f32_16x16x32_bf16 v[34:37], v[164:167], v[144:147], v[34:37]
	v_mfma_f32_16x16x32_bf16 v[38:41], v[168:171], v[144:147], v[38:41]
	ds_read_b128 v[144:147], v121 offset:6976
	v_mfma_f32_16x16x32_bf16 v[26:29], v[156:159], v[148:151], v[26:29]
	v_mfma_f32_16x16x32_bf16 v[30:33], v[160:163], v[148:151], v[30:33]
	ds_read_b128 v[204:207], v131 offset:36928
	v_mfma_f32_16x16x32_bf16 v[18:21], v[164:167], v[148:151], v[18:21]
	v_mfma_f32_16x16x32_bf16 v[22:25], v[168:171], v[148:151], v[22:25]
	ds_read_b128 v[148:151], v131 offset:39232
	v_mfma_f32_16x16x32_bf16 v[10:13], v[156:159], v[152:155], v[10:13]
	v_mfma_f32_16x16x32_bf16 v[14:17], v[160:163], v[152:155], v[14:17]
	ds_read_b128 v[156:159], v131 offset:41536
	v_mfma_f32_16x16x32_bf16 v[2:5], v[164:167], v[152:155], v[2:5]
	v_mfma_f32_16x16x32_bf16 v[6:9], v[168:171], v[152:155], v[6:9]
	ds_read_b128 v[152:155], v131 offset:43840
	s_waitcnt lgkmcnt(3)
	v_mfma_f32_16x16x32_bf16 v[82:85], v[204:207], v[184:187], v[82:85]
	s_waitcnt lgkmcnt(2)
	v_mfma_f32_16x16x32_bf16 v[86:89], v[148:151], v[184:187], v[86:89]
	s_waitcnt vmcnt(11)
	ds_write_b128 v130, v[42:45] offset:55296
	s_waitcnt lgkmcnt(2)
	v_mfma_f32_16x16x32_bf16 v[74:77], v[156:159], v[184:187], v[74:77]
	s_waitcnt lgkmcnt(1)
	v_mfma_f32_16x16x32_bf16 v[78:81], v[152:155], v[184:187], v[78:81]
	s_waitcnt vmcnt(9)
	ds_write_b128 v130, v[46:49] offset:64512
	v_mfma_f32_16x16x32_bf16 v[66:69], v[204:207], v[140:143], v[66:69]
	v_mfma_f32_16x16x32_bf16 v[70:73], v[148:151], v[140:143], v[70:73]
	s_waitcnt vmcnt(8)
	ds_write_b128 v122, v[50:53] offset:55296
	v_mfma_f32_16x16x32_bf16 v[34:37], v[156:159], v[140:143], v[34:37]
	v_mfma_f32_16x16x32_bf16 v[38:41], v[152:155], v[140:143], v[38:41]
	s_waitcnt vmcnt(7)
	ds_write_b128 v123, v[54:57] offset:55296
	v_mfma_f32_16x16x32_bf16 v[26:29], v[204:207], v[198:201], v[26:29]
	v_mfma_f32_16x16x32_bf16 v[30:33], v[148:151], v[198:201], v[30:33]
	ds_write_b128 v124, v[58:61]
	v_mfma_f32_16x16x32_bf16 v[18:21], v[156:159], v[198:201], v[18:21]
	v_mfma_f32_16x16x32_bf16 v[22:25], v[152:155], v[198:201], v[22:25]
	s_waitcnt vmcnt(6)
	ds_write_b128 v124, v[62:65] offset:9216
	v_mfma_f32_16x16x32_bf16 v[10:13], v[204:207], v[144:147], v[10:13]
	v_mfma_f32_16x16x32_bf16 v[14:17], v[148:151], v[144:147], v[14:17]
	v_mfma_f32_16x16x32_bf16 v[2:5], v[156:159], v[144:147], v[2:5]
	v_mfma_f32_16x16x32_bf16 v[6:9], v[152:155], v[144:147], v[6:9]
	s_min_u32 s2, s16, 12
	s_lshl_b32 s4, s2, 7
	v_lshl_add_u64 v[50:51], v[110:111], 0, s[4:5]
	v_add_co_u32_e32 v46, vcc, s34, v50
	v_lshl_add_u64 v[58:59], v[112:113], 0, s[4:5]
	s_nop 0
	v_addc_co_u32_e32 v47, vcc, 0, v51, vcc
	v_add_co_u32_e32 v52, vcc, s35, v50
	s_waitcnt lgkmcnt(0)
	s_barrier
	global_load_dwordx4 v[42:45], v[50:51], off offset:384
	s_nop 0
	v_addc_co_u32_e32 v53, vcc, 0, v51, vcc
	v_add_co_u32_e32 v54, vcc, s36, v50
	global_load_dwordx4 v[46:49], v[46:47], off offset:384
	s_nop 0
	v_addc_co_u32_e32 v55, vcc, 0, v51, vcc
	v_add_co_u32_e32 v62, vcc, s34, v58
	global_load_dwordx4 v[50:53], v[52:53], off offset:384
	s_nop 0
	v_addc_co_u32_e32 v63, vcc, 0, v59, vcc
	global_load_dwordx4 v[54:57], v[54:55], off offset:384
	ds_read_b128 v[140:143], v121 offset:55296
	global_load_dwordx4 v[58:61], v[58:59], off offset:384
	ds_read_b128 v[144:147], v121 offset:57600
	global_load_dwordx4 v[62:65], v[62:63], off offset:384
	ds_read_b128 v[148:151], v121 offset:59904
	ds_read_b128 v[152:155], v121 offset:62208
	ds_read_b128 v[156:159], v125
	ds_read_b128 v[160:163], v125 offset:2304
	ds_read_b128 v[164:167], v125 offset:4608
	ds_read_b128 v[168:171], v125 offset:6912
	s_waitcnt lgkmcnt(3)
	v_mfma_f32_16x16x32_bf16 v[82:85], v[156:159], v[140:143], v[82:85]
	s_waitcnt lgkmcnt(2)
	v_mfma_f32_16x16x32_bf16 v[86:89], v[160:163], v[140:143], v[86:89]
	ds_read_b128 v[184:187], v121 offset:55360
	s_waitcnt lgkmcnt(2)
	v_mfma_f32_16x16x32_bf16 v[74:77], v[164:167], v[140:143], v[74:77]
	s_waitcnt lgkmcnt(1)
	v_mfma_f32_16x16x32_bf16 v[78:81], v[168:171], v[140:143], v[78:81]
	ds_read_b128 v[140:143], v121 offset:57664
	v_mfma_f32_16x16x32_bf16 v[66:69], v[156:159], v[144:147], v[66:69]
	v_mfma_f32_16x16x32_bf16 v[70:73], v[160:163], v[144:147], v[70:73]
	ds_read_b128 v[198:201], v121 offset:59968
	v_mfma_f32_16x16x32_bf16 v[34:37], v[164:167], v[144:147], v[34:37]
	v_mfma_f32_16x16x32_bf16 v[38:41], v[168:171], v[144:147], v[38:41]
	ds_read_b128 v[144:147], v121 offset:62272
	v_mfma_f32_16x16x32_bf16 v[26:29], v[156:159], v[148:151], v[26:29]
	v_mfma_f32_16x16x32_bf16 v[30:33], v[160:163], v[148:151], v[30:33]
	ds_read_b128 v[204:207], v126 offset:64
	v_mfma_f32_16x16x32_bf16 v[18:21], v[164:167], v[148:151], v[18:21]
	v_mfma_f32_16x16x32_bf16 v[22:25], v[168:171], v[148:151], v[22:25]
	ds_read_b128 v[148:151], v127 offset:64
	v_mfma_f32_16x16x32_bf16 v[10:13], v[156:159], v[152:155], v[10:13]
	v_mfma_f32_16x16x32_bf16 v[14:17], v[160:163], v[152:155], v[14:17]
	ds_read_b128 v[156:159], v128 offset:64
	v_mfma_f32_16x16x32_bf16 v[2:5], v[164:167], v[152:155], v[2:5]
	v_mfma_f32_16x16x32_bf16 v[6:9], v[168:171], v[152:155], v[6:9]
	ds_read_b128 v[152:155], v129 offset:64
	s_waitcnt lgkmcnt(3)
	v_mfma_f32_16x16x32_bf16 v[82:85], v[204:207], v[184:187], v[82:85]
	s_waitcnt lgkmcnt(2)
	v_mfma_f32_16x16x32_bf16 v[86:89], v[148:151], v[184:187], v[86:89]
	s_waitcnt vmcnt(11)
	ds_write_b128 v130, v[90:93]
	s_waitcnt lgkmcnt(2)
	v_mfma_f32_16x16x32_bf16 v[74:77], v[156:159], v[184:187], v[74:77]
	s_waitcnt lgkmcnt(1)
	v_mfma_f32_16x16x32_bf16 v[78:81], v[152:155], v[184:187], v[78:81]
	s_waitcnt vmcnt(10)
	ds_write_b128 v130, v[94:97] offset:9216
	v_mfma_f32_16x16x32_bf16 v[66:69], v[204:207], v[140:143], v[66:69]
	v_mfma_f32_16x16x32_bf16 v[70:73], v[148:151], v[140:143], v[70:73]
	s_waitcnt vmcnt(9)
	ds_write_b128 v130, v[98:101] offset:18432
	v_mfma_f32_16x16x32_bf16 v[34:37], v[156:159], v[140:143], v[34:37]
	v_mfma_f32_16x16x32_bf16 v[38:41], v[152:155], v[140:143], v[38:41]
	s_waitcnt vmcnt(8)
	ds_write_b128 v130, v[102:105] offset:27648
	v_mfma_f32_16x16x32_bf16 v[26:29], v[204:207], v[198:201], v[26:29]
	v_mfma_f32_16x16x32_bf16 v[30:33], v[148:151], v[198:201], v[30:33]
	s_waitcnt vmcnt(7)
	ds_write_b128 v130, v[132:135] offset:36864
	v_mfma_f32_16x16x32_bf16 v[18:21], v[156:159], v[198:201], v[18:21]
	v_mfma_f32_16x16x32_bf16 v[22:25], v[152:155], v[198:201], v[22:25]
	s_waitcnt vmcnt(6)
	ds_write_b128 v130, v[136:139] offset:46080
	v_mfma_f32_16x16x32_bf16 v[10:13], v[204:207], v[144:147], v[10:13]
	v_mfma_f32_16x16x32_bf16 v[14:17], v[148:151], v[144:147], v[14:17]
	v_mfma_f32_16x16x32_bf16 v[2:5], v[156:159], v[144:147], v[2:5]
	v_mfma_f32_16x16x32_bf16 v[6:9], v[152:155], v[144:147], v[6:9]
	s_waitcnt lgkmcnt(0)
	s_barrier
	s_cmp_gt_u32 s16, 13
	s_cbranch_scc0 .LBB0_1455
	s_waitcnt vmcnt(5)
	v_mul_f32_e32 v45, 0xbfb8aa3b, v82
	v_exp_f32_e32 v45, v45
	s_waitcnt vmcnt(4)
	v_mul_f32_e32 v46, 0xbfb8aa3b, v83
	v_exp_f32_e32 v49, v46
	s_waitcnt vmcnt(3)
	v_mul_f32_e32 v50, 0xbfb8aa3b, v85
	v_add_f32_e32 v45, 1.0, v45
	v_rcp_f32_e32 v48, v45
	v_add_f32_e32 v45, 1.0, v49
	v_mul_f32_e32 v49, 0xbfb8aa3b, v84
	v_exp_f32_e32 v49, v49
	v_exp_f32_e32 v51, v50
	v_rcp_f32_e32 v50, v45
	v_mov_b32_e32 v52, v82
	v_add_f32_e32 v45, 1.0, v49
	v_rcp_f32_e32 v49, v45
	v_add_f32_e32 v45, 1.0, v51
	v_rcp_f32_e32 v51, v45
	v_mov_b32_e32 v53, v84
	v_pk_mul_f32 v[48:49], v[52:53], v[48:49]
	v_mov_b32_e32 v52, v86
	v_mov_b32_e32 v53, v88
	v_mov_b32_e32 v84, v83
	v_pk_mul_f32 v[48:49], v[52:53], v[48:49]
	v_pk_mul_f32 v[50:51], v[84:85], v[50:51]
	v_mov_b32_e32 v88, v87
	v_pk_mul_f32 v[50:51], v[88:89], v[50:51]
	v_cvt_pk_bf16_f32 v48, v48, v50
	v_cvt_pk_bf16_f32 v49, v49, v51
	v_or_b32_e32 v42, s7, v114
	v_ashrrev_i32_e32 v42, 1, v42
	v_mul_f32_e32 v50, 0xbfb8aa3b, v74
	v_or_b32_e32 v44, v42, v118
	v_exp_f32_e32 v50, v50
	v_mul_f32_e32 v51, 0xbfb8aa3b, v75
	s_waitcnt vmcnt(2)
	v_add_u32_e32 v54, s6, v116
	v_mov_b64_e32 v[42:43], s[12:13]
	v_ashrrev_i32_e32 v45, 31, v44
	v_exp_f32_e32 v51, v51
	v_mad_i64_i32 v[46:47], s[6:7], v54, s52, v[42:43]
	v_lshlrev_b64 v[44:45], 1, v[44:45]
	v_lshl_add_u64 v[46:47], v[46:47], 0, v[44:45]
	s_waitcnt vmcnt(0)
	global_store_dwordx2 v[46:47], v[48:49], off
	v_add_f32_e32 v48, 1.0, v50
	v_mul_f32_e32 v50, 0xbfb8aa3b, v76
	v_add_f32_e32 v49, 1.0, v51
	v_exp_f32_e32 v51, v50
	v_mul_f32_e32 v50, 0xbfb8aa3b, v77
	v_exp_f32_e32 v52, v50
	v_rcp_f32_e32 v50, v49
	v_add_f32_e32 v49, 1.0, v51
	v_rcp_f32_e32 v48, v48
	v_rcp_f32_e32 v49, v49
	v_add_f32_e32 v51, 1.0, v52
	v_rcp_f32_e32 v51, v51
	v_mov_b32_e32 v52, v74
	v_mov_b32_e32 v53, v76
	v_pk_mul_f32 v[48:49], v[52:53], v[48:49]
	v_mov_b32_e32 v52, v78
	v_mov_b32_e32 v53, v80
	v_mov_b32_e32 v76, v75
	v_pk_mul_f32 v[48:49], v[52:53], v[48:49]
	v_pk_mul_f32 v[50:51], v[76:77], v[50:51]
	v_mov_b32_e32 v80, v79
	v_pk_mul_f32 v[50:51], v[80:81], v[50:51]
	v_cvt_pk_bf16_f32 v49, v49, v51
	v_cvt_pk_bf16_f32 v48, v48, v50
	global_store_dwordx2 v[46:47], v[48:49], off offset:32
	v_mul_f32_e32 v47, 0xbfb8aa3b, v66
	v_exp_f32_e32 v48, v47
	v_mul_f32_e32 v47, 0xbfb8aa3b, v67
	v_exp_f32_e32 v49, v47
	v_mul_f32_e32 v50, 0xbfb8aa3b, v68
	v_exp_f32_e32 v51, v50
	v_mul_f32_e32 v50, 0xbfb8aa3b, v69
	v_exp_f32_e32 v52, v50
	v_add_f32_e32 v49, 1.0, v49
	v_add_f32_e32 v48, 1.0, v48
	v_rcp_f32_e32 v50, v49
	v_add_f32_e32 v49, 1.0, v51
	v_rcp_f32_e32 v48, v48
	v_rcp_f32_e32 v49, v49
	v_add_f32_e32 v51, 1.0, v52
	v_rcp_f32_e32 v51, v51
	v_mov_b32_e32 v52, v66
	v_mov_b32_e32 v53, v68
	v_pk_mul_f32 v[48:49], v[52:53], v[48:49]
	v_mov_b32_e32 v52, v70
	v_mov_b32_e32 v53, v72
	v_mov_b32_e32 v68, v67
	v_pk_mul_f32 v[48:49], v[52:53], v[48:49]
	v_pk_mul_f32 v[50:51], v[68:69], v[50:51]
	v_mov_b32_e32 v72, v71
	v_pk_mul_f32 v[50:51], v[72:73], v[50:51]
	v_cvt_pk_bf16_f32 v48, v48, v50
	v_cvt_pk_bf16_f32 v49, v49, v51
	v_mul_f32_e32 v50, 0xbfb8aa3b, v34
	v_exp_f32_e32 v50, v50
	v_mul_f32_e32 v51, 0xbfb8aa3b, v35
	v_or_b32_e32 v46, 16, v54
	v_exp_f32_e32 v51, v51
	v_mad_i64_i32 v[46:47], s[6:7], v46, s52, v[42:43]
	v_lshl_add_u64 v[46:47], v[46:47], 0, v[44:45]
	global_store_dwordx2 v[46:47], v[48:49], off
	v_add_f32_e32 v48, 1.0, v50
	v_mul_f32_e32 v50, 0xbfb8aa3b, v36
	v_add_f32_e32 v49, 1.0, v51
	v_exp_f32_e32 v51, v50
	v_mul_f32_e32 v50, 0xbfb8aa3b, v37
	v_exp_f32_e32 v52, v50
	v_rcp_f32_e32 v50, v49
	v_add_f32_e32 v49, 1.0, v51
	v_rcp_f32_e32 v48, v48
	v_add_f32_e32 v51, 1.0, v52
	v_rcp_f32_e32 v49, v49
	v_rcp_f32_e32 v51, v51
	v_mov_b32_e32 v52, v34
	v_mov_b32_e32 v53, v36
	v_mov_b32_e32 v36, v35
	v_pk_mul_f32 v[48:49], v[52:53], v[48:49]
	v_mov_b32_e32 v53, v40
	v_pk_mul_f32 v[34:35], v[36:37], v[50:51]
	v_mov_b32_e32 v40, v39
	v_mov_b32_e32 v52, v38
	v_pk_mul_f32 v[34:35], v[40:41], v[34:35]
	v_pk_mul_f32 v[48:49], v[52:53], v[48:49]
	v_cvt_pk_bf16_f32 v36, v49, v35
	v_cvt_pk_bf16_f32 v37, v48, v34
	v_mov_b32_e32 v35, v36
	v_mov_b32_e32 v34, v37
	global_store_dwordx2 v[46:47], v[34:35], off offset:32
	v_mul_f32_e32 v35, 0xbfb8aa3b, v26
	v_exp_f32_e32 v36, v35
	v_mul_f32_e32 v35, 0xbfb8aa3b, v27
	v_mul_f32_e32 v38, 0xbfb8aa3b, v28
	v_exp_f32_e32 v37, v35
	v_exp_f32_e32 v39, v38
	v_mul_f32_e32 v38, 0xbfb8aa3b, v29
	v_exp_f32_e32 v40, v38
	v_add_f32_e32 v37, 1.0, v37
	v_add_f32_e32 v36, 1.0, v36
	v_rcp_f32_e32 v38, v37
	v_add_f32_e32 v37, 1.0, v39
	v_add_f32_e32 v39, 1.0, v40
	v_rcp_f32_e32 v36, v36
	v_rcp_f32_e32 v37, v37
	v_rcp_f32_e32 v39, v39
	v_mov_b32_e32 v40, v26
	v_mov_b32_e32 v41, v28
	v_mov_b32_e32 v28, v27
	v_pk_mul_f32 v[36:37], v[40:41], v[36:37]
	v_mov_b32_e32 v41, v32
	v_pk_mul_f32 v[26:27], v[28:29], v[38:39]
	v_mov_b32_e32 v32, v31
	v_mov_b32_e32 v40, v30
	v_pk_mul_f32 v[26:27], v[32:33], v[26:27]
	v_pk_mul_f32 v[36:37], v[40:41], v[36:37]
	v_cvt_pk_bf16_f32 v28, v37, v27
	v_cvt_pk_bf16_f32 v29, v36, v26
	v_mov_b32_e32 v27, v28
	v_mul_f32_e32 v28, 0xbfb8aa3b, v18
	v_mov_b32_e32 v26, v29
	v_exp_f32_e32 v28, v28
	v_mul_f32_e32 v29, 0xbfb8aa3b, v19
	v_or_b32_e32 v34, 32, v54
	v_exp_f32_e32 v29, v29
	v_mad_i64_i32 v[34:35], s[6:7], v34, s52, v[42:43]
	v_lshl_add_u64 v[34:35], v[34:35], 0, v[44:45]
	global_store_dwordx2 v[34:35], v[26:27], off
	v_add_f32_e32 v26, 1.0, v28
	v_mul_f32_e32 v28, 0xbfb8aa3b, v20
	v_add_f32_e32 v27, 1.0, v29
	v_exp_f32_e32 v29, v28
	v_mul_f32_e32 v28, 0xbfb8aa3b, v21
	v_exp_f32_e32 v30, v28
	v_rcp_f32_e32 v28, v27
	v_add_f32_e32 v27, 1.0, v29
	v_rcp_f32_e32 v26, v26
	v_add_f32_e32 v29, 1.0, v30
	v_rcp_f32_e32 v27, v27
	v_rcp_f32_e32 v29, v29
	v_mov_b32_e32 v30, v18
	v_mov_b32_e32 v31, v20
	v_mov_b32_e32 v20, v19
	v_pk_mul_f32 v[26:27], v[30:31], v[26:27]
	v_mov_b32_e32 v31, v24
	v_pk_mul_f32 v[18:19], v[20:21], v[28:29]
	v_mov_b32_e32 v24, v23
	v_mov_b32_e32 v30, v22
	v_pk_mul_f32 v[18:19], v[24:25], v[18:19]
	v_pk_mul_f32 v[26:27], v[30:31], v[26:27]
	v_cvt_pk_bf16_f32 v20, v27, v19
	v_cvt_pk_bf16_f32 v21, v26, v18
	v_mov_b32_e32 v19, v20
	v_mov_b32_e32 v18, v21
	global_store_dwordx2 v[34:35], v[18:19], off offset:32
	v_mul_f32_e32 v19, 0xbfb8aa3b, v10
	v_exp_f32_e32 v20, v19
	v_mul_f32_e32 v19, 0xbfb8aa3b, v11
	v_mul_f32_e32 v22, 0xbfb8aa3b, v12
	v_exp_f32_e32 v21, v19
	v_exp_f32_e32 v23, v22
	v_mul_f32_e32 v22, 0xbfb8aa3b, v13
	v_exp_f32_e32 v24, v22
	v_add_f32_e32 v21, 1.0, v21
	v_add_f32_e32 v20, 1.0, v20
	v_rcp_f32_e32 v22, v21
	v_add_f32_e32 v21, 1.0, v23
	v_add_f32_e32 v23, 1.0, v24
	v_rcp_f32_e32 v20, v20
	v_rcp_f32_e32 v21, v21
	v_rcp_f32_e32 v23, v23
	v_mov_b32_e32 v24, v10
	v_mov_b32_e32 v25, v12
	v_mov_b32_e32 v12, v11
	v_pk_mul_f32 v[20:21], v[24:25], v[20:21]
	v_mov_b32_e32 v25, v16
	v_pk_mul_f32 v[10:11], v[12:13], v[22:23]
	v_mov_b32_e32 v16, v15
	v_mov_b32_e32 v24, v14
	v_pk_mul_f32 v[10:11], v[16:17], v[10:11]
	v_pk_mul_f32 v[20:21], v[24:25], v[20:21]
	v_cvt_pk_bf16_f32 v12, v21, v11
	v_cvt_pk_bf16_f32 v13, v20, v10
	v_mov_b32_e32 v11, v12
	v_mul_f32_e32 v12, 0xbfb8aa3b, v2
	v_mov_b32_e32 v10, v13
	v_exp_f32_e32 v12, v12
	v_mul_f32_e32 v13, 0xbfb8aa3b, v3
	v_or_b32_e32 v18, 48, v54
	v_exp_f32_e32 v13, v13
	v_mad_i64_i32 v[18:19], s[6:7], v18, s52, v[42:43]
	v_lshl_add_u64 v[18:19], v[18:19], 0, v[44:45]
	global_store_dwordx2 v[18:19], v[10:11], off
	v_add_f32_e32 v10, 1.0, v12
	v_mul_f32_e32 v12, 0xbfb8aa3b, v4
	v_add_f32_e32 v11, 1.0, v13
	v_exp_f32_e32 v13, v12
	v_mul_f32_e32 v12, 0xbfb8aa3b, v5
	v_exp_f32_e32 v14, v12
	v_rcp_f32_e32 v12, v11
	v_add_f32_e32 v11, 1.0, v13
	v_rcp_f32_e32 v10, v10
	v_add_f32_e32 v13, 1.0, v14
	v_rcp_f32_e32 v11, v11
	v_rcp_f32_e32 v13, v13
	v_mov_b32_e32 v14, v2
	v_mov_b32_e32 v15, v4
	v_mov_b32_e32 v4, v3
	v_pk_mul_f32 v[10:11], v[14:15], v[10:11]
	v_mov_b32_e32 v15, v8
	v_pk_mul_f32 v[2:3], v[4:5], v[12:13]
	v_mov_b32_e32 v8, v7
	v_mov_b32_e32 v14, v6
	v_pk_mul_f32 v[2:3], v[8:9], v[2:3]
	v_pk_mul_f32 v[10:11], v[14:15], v[10:11]
	v_and_b32_sdwa v6, v3, v177 dst_sel:DWORD dst_unused:UNUSED_PAD src0_sel:WORD_1 src1_sel:DWORD
	v_cvt_pk_bf16_f32 v5, v10, v2
	v_and_b32_sdwa v4, v11, v177 dst_sel:DWORD dst_unused:UNUSED_PAD src0_sel:WORD_1 src1_sel:DWORD
	v_add3_u32 v3, v3, v6, s28
	v_add3_u32 v4, v11, v4, s28
	v_and_b32_e32 v3, 0xffff0000, v3
	v_or_b32_sdwa v3, v3, v4 dst_sel:DWORD dst_unused:UNUSED_PAD src0_sel:DWORD src1_sel:WORD_1
	v_mov_b32_e32 v2, v5
	s_mov_b32 s7, 0
	s_mov_b32 s6, s18
	s_mov_b32 s4, s19
	global_store_dwordx2 v[18:19], v[2:3], off offset:32
	s_branch .LBB0_1446

.LBB0_1470:
	s_add_i32 s2, s17, 4
	s_min_u32 s2, s2, 15
	s_lshl_b32 s4, s2, 7
	v_lshl_add_u64 v[74:75], v[54:55], 0, s[4:5]
	v_add_co_u32_e32 v78, vcc, s34, v74
	v_lshl_add_u64 v[82:83], v[56:57], 0, s[4:5]
	s_nop 0
	v_addc_co_u32_e32 v79, vcc, 0, v75, vcc
	v_add_co_u32_e32 v86, vcc, s34, v82
	global_load_dwordx4 v[74:77], v[74:75], off
	s_nop 0
	global_load_dwordx4 v[78:81], v[78:79], off
	v_addc_co_u32_e32 v87, vcc, 0, v83, vcc
	global_load_dwordx4 v[82:85], v[82:83], off
	s_nop 0
	global_load_dwordx4 v[86:89], v[86:87], off
	v_add_u32_e32 v73, v61, v64
	ds_read_b128 v[90:93], v65
	ds_read_b128 v[94:97], v65 offset:2304
	ds_read_b128 v[98:101], v73 offset:36864
	ds_read_b128 v[102:105], v73 offset:39168
	ds_read_b128 v[106:109], v73 offset:41472
	ds_read_b128 v[110:113], v73 offset:43776
	s_add_i32 s17, s17, 2
	s_waitcnt lgkmcnt(3)
	v_mfma_f32_16x16x32_bf16 v[42:45], v[98:101], v[90:93], v[42:45]
	s_waitcnt lgkmcnt(2)
	v_mfma_f32_16x16x32_bf16 v[46:49], v[102:105], v[90:93], v[46:49]
	s_waitcnt lgkmcnt(1)
	v_mfma_f32_16x16x32_bf16 v[34:37], v[106:109], v[90:93], v[34:37]
	s_waitcnt lgkmcnt(0)
	v_mfma_f32_16x16x32_bf16 v[38:41], v[110:113], v[90:93], v[38:41]
	v_mfma_f32_16x16x32_bf16 v[10:13], v[98:101], v[94:97], v[10:13]
	ds_read_b128 v[90:93], v65 offset:64
	ds_read_b128 v[98:101], v65 offset:2368
	v_mfma_f32_16x16x32_bf16 v[14:17], v[102:105], v[94:97], v[14:17]
	v_mfma_f32_16x16x32_bf16 v[2:5], v[106:109], v[94:97], v[2:5]
	ds_read_b128 v[102:105], v73 offset:36928
	ds_read_b128 v[106:109], v73 offset:39232
	ds_read_b128 v[114:117], v73 offset:41536
	ds_read_b128 v[118:121], v73 offset:43840
	v_mfma_f32_16x16x32_bf16 v[6:9], v[110:113], v[94:97], v[6:9]
	s_waitcnt lgkmcnt(3)
	v_mfma_f32_16x16x32_bf16 v[42:45], v[102:105], v[90:93], v[42:45]
	s_waitcnt vmcnt(7)
	ds_write_b128 v72, v[18:21] offset:55296
	s_waitcnt vmcnt(6)
	ds_write_b128 v72, v[22:25] offset:64512
	s_waitcnt vmcnt(5)
	ds_write_b128 v66, v[26:29]
	s_waitcnt vmcnt(4)
	ds_write_b128 v66, v[30:33] offset:9216
	s_waitcnt lgkmcnt(6)
	v_mfma_f32_16x16x32_bf16 v[46:49], v[106:109], v[90:93], v[46:49]
	s_waitcnt lgkmcnt(5)
	v_mfma_f32_16x16x32_bf16 v[34:37], v[114:117], v[90:93], v[34:37]
	s_waitcnt lgkmcnt(4)
	v_mfma_f32_16x16x32_bf16 v[38:41], v[118:121], v[90:93], v[38:41]
	v_mfma_f32_16x16x32_bf16 v[10:13], v[102:105], v[98:101], v[10:13]
	v_mfma_f32_16x16x32_bf16 v[14:17], v[106:109], v[98:101], v[14:17]
	v_mfma_f32_16x16x32_bf16 v[2:5], v[114:117], v[98:101], v[2:5]
	v_mfma_f32_16x16x32_bf16 v[6:9], v[118:121], v[98:101], v[6:9]
	s_min_u32 s2, s17, 12
	s_lshl_b32 s4, s2, 7
	v_lshl_add_u64 v[18:19], v[54:55], 0, s[4:5]
	v_add_co_u32_e32 v22, vcc, s34, v18
	v_lshl_add_u64 v[26:27], v[56:57], 0, s[4:5]
	s_nop 0
	v_addc_co_u32_e32 v23, vcc, 0, v19, vcc
	v_add_co_u32_e32 v30, vcc, s34, v26
	s_waitcnt lgkmcnt(0)
	s_barrier
	global_load_dwordx4 v[18:21], v[18:19], off offset:384
	s_nop 0
	global_load_dwordx4 v[22:25], v[22:23], off offset:384
	v_addc_co_u32_e32 v31, vcc, 0, v27, vcc
	global_load_dwordx4 v[26:29], v[26:27], off offset:384
	s_nop 0
	global_load_dwordx4 v[30:33], v[30:31], off offset:384
	ds_read_b128 v[90:93], v65 offset:55296
	ds_read_b128 v[94:97], v65 offset:57600
	ds_read_b128 v[98:101], v67
	ds_read_b128 v[102:105], v67 offset:2304
	ds_read_b128 v[106:109], v67 offset:4608
	ds_read_b128 v[110:113], v67 offset:6912
	s_waitcnt lgkmcnt(3)
	v_mfma_f32_16x16x32_bf16 v[42:45], v[98:101], v[90:93], v[42:45]
	s_waitcnt lgkmcnt(2)
	v_mfma_f32_16x16x32_bf16 v[46:49], v[102:105], v[90:93], v[46:49]
	s_waitcnt lgkmcnt(1)
	v_mfma_f32_16x16x32_bf16 v[34:37], v[106:109], v[90:93], v[34:37]
	s_waitcnt lgkmcnt(0)
	v_mfma_f32_16x16x32_bf16 v[38:41], v[110:113], v[90:93], v[38:41]
	v_mfma_f32_16x16x32_bf16 v[10:13], v[98:101], v[94:97], v[10:13]
	ds_read_b128 v[90:93], v65 offset:55360
	ds_read_b128 v[98:101], v65 offset:57664
	v_mfma_f32_16x16x32_bf16 v[14:17], v[102:105], v[94:97], v[14:17]
	v_mfma_f32_16x16x32_bf16 v[2:5], v[106:109], v[94:97], v[2:5]
	ds_read_b128 v[102:105], v68 offset:64
	ds_read_b128 v[106:109], v69 offset:64
	ds_read_b128 v[114:117], v70 offset:64
	ds_read_b128 v[118:121], v71 offset:64
	v_mfma_f32_16x16x32_bf16 v[6:9], v[110:113], v[94:97], v[6:9]
	s_waitcnt lgkmcnt(3)
	v_mfma_f32_16x16x32_bf16 v[42:45], v[102:105], v[90:93], v[42:45]
	s_waitcnt vmcnt(7)
	ds_write_b128 v72, v[74:77]
	s_waitcnt vmcnt(6)
	ds_write_b128 v72, v[78:81] offset:9216
	s_waitcnt vmcnt(5)
	ds_write_b128 v72, v[82:85] offset:36864
	s_waitcnt vmcnt(4)
	ds_write_b128 v72, v[86:89] offset:46080
	s_waitcnt lgkmcnt(6)
	v_mfma_f32_16x16x32_bf16 v[46:49], v[106:109], v[90:93], v[46:49]
	s_waitcnt lgkmcnt(5)
	v_mfma_f32_16x16x32_bf16 v[34:37], v[114:117], v[90:93], v[34:37]
	s_waitcnt lgkmcnt(4)
	v_mfma_f32_16x16x32_bf16 v[38:41], v[118:121], v[90:93], v[38:41]
	v_mfma_f32_16x16x32_bf16 v[10:13], v[102:105], v[98:101], v[10:13]
	v_mfma_f32_16x16x32_bf16 v[14:17], v[106:109], v[98:101], v[14:17]
	v_mfma_f32_16x16x32_bf16 v[2:5], v[114:117], v[98:101], v[2:5]
	v_mfma_f32_16x16x32_bf16 v[6:9], v[118:121], v[98:101], v[6:9]
	s_waitcnt lgkmcnt(0)
	s_barrier
	s_cmp_gt_u32 s17, 13
	s_cbranch_scc0 .LBB0_1470
	s_waitcnt vmcnt(3)
	v_mul_f32_e32 v19, 0xbfb8aa3b, v42
	v_exp_f32_e32 v19, v19
	s_waitcnt vmcnt(2)
	v_mul_f32_e32 v22, 0xbfb8aa3b, v43
	v_exp_f32_e32 v25, v22
	s_waitcnt vmcnt(1)
	v_mul_f32_e32 v26, 0xbfb8aa3b, v45
	v_add_f32_e32 v19, 1.0, v19
	v_rcp_f32_e32 v24, v19
	v_add_f32_e32 v19, 1.0, v25
	v_mul_f32_e32 v25, 0xbfb8aa3b, v44
	v_exp_f32_e32 v25, v25
	v_exp_f32_e32 v27, v26
	v_rcp_f32_e32 v26, v19
	v_mov_b32_e32 v28, v42
	v_add_f32_e32 v19, 1.0, v25
	v_rcp_f32_e32 v25, v19
	v_add_f32_e32 v19, 1.0, v27
	v_rcp_f32_e32 v27, v19
	v_mov_b32_e32 v29, v44
	v_pk_mul_f32 v[24:25], v[28:29], v[24:25]
	v_mov_b32_e32 v28, v46
	v_mov_b32_e32 v29, v48
	v_mov_b32_e32 v44, v43
	v_pk_mul_f32 v[24:25], v[28:29], v[24:25]
	v_pk_mul_f32 v[26:27], v[44:45], v[26:27]
	v_mov_b32_e32 v48, v47
	v_pk_mul_f32 v[26:27], v[48:49], v[26:27]
	v_cvt_pk_bf16_f32 v24, v24, v26
	v_cvt_pk_bf16_f32 v25, v25, v27
	v_or_b32_e32 v18, s15, v58
	v_ashrrev_i32_e32 v18, 1, v18
	v_mul_f32_e32 v26, 0xbfb8aa3b, v34
	v_or_b32_e32 v18, v18, v62
	v_exp_f32_e32 v26, v26
	v_mul_f32_e32 v27, 0xbfb8aa3b, v35
	s_waitcnt vmcnt(0)
	v_add_u32_e32 v30, s14, v60
	v_mov_b64_e32 v[20:21], s[12:13]
	v_ashrrev_i32_e32 v19, 31, v18
	v_exp_f32_e32 v27, v27
	v_mad_i64_i32 v[22:23], s[14:15], v30, s52, v[20:21]
	v_lshlrev_b64 v[18:19], 1, v[18:19]
	v_lshl_add_u64 v[22:23], v[22:23], 0, v[18:19]
	s_waitcnt vmcnt(0)
	global_store_dwordx2 v[22:23], v[24:25], off
	v_add_f32_e32 v24, 1.0, v26
	v_mul_f32_e32 v26, 0xbfb8aa3b, v36
	v_add_f32_e32 v25, 1.0, v27
	v_exp_f32_e32 v27, v26
	v_mul_f32_e32 v26, 0xbfb8aa3b, v37
	v_exp_f32_e32 v28, v26
	v_rcp_f32_e32 v26, v25
	v_add_f32_e32 v25, 1.0, v27
	v_rcp_f32_e32 v24, v24
	v_rcp_f32_e32 v25, v25
	v_add_f32_e32 v27, 1.0, v28
	v_rcp_f32_e32 v27, v27
	v_mov_b32_e32 v28, v34
	v_mov_b32_e32 v29, v36
	v_pk_mul_f32 v[24:25], v[28:29], v[24:25]
	v_mov_b32_e32 v28, v38
	v_mov_b32_e32 v29, v40
	v_mov_b32_e32 v36, v35
	v_pk_mul_f32 v[24:25], v[28:29], v[24:25]
	v_pk_mul_f32 v[26:27], v[36:37], v[26:27]
	v_mov_b32_e32 v40, v39
	v_pk_mul_f32 v[26:27], v[40:41], v[26:27]
	v_cvt_pk_bf16_f32 v25, v25, v27
	v_cvt_pk_bf16_f32 v24, v24, v26
	global_store_dwordx2 v[22:23], v[24:25], off offset:32
	v_mul_f32_e32 v23, 0xbfb8aa3b, v10
	v_mul_f32_e32 v24, 0xbfb8aa3b, v11
	v_exp_f32_e32 v23, v23
	v_exp_f32_e32 v24, v24
	v_or_b32_e32 v22, 16, v30
	v_mad_i64_i32 v[20:21], s[14:15], v22, s52, v[20:21]
	v_add_f32_e32 v22, 1.0, v23
	v_add_f32_e32 v23, 1.0, v24
	v_mul_f32_e32 v24, 0xbfb8aa3b, v12
	v_exp_f32_e32 v25, v24
	v_mul_f32_e32 v24, 0xbfb8aa3b, v13
	v_exp_f32_e32 v26, v24
	v_rcp_f32_e32 v24, v23
	v_add_f32_e32 v23, 1.0, v25
	v_rcp_f32_e32 v22, v22
	v_add_f32_e32 v25, 1.0, v26
	v_rcp_f32_e32 v23, v23
	v_rcp_f32_e32 v25, v25
	v_lshl_add_u64 v[18:19], v[20:21], 0, v[18:19]
	v_mov_b32_e32 v20, v10
	v_mov_b32_e32 v21, v12
	v_mov_b32_e32 v12, v11
	v_pk_mul_f32 v[20:21], v[20:21], v[22:23]
	v_mov_b32_e32 v23, v16
	v_pk_mul_f32 v[10:11], v[12:13], v[24:25]
	v_mov_b32_e32 v16, v15
	v_mov_b32_e32 v22, v14
	v_pk_mul_f32 v[10:11], v[16:17], v[10:11]
	v_pk_mul_f32 v[20:21], v[22:23], v[20:21]
	v_cvt_pk_bf16_f32 v12, v21, v11
	v_cvt_pk_bf16_f32 v13, v20, v10
	v_mov_b32_e32 v11, v12
	v_mul_f32_e32 v12, 0xbfb8aa3b, v2
	v_mov_b32_e32 v10, v13
	v_exp_f32_e32 v12, v12
	v_mul_f32_e32 v13, 0xbfb8aa3b, v3
	v_exp_f32_e32 v13, v13
	global_store_dwordx2 v[18:19], v[10:11], off
	v_add_f32_e32 v10, 1.0, v12
	v_mul_f32_e32 v12, 0xbfb8aa3b, v4
	v_add_f32_e32 v11, 1.0, v13
	v_exp_f32_e32 v13, v12
	v_mul_f32_e32 v12, 0xbfb8aa3b, v5
	v_exp_f32_e32 v14, v12
	v_rcp_f32_e32 v12, v11
	v_add_f32_e32 v11, 1.0, v13
	v_rcp_f32_e32 v10, v10
	v_add_f32_e32 v13, 1.0, v14
	v_rcp_f32_e32 v11, v11
	v_rcp_f32_e32 v13, v13
	v_mov_b32_e32 v14, v2
	v_mov_b32_e32 v15, v4
	v_mov_b32_e32 v4, v3
	v_pk_mul_f32 v[10:11], v[14:15], v[10:11]
	v_mov_b32_e32 v15, v8
	v_pk_mul_f32 v[2:3], v[4:5], v[12:13]
	v_mov_b32_e32 v8, v7
	v_mov_b32_e32 v14, v6
	v_pk_mul_f32 v[2:3], v[8:9], v[2:3]
	v_pk_mul_f32 v[10:11], v[14:15], v[10:11]
	v_and_b32_sdwa v6, v3, v177 dst_sel:DWORD dst_unused:UNUSED_PAD src0_sel:WORD_1 src1_sel:DWORD
	v_cvt_pk_bf16_f32 v5, v10, v2
	v_and_b32_sdwa v4, v11, v177 dst_sel:DWORD dst_unused:UNUSED_PAD src0_sel:WORD_1 src1_sel:DWORD
	v_add3_u32 v3, v3, v6, s28
	v_add3_u32 v4, v11, v4, s28
	v_and_b32_e32 v3, 0xffff0000, v3
	v_or_b32_sdwa v3, v3, v4 dst_sel:DWORD dst_unused:UNUSED_PAD src0_sel:DWORD src1_sel:WORD_1
	v_mov_b32_e32 v2, v5
	s_mov_b32 s4, 0
	global_store_dwordx2 v[18:19], v[2:3], off offset:32
	s_branch .LBB0_1465
